# ssd_out_item (both layers): divergent per-element decay-factor code (192 exec-masked branches with serialized LDS reads) replaced by branch-free v_cndmask code with batched ds_read_b128; + attention s
# speedup vs baseline: 1.0368x; 1.0114x over previous
.LBB0_740:
	s_or_b64 exec, exec, s[66:67]
	v_lshlrev_b32_e32 v54, 3, v168
	v_mov_b32_e32 v2, s46
	v_mov_b32_e32 v3, s45
	v_cndmask_b32_e32 v1, v5, v4, vcc
	v_cndmask_b32_e32 v2, v2, v3, vcc
	v_lshl_add_u32 v57, v54, 1, s23
	v_lshl_add_u32 v1, v1, 2, v2
	v_mad_u32_u24 v8, v52, s71, v57
	ds_write_b32 v1, v0
	s_waitcnt lgkmcnt(0)
	s_barrier
	ds_read_b128 v[0:3], v8 offset:17408
	ds_read_b128 v[4:7], v8 offset:17440
	s_waitcnt lgkmcnt(1)
	v_mfma_f32_32x32x16_bf16 v[24:39], v[0:3], v[48:51], 0
	v_lshlrev_b32_e32 v110, 2, v168
	v_cmp_ge_u32_e32 vcc, v110, v53
	s_waitcnt lgkmcnt(0)
	v_mfma_f32_32x32x16_bf16 v[24:39], v[4:7], v[102:105], v[24:39]
	ds_read_b128 v[0:3], v8 offset:17472
	ds_read_b128 v[4:7], v8 offset:17504
	s_waitcnt lgkmcnt(1)
	v_mfma_f32_32x32x16_bf16 v[24:39], v[0:3], v[98:101], v[24:39]
	v_lshl_add_u32 v0, v53, 2, s23
	ds_read2st64_b32 v[126:127], v0 offset0:140 offset1:142
	s_waitcnt lgkmcnt(1)
	v_mfma_f32_32x32x16_bf16 v[24:39], v[4:7], v[94:97], v[24:39]
	v_lshl_add_u32 v236, v110, 2, s23
	v_sub_u32_e32 v237, v53, v110
	ds_read_b128 v[170:173], v236 offset:35840
	ds_read_b128 v[174:177], v236 offset:36352
	ds_read_b128 v[178:181], v236 offset:36864
	ds_read_b128 v[182:185], v236 offset:37376
	ds_read_b128 v[186:189], v236 offset:35872
	ds_read_b128 v[190:193], v236 offset:36384
	ds_read_b128 v[194:197], v236 offset:36896
	ds_read_b128 v[198:201], v236 offset:37408
	ds_read_b128 v[202:205], v236 offset:35904
	ds_read_b128 v[206:209], v236 offset:36416
	ds_read_b128 v[210:213], v236 offset:36928
	ds_read_b128 v[214:217], v236 offset:37440
	s_waitcnt lgkmcnt(8)
	ds_read_b128 v[218:221], v236 offset:35936
	ds_read_b128 v[222:225], v236 offset:36448
	ds_read_b128 v[226:229], v236 offset:36960
	ds_read_b128 v[230:233], v236 offset:37472
	v_mov_b32_e32 v238, v237
	v_cmp_lt_i32_e32 vcc, 0, v238
	v_cmp_lt_i32_e64 s[0:1], 1, v238
	v_cmp_lt_i32_e64 s[4:5], 2, v238
	v_cmp_lt_i32_e64 s[66:67], 3, v238
	v_sub_f32_e32 v170, v126, v170
	v_sub_f32_e32 v171, v126, v171
	v_sub_f32_e32 v172, v126, v172
	v_sub_f32_e32 v173, v126, v173
	v_sub_f32_e32 v174, v127, v174
	v_sub_f32_e32 v175, v127, v175
	v_sub_f32_e32 v176, v127, v176
	v_sub_f32_e32 v177, v127, v177
	v_cndmask_b32_e64 v170, v174, v170, vcc
	v_cndmask_b32_e64 v171, v175, v171, s[0:1]
	v_cndmask_b32_e64 v172, v176, v172, s[4:5]
	v_cndmask_b32_e64 v173, v177, v173, s[66:67]
	v_add_f32_e32 v174, v178, v182
	v_add_f32_e32 v175, v179, v183
	v_add_f32_e32 v176, v180, v184
	v_add_f32_e32 v177, v181, v185
	v_cndmask_b32_e64 v178, v182, v178, vcc
	v_cndmask_b32_e64 v179, v183, v179, s[0:1]
	v_cndmask_b32_e64 v180, v184, v180, s[4:5]
	v_cndmask_b32_e64 v181, v185, v181, s[66:67]
	v_cmp_eq_u32_e32 vcc, 0, v238
	v_cmp_eq_u32_e64 s[0:1], 1, v238
	v_cmp_eq_u32_e64 s[4:5], 2, v238
	v_cmp_eq_u32_e64 s[66:67], 3, v238
	v_mul_f32_e32 v170, 0x3fb8aa3b, v170
	v_mul_f32_e32 v171, 0x3fb8aa3b, v171
	v_mul_f32_e32 v172, 0x3fb8aa3b, v172
	v_mul_f32_e32 v173, 0x3fb8aa3b, v173
	v_exp_f32_e32 v170, v170
	v_exp_f32_e32 v171, v171
	v_exp_f32_e32 v172, v172
	v_exp_f32_e32 v173, v173
	v_mul_f32_e32 v178, v178, v170
	v_mul_f32_e32 v179, v179, v171
	v_mul_f32_e32 v180, v180, v172
	v_mul_f32_e32 v181, v181, v173
	v_cndmask_b32_e64 v0, v178, v174, vcc
	v_cndmask_b32_e64 v1, v179, v175, s[0:1]
	v_cndmask_b32_e64 v2, v180, v176, s[4:5]
	v_cndmask_b32_e64 v3, v181, v177, s[66:67]
	s_waitcnt lgkmcnt(8)
	v_add_u32_e32 v238, -8, v237
	v_cmp_lt_i32_e32 vcc, 0, v238
	v_cmp_lt_i32_e64 s[0:1], 1, v238
	v_cmp_lt_i32_e64 s[4:5], 2, v238
	v_cmp_lt_i32_e64 s[66:67], 3, v238
	v_sub_f32_e32 v186, v126, v186
	v_sub_f32_e32 v187, v126, v187
	v_sub_f32_e32 v188, v126, v188
	v_sub_f32_e32 v189, v126, v189
	v_sub_f32_e32 v190, v127, v190
	v_sub_f32_e32 v191, v127, v191
	v_sub_f32_e32 v192, v127, v192
	v_sub_f32_e32 v193, v127, v193
	v_cndmask_b32_e64 v186, v190, v186, vcc
	v_cndmask_b32_e64 v187, v191, v187, s[0:1]
	v_cndmask_b32_e64 v188, v192, v188, s[4:5]
	v_cndmask_b32_e64 v189, v193, v189, s[66:67]
	v_add_f32_e32 v190, v194, v198
	v_add_f32_e32 v191, v195, v199
	v_add_f32_e32 v192, v196, v200
	v_add_f32_e32 v193, v197, v201
	v_cndmask_b32_e64 v194, v198, v194, vcc
	v_cndmask_b32_e64 v195, v199, v195, s[0:1]
	v_cndmask_b32_e64 v196, v200, v196, s[4:5]
	v_cndmask_b32_e64 v197, v201, v197, s[66:67]
	v_cmp_eq_u32_e32 vcc, 0, v238
	v_cmp_eq_u32_e64 s[0:1], 1, v238
	v_cmp_eq_u32_e64 s[4:5], 2, v238
	v_cmp_eq_u32_e64 s[66:67], 3, v238
	v_mul_f32_e32 v186, 0x3fb8aa3b, v186
	v_mul_f32_e32 v187, 0x3fb8aa3b, v187
	v_mul_f32_e32 v188, 0x3fb8aa3b, v188
	v_mul_f32_e32 v189, 0x3fb8aa3b, v189
	v_exp_f32_e32 v186, v186
	v_exp_f32_e32 v187, v187
	v_exp_f32_e32 v188, v188
	v_exp_f32_e32 v189, v189
	v_mul_f32_e32 v194, v194, v186
	v_mul_f32_e32 v195, v195, v187
	v_mul_f32_e32 v196, v196, v188
	v_mul_f32_e32 v197, v197, v189
	v_cndmask_b32_e64 v4, v194, v190, vcc
	v_cndmask_b32_e64 v5, v195, v191, s[0:1]
	v_cndmask_b32_e64 v6, v196, v192, s[4:5]
	v_cndmask_b32_e64 v7, v197, v193, s[66:67]
	s_waitcnt lgkmcnt(4)
	v_add_u32_e32 v238, -16, v237
	v_cmp_lt_i32_e32 vcc, 0, v238
	v_cmp_lt_i32_e64 s[0:1], 1, v238
	v_cmp_lt_i32_e64 s[4:5], 2, v238
	v_cmp_lt_i32_e64 s[66:67], 3, v238
	v_sub_f32_e32 v202, v126, v202
	v_sub_f32_e32 v203, v126, v203
	v_sub_f32_e32 v204, v126, v204
	v_sub_f32_e32 v205, v126, v205
	v_sub_f32_e32 v206, v127, v206
	v_sub_f32_e32 v207, v127, v207
	v_sub_f32_e32 v208, v127, v208
	v_sub_f32_e32 v209, v127, v209
	v_cndmask_b32_e64 v202, v206, v202, vcc
	v_cndmask_b32_e64 v203, v207, v203, s[0:1]
	v_cndmask_b32_e64 v204, v208, v204, s[4:5]
	v_cndmask_b32_e64 v205, v209, v205, s[66:67]
	v_add_f32_e32 v206, v210, v214
	v_add_f32_e32 v207, v211, v215
	v_add_f32_e32 v208, v212, v216
	v_add_f32_e32 v209, v213, v217
	v_cndmask_b32_e64 v210, v214, v210, vcc
	v_cndmask_b32_e64 v211, v215, v211, s[0:1]
	v_cndmask_b32_e64 v212, v216, v212, s[4:5]
	v_cndmask_b32_e64 v213, v217, v213, s[66:67]
	v_cmp_eq_u32_e32 vcc, 0, v238
	v_cmp_eq_u32_e64 s[0:1], 1, v238
	v_cmp_eq_u32_e64 s[4:5], 2, v238
	v_cmp_eq_u32_e64 s[66:67], 3, v238
	v_mul_f32_e32 v202, 0x3fb8aa3b, v202
	v_mul_f32_e32 v203, 0x3fb8aa3b, v203
	v_mul_f32_e32 v204, 0x3fb8aa3b, v204
	v_mul_f32_e32 v205, 0x3fb8aa3b, v205
	v_exp_f32_e32 v202, v202
	v_exp_f32_e32 v203, v203
	v_exp_f32_e32 v204, v204
	v_exp_f32_e32 v205, v205
	v_mul_f32_e32 v210, v210, v202
	v_mul_f32_e32 v211, v211, v203
	v_mul_f32_e32 v212, v212, v204
	v_mul_f32_e32 v213, v213, v205
	v_cndmask_b32_e64 v40, v210, v206, vcc
	v_cndmask_b32_e64 v41, v211, v207, s[0:1]
	v_cndmask_b32_e64 v8, v212, v208, s[4:5]
	v_cndmask_b32_e64 v9, v213, v209, s[66:67]
	s_waitcnt lgkmcnt(0)
	v_add_u32_e32 v238, 0xffffffe8, v237
	v_cmp_lt_i32_e32 vcc, 0, v238
	v_cmp_lt_i32_e64 s[0:1], 1, v238
	v_cmp_lt_i32_e64 s[4:5], 2, v238
	v_cmp_lt_i32_e64 s[66:67], 3, v238
	v_sub_f32_e32 v218, v126, v218
	v_sub_f32_e32 v219, v126, v219
	v_sub_f32_e32 v220, v126, v220
	v_sub_f32_e32 v221, v126, v221
	v_sub_f32_e32 v222, v127, v222
	v_sub_f32_e32 v223, v127, v223
	v_sub_f32_e32 v224, v127, v224
	v_sub_f32_e32 v225, v127, v225
	v_cndmask_b32_e64 v218, v222, v218, vcc
	v_cndmask_b32_e64 v219, v223, v219, s[0:1]
	v_cndmask_b32_e64 v220, v224, v220, s[4:5]
	v_cndmask_b32_e64 v221, v225, v221, s[66:67]
	v_add_f32_e32 v222, v226, v230
	v_add_f32_e32 v223, v227, v231
	v_add_f32_e32 v224, v228, v232
	v_add_f32_e32 v225, v229, v233
	v_cndmask_b32_e64 v226, v230, v226, vcc
	v_cndmask_b32_e64 v227, v231, v227, s[0:1]
	v_cndmask_b32_e64 v228, v232, v228, s[4:5]
	v_cndmask_b32_e64 v229, v233, v229, s[66:67]
	v_cmp_eq_u32_e32 vcc, 0, v238
	v_cmp_eq_u32_e64 s[0:1], 1, v238
	v_cmp_eq_u32_e64 s[4:5], 2, v238
	v_cmp_eq_u32_e64 s[66:67], 3, v238
	v_mul_f32_e32 v218, 0x3fb8aa3b, v218
	v_mul_f32_e32 v219, 0x3fb8aa3b, v219
	v_mul_f32_e32 v220, 0x3fb8aa3b, v220
	v_mul_f32_e32 v221, 0x3fb8aa3b, v221
	v_exp_f32_e32 v218, v218
	v_exp_f32_e32 v219, v219
	v_exp_f32_e32 v220, v220
	v_exp_f32_e32 v221, v221
	v_mul_f32_e32 v226, v226, v218
	v_mul_f32_e32 v227, v227, v219
	v_mul_f32_e32 v228, v228, v220
	v_mul_f32_e32 v229, v229, v221
	v_cndmask_b32_e64 v10, v226, v222, vcc
	v_cndmask_b32_e64 v11, v227, v223, s[0:1]
	v_cndmask_b32_e64 v12, v228, v224, s[4:5]
	v_cndmask_b32_e64 v42, v229, v225, s[66:67]
	v_mul_f32_e32 v16, v28, v4
	v_mul_u32_u24_e32 v4, 0x88, v52
	v_lshl_add_u32 v56, v110, 1, s23
	v_lshl_add_u32 v62, v4, 1, v56
	v_mul_f32_e32 v13, v31, v7
	v_mul_f32_e32 v14, v30, v6
	v_mul_f32_e32 v15, v29, v5
	ds_read2_b64 v[4:7], v62 offset1:2
	v_mul_f32_e32 v3, v27, v3
	v_mul_f32_e32 v2, v26, v2
	v_mul_f32_e32 v1, v25, v1
	v_mul_f32_e32 v0, v24, v0
	v_cvt_pk_bf16_f32 v0, v0, v1
	v_cvt_pk_bf16_f32 v1, v2, v3
	v_cvt_pk_bf16_f32 v2, v16, v15
	v_cvt_pk_bf16_f32 v3, v14, v13
	v_add_u32_e32 v63, 0x2000, v62
	v_mul_f32_e32 v44, v37, v11
	v_mul_f32_e32 v45, v36, v10
	v_mul_f32_e32 v46, v35, v9
	v_mul_f32_e32 v47, v34, v8
	ds_read2_b64 v[34:37], v62 offset0:4 offset1:6
	s_waitcnt lgkmcnt(1)
	v_mfma_f32_32x32x16_bf16 v[16:31], v[4:7], v[0:3], 0
	ds_read2_b64 v[4:7], v63 offset0:64 offset1:66
	v_mul_f32_e32 v43, v38, v12
	v_mul_f32_e32 v33, v33, v41
	v_mul_f32_e32 v32, v32, v40
	v_mul_f32_e32 v41, v39, v42
	v_cvt_pk_bf16_f32 v38, v32, v33
	v_cvt_pk_bf16_f32 v39, v47, v46
	v_cvt_pk_bf16_f32 v40, v45, v44
	v_cvt_pk_bf16_f32 v41, v43, v41
	s_waitcnt lgkmcnt(0)
	v_mfma_f32_32x32x16_bf16 v[0:15], v[4:7], v[0:3], 0
	v_or_b32_e32 v59, 32, v110
	v_cmp_ge_u32_e32 vcc, v59, v53
	v_mfma_f32_32x32x16_bf16 v[16:31], v[34:37], v[38:41], v[16:31]
	ds_read2_b64 v[32:35], v63 offset0:68 offset1:70
	v_or_b32_e32 v36, 32, v52
	v_mad_u32_u24 v58, v36, s71, v57
	s_waitcnt lgkmcnt(0)
	v_mfma_f32_32x32x16_bf16 v[0:15], v[32:35], v[38:41], v[0:15]
	ds_read_b128 v[32:35], v58 offset:17408
	ds_read_b128 v[64:67], v58 offset:17440
	s_waitcnt lgkmcnt(1)
	v_mfma_f32_32x32x16_bf16 v[32:47], v[32:35], v[48:51], 0
	s_waitcnt lgkmcnt(0)
	v_mfma_f32_32x32x16_bf16 v[32:47], v[64:67], v[102:105], v[32:47]
	ds_read_b128 v[64:67], v58 offset:17472
	ds_read_b128 v[68:71], v58 offset:17504
	s_waitcnt lgkmcnt(1)
	v_mfma_f32_32x32x16_bf16 v[32:47], v[64:67], v[98:101], v[32:47]
	s_waitcnt lgkmcnt(0)
	v_mfma_f32_32x32x16_bf16 v[32:47], v[68:71], v[94:97], v[32:47]
	v_lshl_add_u32 v236, v110, 2, s23
	v_sub_u32_e32 v237, v53, v110
	ds_read_b128 v[170:173], v236 offset:35968
	ds_read_b128 v[174:177], v236 offset:36480
	ds_read_b128 v[178:181], v236 offset:36992
	ds_read_b128 v[182:185], v236 offset:37504
	ds_read_b128 v[186:189], v236 offset:36000
	ds_read_b128 v[190:193], v236 offset:36512
	ds_read_b128 v[194:197], v236 offset:37024
	ds_read_b128 v[198:201], v236 offset:37536
	ds_read_b128 v[202:205], v236 offset:36032
	ds_read_b128 v[206:209], v236 offset:36544
	ds_read_b128 v[210:213], v236 offset:37056
	ds_read_b128 v[214:217], v236 offset:37568
	s_waitcnt lgkmcnt(8)
	ds_read_b128 v[218:221], v236 offset:36064
	ds_read_b128 v[222:225], v236 offset:36576
	ds_read_b128 v[226:229], v236 offset:37088
	ds_read_b128 v[230:233], v236 offset:37600
	v_add_u32_e32 v238, 0xffffffe0, v237
	v_cmp_lt_i32_e32 vcc, 0, v238
	v_cmp_lt_i32_e64 s[0:1], 1, v238
	v_cmp_lt_i32_e64 s[4:5], 2, v238
	v_cmp_lt_i32_e64 s[66:67], 3, v238
	v_sub_f32_e32 v170, v126, v170
	v_sub_f32_e32 v171, v126, v171
	v_sub_f32_e32 v172, v126, v172
	v_sub_f32_e32 v173, v126, v173
	v_sub_f32_e32 v174, v127, v174
	v_sub_f32_e32 v175, v127, v175
	v_sub_f32_e32 v176, v127, v176
	v_sub_f32_e32 v177, v127, v177
	v_cndmask_b32_e64 v170, v174, v170, vcc
	v_cndmask_b32_e64 v171, v175, v171, s[0:1]
	v_cndmask_b32_e64 v172, v176, v172, s[4:5]
	v_cndmask_b32_e64 v173, v177, v173, s[66:67]
	v_add_f32_e32 v174, v178, v182
	v_add_f32_e32 v175, v179, v183
	v_add_f32_e32 v176, v180, v184
	v_add_f32_e32 v177, v181, v185
	v_cndmask_b32_e64 v178, v182, v178, vcc
	v_cndmask_b32_e64 v179, v183, v179, s[0:1]
	v_cndmask_b32_e64 v180, v184, v180, s[4:5]
	v_cndmask_b32_e64 v181, v185, v181, s[66:67]
	v_cmp_eq_u32_e32 vcc, 0, v238
	v_cmp_eq_u32_e64 s[0:1], 1, v238
	v_cmp_eq_u32_e64 s[4:5], 2, v238
	v_cmp_eq_u32_e64 s[66:67], 3, v238
	v_mul_f32_e32 v170, 0x3fb8aa3b, v170
	v_mul_f32_e32 v171, 0x3fb8aa3b, v171
	v_mul_f32_e32 v172, 0x3fb8aa3b, v172
	v_mul_f32_e32 v173, 0x3fb8aa3b, v173
	v_exp_f32_e32 v170, v170
	v_exp_f32_e32 v171, v171
	v_exp_f32_e32 v172, v172
	v_exp_f32_e32 v173, v173
	v_mul_f32_e32 v178, v178, v170
	v_mul_f32_e32 v179, v179, v171
	v_mul_f32_e32 v180, v180, v172
	v_mul_f32_e32 v181, v181, v173
	v_cndmask_b32_e64 v58, v178, v174, vcc
	v_cndmask_b32_e64 v59, v179, v175, s[0:1]
	v_cndmask_b32_e64 v64, v180, v176, s[4:5]
	v_cndmask_b32_e64 v65, v181, v177, s[66:67]
	s_waitcnt lgkmcnt(8)
	v_add_u32_e32 v238, 0xffffffd8, v237
	v_cmp_lt_i32_e32 vcc, 0, v238
	v_cmp_lt_i32_e64 s[0:1], 1, v238
	v_cmp_lt_i32_e64 s[4:5], 2, v238
	v_cmp_lt_i32_e64 s[66:67], 3, v238
	v_sub_f32_e32 v186, v126, v186
	v_sub_f32_e32 v187, v126, v187
	v_sub_f32_e32 v188, v126, v188
	v_sub_f32_e32 v189, v126, v189
	v_sub_f32_e32 v190, v127, v190
	v_sub_f32_e32 v191, v127, v191
	v_sub_f32_e32 v192, v127, v192
	v_sub_f32_e32 v193, v127, v193
	v_cndmask_b32_e64 v186, v190, v186, vcc
	v_cndmask_b32_e64 v187, v191, v187, s[0:1]
	v_cndmask_b32_e64 v188, v192, v188, s[4:5]
	v_cndmask_b32_e64 v189, v193, v189, s[66:67]
	v_add_f32_e32 v190, v194, v198
	v_add_f32_e32 v191, v195, v199
	v_add_f32_e32 v192, v196, v200
	v_add_f32_e32 v193, v197, v201
	v_cndmask_b32_e64 v194, v198, v194, vcc
	v_cndmask_b32_e64 v195, v199, v195, s[0:1]
	v_cndmask_b32_e64 v196, v200, v196, s[4:5]
	v_cndmask_b32_e64 v197, v201, v197, s[66:67]
	v_cmp_eq_u32_e32 vcc, 0, v238
	v_cmp_eq_u32_e64 s[0:1], 1, v238
	v_cmp_eq_u32_e64 s[4:5], 2, v238
	v_cmp_eq_u32_e64 s[66:67], 3, v238
	v_mul_f32_e32 v186, 0x3fb8aa3b, v186
	v_mul_f32_e32 v187, 0x3fb8aa3b, v187
	v_mul_f32_e32 v188, 0x3fb8aa3b, v188
	v_mul_f32_e32 v189, 0x3fb8aa3b, v189
	v_exp_f32_e32 v186, v186
	v_exp_f32_e32 v187, v187
	v_exp_f32_e32 v188, v188
	v_exp_f32_e32 v189, v189
	v_mul_f32_e32 v194, v194, v186
	v_mul_f32_e32 v195, v195, v187
	v_mul_f32_e32 v196, v196, v188
	v_mul_f32_e32 v197, v197, v189
	v_cndmask_b32_e64 v66, v194, v190, vcc
	v_cndmask_b32_e64 v67, v195, v191, s[0:1]
	v_cndmask_b32_e64 v68, v196, v192, s[4:5]
	v_cndmask_b32_e64 v70, v197, v193, s[66:67]
	s_waitcnt lgkmcnt(4)
	v_add_u32_e32 v238, 0xffffffd0, v237
	v_cmp_lt_i32_e32 vcc, 0, v238
	v_cmp_lt_i32_e64 s[0:1], 1, v238
	v_cmp_lt_i32_e64 s[4:5], 2, v238
	v_cmp_lt_i32_e64 s[66:67], 3, v238
	v_sub_f32_e32 v202, v126, v202
	v_sub_f32_e32 v203, v126, v203
	v_sub_f32_e32 v204, v126, v204
	v_sub_f32_e32 v205, v126, v205
	v_sub_f32_e32 v206, v127, v206
	v_sub_f32_e32 v207, v127, v207
	v_sub_f32_e32 v208, v127, v208
	v_sub_f32_e32 v209, v127, v209
	v_cndmask_b32_e64 v202, v206, v202, vcc
	v_cndmask_b32_e64 v203, v207, v203, s[0:1]
	v_cndmask_b32_e64 v204, v208, v204, s[4:5]
	v_cndmask_b32_e64 v205, v209, v205, s[66:67]
	v_add_f32_e32 v206, v210, v214
	v_add_f32_e32 v207, v211, v215
	v_add_f32_e32 v208, v212, v216
	v_add_f32_e32 v209, v213, v217
	v_cndmask_b32_e64 v210, v214, v210, vcc
	v_cndmask_b32_e64 v211, v215, v211, s[0:1]
	v_cndmask_b32_e64 v212, v216, v212, s[4:5]
	v_cndmask_b32_e64 v213, v217, v213, s[66:67]
	v_cmp_eq_u32_e32 vcc, 0, v238
	v_cmp_eq_u32_e64 s[0:1], 1, v238
	v_cmp_eq_u32_e64 s[4:5], 2, v238
	v_cmp_eq_u32_e64 s[66:67], 3, v238
	v_mul_f32_e32 v202, 0x3fb8aa3b, v202
	v_mul_f32_e32 v203, 0x3fb8aa3b, v203
	v_mul_f32_e32 v204, 0x3fb8aa3b, v204
	v_mul_f32_e32 v205, 0x3fb8aa3b, v205
	v_exp_f32_e32 v202, v202
	v_exp_f32_e32 v203, v203
	v_exp_f32_e32 v204, v204
	v_exp_f32_e32 v205, v205
	v_mul_f32_e32 v210, v210, v202
	v_mul_f32_e32 v211, v211, v203
	v_mul_f32_e32 v212, v212, v204
	v_mul_f32_e32 v213, v213, v205
	v_cndmask_b32_e64 v69, v210, v206, vcc
	v_cndmask_b32_e64 v71, v211, v207, s[0:1]
	v_cndmask_b32_e64 v72, v212, v208, s[4:5]
	v_cndmask_b32_e64 v73, v213, v209, s[66:67]
	s_waitcnt lgkmcnt(0)
	v_add_u32_e32 v238, 0xffffffc8, v237
	v_cmp_lt_i32_e32 vcc, 0, v238
	v_cmp_lt_i32_e64 s[0:1], 1, v238
	v_cmp_lt_i32_e64 s[4:5], 2, v238
	v_cmp_lt_i32_e64 s[66:67], 3, v238
	v_sub_f32_e32 v218, v126, v218
	v_sub_f32_e32 v219, v126, v219
	v_sub_f32_e32 v220, v126, v220
	v_sub_f32_e32 v221, v126, v221
	v_sub_f32_e32 v222, v127, v222
	v_sub_f32_e32 v223, v127, v223
	v_sub_f32_e32 v224, v127, v224
	v_sub_f32_e32 v225, v127, v225
	v_cndmask_b32_e64 v218, v222, v218, vcc
	v_cndmask_b32_e64 v219, v223, v219, s[0:1]
	v_cndmask_b32_e64 v220, v224, v220, s[4:5]
	v_cndmask_b32_e64 v221, v225, v221, s[66:67]
	v_add_f32_e32 v222, v226, v230
	v_add_f32_e32 v223, v227, v231
	v_add_f32_e32 v224, v228, v232
	v_add_f32_e32 v225, v229, v233
	v_cndmask_b32_e64 v226, v230, v226, vcc
	v_cndmask_b32_e64 v227, v231, v227, s[0:1]
	v_cndmask_b32_e64 v228, v232, v228, s[4:5]
	v_cndmask_b32_e64 v229, v233, v229, s[66:67]
	v_cmp_eq_u32_e32 vcc, 0, v238
	v_cmp_eq_u32_e64 s[0:1], 1, v238
	v_cmp_eq_u32_e64 s[4:5], 2, v238
	v_cmp_eq_u32_e64 s[66:67], 3, v238
	v_mul_f32_e32 v218, 0x3fb8aa3b, v218
	v_mul_f32_e32 v219, 0x3fb8aa3b, v219
	v_mul_f32_e32 v220, 0x3fb8aa3b, v220
	v_mul_f32_e32 v221, 0x3fb8aa3b, v221
	v_exp_f32_e32 v218, v218
	v_exp_f32_e32 v219, v219
	v_exp_f32_e32 v220, v220
	v_exp_f32_e32 v221, v221
	v_mul_f32_e32 v226, v226, v218
	v_mul_f32_e32 v227, v227, v219
	v_mul_f32_e32 v228, v228, v220
	v_mul_f32_e32 v229, v229, v221
	v_cndmask_b32_e64 v74, v226, v222, vcc
	v_cndmask_b32_e64 v75, v227, v223, s[0:1]
	v_cndmask_b32_e64 v76, v228, v224, s[4:5]
	v_cndmask_b32_e64 v77, v229, v225, s[66:67]
	v_mul_f32_e32 v70, v39, v70
	v_mul_f32_e32 v68, v38, v68
	v_mul_f32_e32 v67, v37, v67
	v_mul_f32_e32 v66, v36, v66
	ds_read2_b64 v[36:39], v62 offset0:8 offset1:10
	v_mul_f32_e32 v35, v35, v65
	v_mul_f32_e32 v34, v34, v64
	v_mul_f32_e32 v33, v33, v59
	v_mul_f32_e32 v32, v32, v58
	v_cvt_pk_bf16_f32 v32, v32, v33
	v_cvt_pk_bf16_f32 v33, v34, v35
	v_cvt_pk_bf16_f32 v34, v66, v67
	v_cvt_pk_bf16_f32 v35, v68, v70
	v_mul_f32_e32 v58, v45, v75
	v_mul_f32_e32 v59, v44, v74
	s_waitcnt lgkmcnt(0)
	v_mfma_f32_32x32x16_bf16 v[16:31], v[36:39], v[32:35], v[16:31]
	ds_read2_b64 v[36:39], v63 offset0:72 offset1:74
	v_mul_f32_e32 v64, v43, v73
	v_mul_f32_e32 v65, v42, v72
	ds_read2_b64 v[42:45], v62 offset0:12 offset1:14
	v_mul_f32_e32 v46, v46, v76
	s_waitcnt lgkmcnt(1)
	v_mfma_f32_32x32x16_bf16 v[0:15], v[36:39], v[32:35], v[0:15]
	ds_read2_b64 v[36:39], v63 offset0:76 offset1:78
	v_mul_f32_e32 v32, v41, v71
	v_mul_f32_e32 v33, v40, v69
	v_mul_f32_e32 v35, v47, v77
	v_mul_u32_u24_e32 v40, 0x90, v52
	v_cvt_pk_bf16_f32 v32, v33, v32
	v_cvt_pk_bf16_f32 v33, v65, v64
	v_cvt_pk_bf16_f32 v34, v59, v58
	v_cvt_pk_bf16_f32 v35, v46, v35
	v_add_u32_e32 v57, v57, v40
	v_or_b32_e32 v59, 64, v110
	s_waitcnt lgkmcnt(1)
	v_mfma_f32_32x32x16_bf16 v[16:31], v[42:45], v[32:35], v[16:31]
	v_cmp_ge_u32_e32 vcc, v59, v53
	s_waitcnt lgkmcnt(0)
	v_mfma_f32_32x32x16_bf16 v[0:15], v[36:39], v[32:35], v[0:15]
	ds_read_b128 v[32:35], v57 offset:26624
	ds_read_b128 v[64:67], v57 offset:26656
	s_waitcnt lgkmcnt(1)
	v_mfma_f32_32x32x16_bf16 v[32:47], v[32:35], v[48:51], 0
	s_waitcnt lgkmcnt(0)
	v_mfma_f32_32x32x16_bf16 v[32:47], v[64:67], v[102:105], v[32:47]
	ds_read_b128 v[64:67], v57 offset:26688
	ds_read_b128 v[68:71], v57 offset:26720
	s_waitcnt lgkmcnt(1)
	v_mfma_f32_32x32x16_bf16 v[32:47], v[64:67], v[98:101], v[32:47]
	s_waitcnt lgkmcnt(0)
	v_mfma_f32_32x32x16_bf16 v[32:47], v[68:71], v[94:97], v[32:47]
	v_lshl_add_u32 v236, v110, 2, s23
	v_sub_u32_e32 v237, v53, v110
	ds_read_b128 v[170:173], v236 offset:36096
	ds_read_b128 v[174:177], v236 offset:36608
	ds_read_b128 v[178:181], v236 offset:37120
	ds_read_b128 v[182:185], v236 offset:37632
	ds_read_b128 v[186:189], v236 offset:36128
	ds_read_b128 v[190:193], v236 offset:36640
	ds_read_b128 v[194:197], v236 offset:37152
	ds_read_b128 v[198:201], v236 offset:37664
	ds_read_b128 v[202:205], v236 offset:36160
	ds_read_b128 v[206:209], v236 offset:36672
	ds_read_b128 v[210:213], v236 offset:37184
	ds_read_b128 v[214:217], v236 offset:37696
	s_waitcnt lgkmcnt(8)
	ds_read_b128 v[218:221], v236 offset:36192
	ds_read_b128 v[222:225], v236 offset:36704
	ds_read_b128 v[226:229], v236 offset:37216
	ds_read_b128 v[230:233], v236 offset:37728
	v_add_u32_e32 v238, 0xffffffc0, v237
	v_cmp_lt_i32_e32 vcc, 0, v238
	v_cmp_lt_i32_e64 s[0:1], 1, v238
	v_cmp_lt_i32_e64 s[4:5], 2, v238
	v_cmp_lt_i32_e64 s[66:67], 3, v238
	v_sub_f32_e32 v170, v126, v170
	v_sub_f32_e32 v171, v126, v171
	v_sub_f32_e32 v172, v126, v172
	v_sub_f32_e32 v173, v126, v173
	v_sub_f32_e32 v174, v127, v174
	v_sub_f32_e32 v175, v127, v175
	v_sub_f32_e32 v176, v127, v176
	v_sub_f32_e32 v177, v127, v177
	v_cndmask_b32_e64 v170, v174, v170, vcc
	v_cndmask_b32_e64 v171, v175, v171, s[0:1]
	v_cndmask_b32_e64 v172, v176, v172, s[4:5]
	v_cndmask_b32_e64 v173, v177, v173, s[66:67]
	v_add_f32_e32 v174, v178, v182
	v_add_f32_e32 v175, v179, v183
	v_add_f32_e32 v176, v180, v184
	v_add_f32_e32 v177, v181, v185
	v_cndmask_b32_e64 v178, v182, v178, vcc
	v_cndmask_b32_e64 v179, v183, v179, s[0:1]
	v_cndmask_b32_e64 v180, v184, v180, s[4:5]
	v_cndmask_b32_e64 v181, v185, v181, s[66:67]
	v_cmp_eq_u32_e32 vcc, 0, v238
	v_cmp_eq_u32_e64 s[0:1], 1, v238
	v_cmp_eq_u32_e64 s[4:5], 2, v238
	v_cmp_eq_u32_e64 s[66:67], 3, v238
	v_mul_f32_e32 v170, 0x3fb8aa3b, v170
	v_mul_f32_e32 v171, 0x3fb8aa3b, v171
	v_mul_f32_e32 v172, 0x3fb8aa3b, v172
	v_mul_f32_e32 v173, 0x3fb8aa3b, v173
	v_exp_f32_e32 v170, v170
	v_exp_f32_e32 v171, v171
	v_exp_f32_e32 v172, v172
	v_exp_f32_e32 v173, v173
	v_mul_f32_e32 v178, v178, v170
	v_mul_f32_e32 v179, v179, v171
	v_mul_f32_e32 v180, v180, v172
	v_mul_f32_e32 v181, v181, v173
	v_cndmask_b32_e64 v58, v178, v174, vcc
	v_cndmask_b32_e64 v59, v179, v175, s[0:1]
	v_cndmask_b32_e64 v64, v180, v176, s[4:5]
	v_cndmask_b32_e64 v65, v181, v177, s[66:67]
	s_waitcnt lgkmcnt(8)
	v_add_u32_e32 v238, 0xffffffb8, v237
	v_cmp_lt_i32_e32 vcc, 0, v238
	v_cmp_lt_i32_e64 s[0:1], 1, v238
	v_cmp_lt_i32_e64 s[4:5], 2, v238
	v_cmp_lt_i32_e64 s[66:67], 3, v238
	v_sub_f32_e32 v186, v126, v186
	v_sub_f32_e32 v187, v126, v187
	v_sub_f32_e32 v188, v126, v188
	v_sub_f32_e32 v189, v126, v189
	v_sub_f32_e32 v190, v127, v190
	v_sub_f32_e32 v191, v127, v191
	v_sub_f32_e32 v192, v127, v192
	v_sub_f32_e32 v193, v127, v193
	v_cndmask_b32_e64 v186, v190, v186, vcc
	v_cndmask_b32_e64 v187, v191, v187, s[0:1]
	v_cndmask_b32_e64 v188, v192, v188, s[4:5]
	v_cndmask_b32_e64 v189, v193, v189, s[66:67]
	v_add_f32_e32 v190, v194, v198
	v_add_f32_e32 v191, v195, v199
	v_add_f32_e32 v192, v196, v200
	v_add_f32_e32 v193, v197, v201
	v_cndmask_b32_e64 v194, v198, v194, vcc
	v_cndmask_b32_e64 v195, v199, v195, s[0:1]
	v_cndmask_b32_e64 v196, v200, v196, s[4:5]
	v_cndmask_b32_e64 v197, v201, v197, s[66:67]
	v_cmp_eq_u32_e32 vcc, 0, v238
	v_cmp_eq_u32_e64 s[0:1], 1, v238
	v_cmp_eq_u32_e64 s[4:5], 2, v238
	v_cmp_eq_u32_e64 s[66:67], 3, v238
	v_mul_f32_e32 v186, 0x3fb8aa3b, v186
	v_mul_f32_e32 v187, 0x3fb8aa3b, v187
	v_mul_f32_e32 v188, 0x3fb8aa3b, v188
	v_mul_f32_e32 v189, 0x3fb8aa3b, v189
	v_exp_f32_e32 v186, v186
	v_exp_f32_e32 v187, v187
	v_exp_f32_e32 v188, v188
	v_exp_f32_e32 v189, v189
	v_mul_f32_e32 v194, v194, v186
	v_mul_f32_e32 v195, v195, v187
	v_mul_f32_e32 v196, v196, v188
	v_mul_f32_e32 v197, v197, v189
	v_cndmask_b32_e64 v66, v194, v190, vcc
	v_cndmask_b32_e64 v67, v195, v191, s[0:1]
	v_cndmask_b32_e64 v68, v196, v192, s[4:5]
	v_cndmask_b32_e64 v70, v197, v193, s[66:67]
	s_waitcnt lgkmcnt(4)
	v_add_u32_e32 v238, 0xffffffb0, v237
	v_cmp_lt_i32_e32 vcc, 0, v238
	v_cmp_lt_i32_e64 s[0:1], 1, v238
	v_cmp_lt_i32_e64 s[4:5], 2, v238
	v_cmp_lt_i32_e64 s[66:67], 3, v238
	v_sub_f32_e32 v202, v126, v202
	v_sub_f32_e32 v203, v126, v203
	v_sub_f32_e32 v204, v126, v204
	v_sub_f32_e32 v205, v126, v205
	v_sub_f32_e32 v206, v127, v206
	v_sub_f32_e32 v207, v127, v207
	v_sub_f32_e32 v208, v127, v208
	v_sub_f32_e32 v209, v127, v209
	v_cndmask_b32_e64 v202, v206, v202, vcc
	v_cndmask_b32_e64 v203, v207, v203, s[0:1]
	v_cndmask_b32_e64 v204, v208, v204, s[4:5]
	v_cndmask_b32_e64 v205, v209, v205, s[66:67]
	v_add_f32_e32 v206, v210, v214
	v_add_f32_e32 v207, v211, v215
	v_add_f32_e32 v208, v212, v216
	v_add_f32_e32 v209, v213, v217
	v_cndmask_b32_e64 v210, v214, v210, vcc
	v_cndmask_b32_e64 v211, v215, v211, s[0:1]
	v_cndmask_b32_e64 v212, v216, v212, s[4:5]
	v_cndmask_b32_e64 v213, v217, v213, s[66:67]
	v_cmp_eq_u32_e32 vcc, 0, v238
	v_cmp_eq_u32_e64 s[0:1], 1, v238
	v_cmp_eq_u32_e64 s[4:5], 2, v238
	v_cmp_eq_u32_e64 s[66:67], 3, v238
	v_mul_f32_e32 v202, 0x3fb8aa3b, v202
	v_mul_f32_e32 v203, 0x3fb8aa3b, v203
	v_mul_f32_e32 v204, 0x3fb8aa3b, v204
	v_mul_f32_e32 v205, 0x3fb8aa3b, v205
	v_exp_f32_e32 v202, v202
	v_exp_f32_e32 v203, v203
	v_exp_f32_e32 v204, v204
	v_exp_f32_e32 v205, v205
	v_mul_f32_e32 v210, v210, v202
	v_mul_f32_e32 v211, v211, v203
	v_mul_f32_e32 v212, v212, v204
	v_mul_f32_e32 v213, v213, v205
	v_cndmask_b32_e64 v69, v210, v206, vcc
	v_cndmask_b32_e64 v71, v211, v207, s[0:1]
	v_cndmask_b32_e64 v72, v212, v208, s[4:5]
	v_cndmask_b32_e64 v73, v213, v209, s[66:67]
	s_waitcnt lgkmcnt(0)
	v_add_u32_e32 v238, 0xffffffa8, v237
	v_cmp_lt_i32_e32 vcc, 0, v238
	v_cmp_lt_i32_e64 s[0:1], 1, v238
	v_cmp_lt_i32_e64 s[4:5], 2, v238
	v_cmp_lt_i32_e64 s[66:67], 3, v238
	v_sub_f32_e32 v218, v126, v218
	v_sub_f32_e32 v219, v126, v219
	v_sub_f32_e32 v220, v126, v220
	v_sub_f32_e32 v221, v126, v221
	v_sub_f32_e32 v222, v127, v222
	v_sub_f32_e32 v223, v127, v223
	v_sub_f32_e32 v224, v127, v224
	v_sub_f32_e32 v225, v127, v225
	v_cndmask_b32_e64 v218, v222, v218, vcc
	v_cndmask_b32_e64 v219, v223, v219, s[0:1]
	v_cndmask_b32_e64 v220, v224, v220, s[4:5]
	v_cndmask_b32_e64 v221, v225, v221, s[66:67]
	v_add_f32_e32 v222, v226, v230
	v_add_f32_e32 v223, v227, v231
	v_add_f32_e32 v224, v228, v232
	v_add_f32_e32 v225, v229, v233
	v_cndmask_b32_e64 v226, v230, v226, vcc
	v_cndmask_b32_e64 v227, v231, v227, s[0:1]
	v_cndmask_b32_e64 v228, v232, v228, s[4:5]
	v_cndmask_b32_e64 v229, v233, v229, s[66:67]
	v_cmp_eq_u32_e32 vcc, 0, v238
	v_cmp_eq_u32_e64 s[0:1], 1, v238
	v_cmp_eq_u32_e64 s[4:5], 2, v238
	v_cmp_eq_u32_e64 s[66:67], 3, v238
	v_mul_f32_e32 v218, 0x3fb8aa3b, v218
	v_mul_f32_e32 v219, 0x3fb8aa3b, v219
	v_mul_f32_e32 v220, 0x3fb8aa3b, v220
	v_mul_f32_e32 v221, 0x3fb8aa3b, v221
	v_exp_f32_e32 v218, v218
	v_exp_f32_e32 v219, v219
	v_exp_f32_e32 v220, v220
	v_exp_f32_e32 v221, v221
	v_mul_f32_e32 v226, v226, v218
	v_mul_f32_e32 v227, v227, v219
	v_mul_f32_e32 v228, v228, v220
	v_mul_f32_e32 v229, v229, v221
	v_cndmask_b32_e64 v74, v226, v222, vcc
	v_cndmask_b32_e64 v75, v227, v223, s[0:1]
	v_cndmask_b32_e64 v76, v228, v224, s[4:5]
	v_cndmask_b32_e64 v77, v229, v225, s[66:67]
	v_mul_f32_e32 v70, v39, v70
	v_mul_f32_e32 v68, v38, v68
	v_mul_f32_e32 v67, v37, v67
	v_mul_f32_e32 v66, v36, v66
	ds_read2_b64 v[36:39], v62 offset0:16 offset1:18
	v_mul_f32_e32 v35, v35, v65
	v_mul_f32_e32 v34, v34, v64
	v_mul_f32_e32 v33, v33, v59
	v_mul_f32_e32 v32, v32, v58
	v_cvt_pk_bf16_f32 v32, v32, v33
	v_cvt_pk_bf16_f32 v33, v34, v35
	v_cvt_pk_bf16_f32 v34, v66, v67
	v_cvt_pk_bf16_f32 v35, v68, v70
	v_mul_f32_e32 v58, v45, v75
	v_mul_f32_e32 v59, v44, v74
	s_waitcnt lgkmcnt(0)
	v_mfma_f32_32x32x16_bf16 v[16:31], v[36:39], v[32:35], v[16:31]
	ds_read2_b64 v[36:39], v63 offset0:80 offset1:82
	v_mul_f32_e32 v64, v43, v73
	v_mul_f32_e32 v65, v42, v72
	ds_read2_b64 v[42:45], v62 offset0:20 offset1:22
	v_mul_f32_e32 v46, v46, v76
	s_waitcnt lgkmcnt(1)
	v_mfma_f32_32x32x16_bf16 v[0:15], v[36:39], v[32:35], v[0:15]
	ds_read2_b64 v[36:39], v63 offset0:84 offset1:86
	v_mul_f32_e32 v32, v41, v71
	v_mul_f32_e32 v33, v40, v69
	v_mul_f32_e32 v35, v47, v77
	v_cvt_pk_bf16_f32 v32, v33, v32
	v_cvt_pk_bf16_f32 v33, v65, v64
	v_cvt_pk_bf16_f32 v34, v59, v58
	v_cvt_pk_bf16_f32 v35, v46, v35
	v_or_b32_e32 v58, 0x60, v110
	v_cmp_ge_u32_e32 vcc, v58, v53
	s_waitcnt lgkmcnt(1)
	v_mfma_f32_32x32x16_bf16 v[16:31], v[42:45], v[32:35], v[16:31]
	s_waitcnt lgkmcnt(0)
	v_mfma_f32_32x32x16_bf16 v[0:15], v[36:39], v[32:35], v[0:15]
	ds_read_b128 v[32:35], v57 offset:31232
	ds_read_b128 v[64:67], v57 offset:31264
	s_waitcnt lgkmcnt(1)
	v_mfma_f32_32x32x16_bf16 v[32:47], v[32:35], v[48:51], 0
	s_waitcnt lgkmcnt(0)
	v_mfma_f32_32x32x16_bf16 v[32:47], v[64:67], v[102:105], v[32:47]
	ds_read_b128 v[64:67], v57 offset:31296
	ds_read_b128 v[68:71], v57 offset:31328
	s_waitcnt lgkmcnt(1)
	v_mfma_f32_32x32x16_bf16 v[32:47], v[64:67], v[98:101], v[32:47]
	s_waitcnt lgkmcnt(0)
	v_mfma_f32_32x32x16_bf16 v[32:47], v[68:71], v[94:97], v[32:47]
	v_lshl_add_u32 v236, v110, 2, s23
	v_sub_u32_e32 v237, v53, v110
	ds_read_b128 v[170:173], v236 offset:36224
	ds_read_b128 v[174:177], v236 offset:36736
	ds_read_b128 v[178:181], v236 offset:37248
	ds_read_b128 v[182:185], v236 offset:37760
	ds_read_b128 v[186:189], v236 offset:36256
	ds_read_b128 v[190:193], v236 offset:36768
	ds_read_b128 v[194:197], v236 offset:37280
	ds_read_b128 v[198:201], v236 offset:37792
	ds_read_b128 v[202:205], v236 offset:36288
	ds_read_b128 v[206:209], v236 offset:36800
	ds_read_b128 v[210:213], v236 offset:37312
	ds_read_b128 v[214:217], v236 offset:37824
	s_waitcnt lgkmcnt(8)
	ds_read_b128 v[218:221], v236 offset:36320
	ds_read_b128 v[222:225], v236 offset:36832
	ds_read_b128 v[226:229], v236 offset:37344
	ds_read_b128 v[230:233], v236 offset:37856
	v_add_u32_e32 v238, 0xffffffa0, v237
	v_cmp_lt_i32_e32 vcc, 0, v238
	v_cmp_lt_i32_e64 s[0:1], 1, v238
	v_cmp_lt_i32_e64 s[4:5], 2, v238
	v_cmp_lt_i32_e64 s[66:67], 3, v238
	v_sub_f32_e32 v170, v126, v170
	v_sub_f32_e32 v171, v126, v171
	v_sub_f32_e32 v172, v126, v172
	v_sub_f32_e32 v173, v126, v173
	v_sub_f32_e32 v174, v127, v174
	v_sub_f32_e32 v175, v127, v175
	v_sub_f32_e32 v176, v127, v176
	v_sub_f32_e32 v177, v127, v177
	v_cndmask_b32_e64 v170, v174, v170, vcc
	v_cndmask_b32_e64 v171, v175, v171, s[0:1]
	v_cndmask_b32_e64 v172, v176, v172, s[4:5]
	v_cndmask_b32_e64 v173, v177, v173, s[66:67]
	v_add_f32_e32 v174, v178, v182
	v_add_f32_e32 v175, v179, v183
	v_add_f32_e32 v176, v180, v184
	v_add_f32_e32 v177, v181, v185
	v_cndmask_b32_e64 v178, v182, v178, vcc
	v_cndmask_b32_e64 v179, v183, v179, s[0:1]
	v_cndmask_b32_e64 v180, v184, v180, s[4:5]
	v_cndmask_b32_e64 v181, v185, v181, s[66:67]
	v_cmp_eq_u32_e32 vcc, 0, v238
	v_cmp_eq_u32_e64 s[0:1], 1, v238
	v_cmp_eq_u32_e64 s[4:5], 2, v238
	v_cmp_eq_u32_e64 s[66:67], 3, v238
	v_mul_f32_e32 v170, 0x3fb8aa3b, v170
	v_mul_f32_e32 v171, 0x3fb8aa3b, v171
	v_mul_f32_e32 v172, 0x3fb8aa3b, v172
	v_mul_f32_e32 v173, 0x3fb8aa3b, v173
	v_exp_f32_e32 v170, v170
	v_exp_f32_e32 v171, v171
	v_exp_f32_e32 v172, v172
	v_exp_f32_e32 v173, v173
	v_mul_f32_e32 v178, v178, v170
	v_mul_f32_e32 v179, v179, v171
	v_mul_f32_e32 v180, v180, v172
	v_mul_f32_e32 v181, v181, v173
	v_cndmask_b32_e64 v57, v178, v174, vcc
	v_cndmask_b32_e64 v58, v179, v175, s[0:1]
	v_cndmask_b32_e64 v59, v180, v176, s[4:5]
	v_cndmask_b32_e64 v64, v181, v177, s[66:67]
	s_waitcnt lgkmcnt(8)
	v_add_u32_e32 v238, 0xffffff98, v237
	v_cmp_lt_i32_e32 vcc, 0, v238
	v_cmp_lt_i32_e64 s[0:1], 1, v238
	v_cmp_lt_i32_e64 s[4:5], 2, v238
	v_cmp_lt_i32_e64 s[66:67], 3, v238
	v_sub_f32_e32 v186, v126, v186
	v_sub_f32_e32 v187, v126, v187
	v_sub_f32_e32 v188, v126, v188
	v_sub_f32_e32 v189, v126, v189
	v_sub_f32_e32 v190, v127, v190
	v_sub_f32_e32 v191, v127, v191
	v_sub_f32_e32 v192, v127, v192
	v_sub_f32_e32 v193, v127, v193
	v_cndmask_b32_e64 v186, v190, v186, vcc
	v_cndmask_b32_e64 v187, v191, v187, s[0:1]
	v_cndmask_b32_e64 v188, v192, v188, s[4:5]
	v_cndmask_b32_e64 v189, v193, v189, s[66:67]
	v_add_f32_e32 v190, v194, v198
	v_add_f32_e32 v191, v195, v199
	v_add_f32_e32 v192, v196, v200
	v_add_f32_e32 v193, v197, v201
	v_cndmask_b32_e64 v194, v198, v194, vcc
	v_cndmask_b32_e64 v195, v199, v195, s[0:1]
	v_cndmask_b32_e64 v196, v200, v196, s[4:5]
	v_cndmask_b32_e64 v197, v201, v197, s[66:67]
	v_cmp_eq_u32_e32 vcc, 0, v238
	v_cmp_eq_u32_e64 s[0:1], 1, v238
	v_cmp_eq_u32_e64 s[4:5], 2, v238
	v_cmp_eq_u32_e64 s[66:67], 3, v238
	v_mul_f32_e32 v186, 0x3fb8aa3b, v186
	v_mul_f32_e32 v187, 0x3fb8aa3b, v187
	v_mul_f32_e32 v188, 0x3fb8aa3b, v188
	v_mul_f32_e32 v189, 0x3fb8aa3b, v189
	v_exp_f32_e32 v186, v186
	v_exp_f32_e32 v187, v187
	v_exp_f32_e32 v188, v188
	v_exp_f32_e32 v189, v189
	v_mul_f32_e32 v194, v194, v186
	v_mul_f32_e32 v195, v195, v187
	v_mul_f32_e32 v196, v196, v188
	v_mul_f32_e32 v197, v197, v189
	v_cndmask_b32_e64 v56, v194, v190, vcc
	v_cndmask_b32_e64 v65, v195, v191, s[0:1]
	v_cndmask_b32_e64 v66, v196, v192, s[4:5]
	v_cndmask_b32_e64 v67, v197, v193, s[66:67]
	s_waitcnt lgkmcnt(4)
	v_add_u32_e32 v238, 0xffffff90, v237
	v_cmp_lt_i32_e32 vcc, 0, v238
	v_cmp_lt_i32_e64 s[0:1], 1, v238
	v_cmp_lt_i32_e64 s[4:5], 2, v238
	v_cmp_lt_i32_e64 s[66:67], 3, v238
	v_sub_f32_e32 v202, v126, v202
	v_sub_f32_e32 v203, v126, v203
	v_sub_f32_e32 v204, v126, v204
	v_sub_f32_e32 v205, v126, v205
	v_sub_f32_e32 v206, v127, v206
	v_sub_f32_e32 v207, v127, v207
	v_sub_f32_e32 v208, v127, v208
	v_sub_f32_e32 v209, v127, v209
	v_cndmask_b32_e64 v202, v206, v202, vcc
	v_cndmask_b32_e64 v203, v207, v203, s[0:1]
	v_cndmask_b32_e64 v204, v208, v204, s[4:5]
	v_cndmask_b32_e64 v205, v209, v205, s[66:67]
	v_add_f32_e32 v206, v210, v214
	v_add_f32_e32 v207, v211, v215
	v_add_f32_e32 v208, v212, v216
	v_add_f32_e32 v209, v213, v217
	v_cndmask_b32_e64 v210, v214, v210, vcc
	v_cndmask_b32_e64 v211, v215, v211, s[0:1]
	v_cndmask_b32_e64 v212, v216, v212, s[4:5]
	v_cndmask_b32_e64 v213, v217, v213, s[66:67]
	v_cmp_eq_u32_e32 vcc, 0, v238
	v_cmp_eq_u32_e64 s[0:1], 1, v238
	v_cmp_eq_u32_e64 s[4:5], 2, v238
	v_cmp_eq_u32_e64 s[66:67], 3, v238
	v_mul_f32_e32 v202, 0x3fb8aa3b, v202
	v_mul_f32_e32 v203, 0x3fb8aa3b, v203
	v_mul_f32_e32 v204, 0x3fb8aa3b, v204
	v_mul_f32_e32 v205, 0x3fb8aa3b, v205
	v_exp_f32_e32 v202, v202
	v_exp_f32_e32 v203, v203
	v_exp_f32_e32 v204, v204
	v_exp_f32_e32 v205, v205
	v_mul_f32_e32 v210, v210, v202
	v_mul_f32_e32 v211, v211, v203
	v_mul_f32_e32 v212, v212, v204
	v_mul_f32_e32 v213, v213, v205
	v_cndmask_b32_e64 v68, v210, v206, vcc
	v_cndmask_b32_e64 v69, v211, v207, s[0:1]
	v_cndmask_b32_e64 v70, v212, v208, s[4:5]
	v_cndmask_b32_e64 v71, v213, v209, s[66:67]
	s_waitcnt lgkmcnt(0)
	v_add_u32_e32 v238, 0xffffff88, v237
	v_cmp_lt_i32_e32 vcc, 0, v238
	v_cmp_lt_i32_e64 s[0:1], 1, v238
	v_cmp_lt_i32_e64 s[4:5], 2, v238
	v_cmp_lt_i32_e64 s[66:67], 3, v238
	v_sub_f32_e32 v218, v126, v218
	v_sub_f32_e32 v219, v126, v219
	v_sub_f32_e32 v220, v126, v220
	v_sub_f32_e32 v221, v126, v221
	v_sub_f32_e32 v222, v127, v222
	v_sub_f32_e32 v223, v127, v223
	v_sub_f32_e32 v224, v127, v224
	v_sub_f32_e32 v225, v127, v225
	v_cndmask_b32_e64 v218, v222, v218, vcc
	v_cndmask_b32_e64 v219, v223, v219, s[0:1]
	v_cndmask_b32_e64 v220, v224, v220, s[4:5]
	v_cndmask_b32_e64 v221, v225, v221, s[66:67]
	v_add_f32_e32 v222, v226, v230
	v_add_f32_e32 v223, v227, v231
	v_add_f32_e32 v224, v228, v232
	v_add_f32_e32 v225, v229, v233
	v_cndmask_b32_e64 v226, v230, v226, vcc
	v_cndmask_b32_e64 v227, v231, v227, s[0:1]
	v_cndmask_b32_e64 v228, v232, v228, s[4:5]
	v_cndmask_b32_e64 v229, v233, v229, s[66:67]
	v_cmp_eq_u32_e32 vcc, 0, v238
	v_cmp_eq_u32_e64 s[0:1], 1, v238
	v_cmp_eq_u32_e64 s[4:5], 2, v238
	v_cmp_eq_u32_e64 s[66:67], 3, v238
	v_mul_f32_e32 v218, 0x3fb8aa3b, v218
	v_mul_f32_e32 v219, 0x3fb8aa3b, v219
	v_mul_f32_e32 v220, 0x3fb8aa3b, v220
	v_mul_f32_e32 v221, 0x3fb8aa3b, v221
	v_exp_f32_e32 v218, v218
	v_exp_f32_e32 v219, v219
	v_exp_f32_e32 v220, v220
	v_exp_f32_e32 v221, v221
	v_mul_f32_e32 v226, v226, v218
	v_mul_f32_e32 v227, v227, v219
	v_mul_f32_e32 v228, v228, v220
	v_mul_f32_e32 v229, v229, v221
	v_cndmask_b32_e64 v72, v226, v222, vcc
	v_cndmask_b32_e64 v73, v227, v223, s[0:1]
	v_cndmask_b32_e64 v75, v228, v224, s[4:5]
	v_cndmask_b32_e64 v74, v229, v225, s[66:67]
	s_lshl_b32 s0, s77, 6
	s_mul_i32 s1, s79, 34
	s_add_i32 s4, s1, s78
	s_ashr_i32 s5, s4, 31
	s_lshl_b64 s[4:5], s[4:5], 16
	s_lshl_b32 s1, s77, 13
	s_add_u32 s40, s55, s1
	s_addc_u32 s41, s63, 0
	v_lshlrev_b32_e32 v122, 1, v54
	v_lshl_add_u64 v[54:55], s[40:41], 0, v[122:123]
	v_lshl_add_u64 v[54:55], v[54:55], 0, s[4:5]
	v_lshlrev_b32_e32 v122, 7, v52
	v_lshl_add_u64 v[92:93], v[54:55], 0, v[122:123]
	global_load_dwordx4 v[76:79], v[92:93], off
	v_mov_b32_e32 v107, v123
	v_or_b32_e32 v106, 0x1000, v122
	s_mov_b64 s[4:5], 0x880000
	v_lshl_add_u64 v[112:113], v[54:55], 0, v[106:107]
	v_lshl_add_u64 v[108:109], v[54:55], 0, s[4:5]
	global_load_dwordx4 v[52:55], v[92:93], off offset:32
	global_load_dwordx4 v[80:83], v[112:113], off
	global_load_dwordx4 v[138:141], v[92:93], off offset:64
	v_mul_f32_e32 v46, v46, v75
	v_mul_f32_e32 v45, v45, v73
	v_mul_f32_e32 v73, v37, v65
	v_mul_f32_e32 v56, v36, v56
	v_mul_f32_e32 v75, v35, v64
	v_mul_f32_e32 v59, v34, v59
	v_mul_f32_e32 v33, v33, v58
	v_mul_f32_e32 v32, v32, v57
	v_cvt_pk_bf16_f32 v89, v59, v75
	v_cvt_pk_bf16_f32 v90, v56, v73
	global_load_dwordx4 v[56:59], v[112:113], off offset:32
	global_load_dwordx4 v[142:145], v[112:113], off offset:64
	v_lshl_add_u64 v[114:115], v[108:109], 0, v[122:123]
	global_load_dwordx4 v[84:87], v[114:115], off
	global_load_dwordx4 v[134:137], v[114:115], off offset:32
	ds_read2_b64 v[34:37], v62 offset0:24 offset1:26
	v_mul_f32_e32 v39, v39, v67
	v_mul_f32_e32 v38, v38, v66
	ds_read2_b64 v[64:67], v63 offset0:88 offset1:90
	v_cvt_pk_bf16_f32 v88, v32, v33
	v_cvt_pk_bf16_f32 v91, v38, v39
	v_mul_f32_e32 v44, v44, v72
	v_mul_f32_e32 v43, v43, v71
	s_waitcnt lgkmcnt(1)
	v_mfma_f32_32x32x16_bf16 v[16:31], v[34:37], v[88:91], v[16:31]
	ds_read2_b64 v[32:35], v62 offset0:28 offset1:30
	ds_read2_b64 v[36:39], v63 offset0:92 offset1:94
	global_load_dwordx4 v[146:149], v[92:93], off offset:96
	global_load_dwordx4 v[170:173], v[112:113], off offset:96
	global_load_dwordx4 v[174:177], v[114:115], off offset:64
	v_mul_f32_e32 v42, v42, v70
	v_mul_f32_e32 v41, v41, v69
	v_mul_f32_e32 v40, v40, v68
	s_waitcnt lgkmcnt(2)
	v_mfma_f32_32x32x16_bf16 v[0:15], v[64:67], v[88:91], v[0:15]
	v_mul_f32_e32 v47, v47, v74
	s_movk_i32 s1, 0x1360
	global_load_dwordx4 v[118:121], v[114:115], off offset:96
	s_lshl_b32 s60, s0, 1
	v_lshlrev_b32_e32 v122, 1, v110
	v_lshl_add_u64 v[106:107], v[108:109], 0, v[106:107]
	v_cvt_pk_bf16_f32 v40, v40, v41
	v_cvt_pk_bf16_f32 v41, v42, v43
	v_cvt_pk_bf16_f32 v42, v44, v45
	v_cvt_pk_bf16_f32 v43, v46, v47
	v_ashrrev_i32_e32 v125, 31, v124
	s_waitcnt vmcnt(11)
	v_mfma_f32_32x32x16_bf16 v[62:77], v[76:79], v[48:51], 0
	v_mov_b64_e32 v[78:79], s[6:7]
	v_mad_i64_i32 v[178:179], s[4:5], v124, s1, v[78:79]
	v_lshl_add_u64 v[112:113], v[178:179], 0, s[60:61]
	v_lshl_add_u64 v[150:151], v[112:113], 0, v[122:123]
	v_add_co_u32_e32 v110, vcc, s73, v150
	s_waitcnt vmcnt(10)
	v_mfma_f32_32x32x16_bf16 v[62:77], v[52:55], v[102:105], v[62:77]
	v_addc_co_u32_e32 v111, vcc, 0, v151, vcc
	global_load_dwordx2 v[162:163], v[110:111], off offset:2368
	global_load_dwordx4 v[52:55], v[106:107], off
	global_load_dwordx4 v[114:117], v[106:107], off offset:32
	s_lshl_b32 s4, s77, 2
	global_load_dwordx4 v[110:113], v[106:107], off offset:64
	s_waitcnt lgkmcnt(1)
	v_mfma_f32_32x32x16_bf16 v[16:31], v[32:35], v[40:43], v[16:31]
	s_mov_b64 s[0:1], 0x54dc940
	s_waitcnt vmcnt(3)
	v_lshlrev_b32_e32 v169, 16, v162
	s_waitcnt lgkmcnt(0)
	v_mfma_f32_32x32x16_bf16 v[0:15], v[36:39], v[40:43], v[0:15]
	v_and_b32_e32 v162, 0xffff0000, v162
	v_mfma_f32_32x32x16_bf16 v[32:47], v[80:83], v[48:51], 0
	v_mfma_f32_32x32x16_bf16 v[32:47], v[56:59], v[102:105], v[32:47]
	v_lshl_add_u64 v[56:57], v[60:61], 0, s[60:61]
	v_lshl_add_u64 v[56:57], v[56:57], 0, v[122:123]
	global_load_dwordx2 v[160:161], v[56:57], off
	v_mov_b32_e32 v58, s4
	global_load_dword v128, v58, s[16:17]
	v_mul_f32_e32 v58, 0x3fb8aa3b, v126
	global_load_dwordx4 v[106:109], v[106:107], off offset:96
	v_mfma_f32_32x32x16_bf16 v[78:93], v[84:87], v[48:51], 0
	v_mul_f32_e32 v59, 0x3fb8aa3b, v127
	v_exp_f32_e32 v130, v58
	v_exp_f32_e32 v132, v59
	v_lshl_add_u64 v[58:59], v[150:151], 0, s[0:1]
	v_mfma_f32_32x32x16_bf16 v[78:93], v[134:137], v[102:105], v[78:93]
	v_mfma_f32_32x32x16_bf16 v[62:77], v[138:141], v[98:101], v[62:77]
	v_mfma_f32_32x32x16_bf16 v[32:47], v[142:145], v[98:101], v[32:47]
	v_mfma_f32_32x32x16_bf16 v[62:77], v[146:149], v[94:97], v[62:77]
	global_load_dwordx2 v[156:157], v[56:57], off offset:16
	global_load_dwordx2 v[152:153], v[56:57], off offset:32
	global_load_dwordx2 v[148:149], v[56:57], off offset:48
	global_load_dwordx2 v[144:145], v[56:57], off offset:64
	global_load_dwordx2 v[140:141], v[56:57], off offset:80
	global_load_dwordx2 v[136:137], v[56:57], off offset:96
	global_load_dwordx2 v[126:127], v[56:57], off offset:112
	global_load_dwordx2 v[158:159], v[58:59], off offset:16
	global_load_dwordx2 v[154:155], v[58:59], off offset:32
	global_load_dwordx2 v[150:151], v[58:59], off offset:48
	global_load_dwordx2 v[146:147], v[58:59], off offset:64
	global_load_dwordx2 v[142:143], v[58:59], off offset:80
	global_load_dwordx2 v[138:139], v[58:59], off offset:96
	global_load_dwordx2 v[134:135], v[58:59], off offset:112
	v_mul_f32_e32 v58, 0xbfb8aa3b, v169
	v_mul_f32_e32 v59, 0xbfb8aa3b, v162
	v_exp_f32_e32 v58, v58
	v_exp_f32_e32 v59, v59
	v_mfma_f32_32x32x16_bf16 v[78:93], v[174:177], v[98:101], v[78:93]
	v_mad_i64_i32 v[56:57], s[0:1], v124, s74, v[178:179]
	v_fma_f32 v16, v130, v62, v16
	v_fma_f32 v17, v130, v63, v17
	v_fma_f32 v18, v130, v64, v18
	v_fma_f32 v19, v130, v65, v19
	v_mfma_f32_32x32x16_bf16 v[78:93], v[118:121], v[94:97], v[78:93]
	v_lshl_add_u64 v[118:119], v[56:57], 0, s[60:61]
	s_waitcnt vmcnt(16)
	v_lshlrev_b32_e32 v120, 16, v160
	s_nop 8
	v_pk_fma_f32 v[16:17], v[132:133], v[78:79], v[16:17] op_sel_hi:[0,1,1]
	v_pk_add_f32 v[78:79], v[58:59], 1.0 op_sel_hi:[1,0]
	v_mfma_f32_32x32x16_bf16 v[48:63], v[52:55], v[48:51], 0
	v_and_b32_e32 v121, 0xffff0000, v160
	s_waitcnt vmcnt(15)
	v_fma_f32 v16, v128, v120, v16
	v_fma_f32 v17, v128, v121, v17
	v_fma_f32 v18, v132, v80, v18
	v_fma_f32 v19, v132, v81, v19
	v_mfma_f32_32x32x16_bf16 v[48:63], v[114:117], v[102:105], v[48:63]
	v_div_scale_f32 v102, vcc, v162, v79, v162
	v_mfma_f32_32x32x16_bf16 v[32:47], v[170:173], v[94:97], v[32:47]
	v_div_scale_f32 v170, s[0:1], v79, v79, v162
	v_rcp_f32_e32 v171, v170
	s_nop 0
	v_fma_f32 v120, -v170, v171, 1.0
	v_mfma_f32_32x32x16_bf16 v[48:63], v[110:113], v[98:101], v[48:63]
	v_fmac_f32_e32 v171, v120, v171
	v_mul_f32_e32 v103, v102, v171
	v_div_scale_f32 v98, s[0:1], v78, v78, v169
	v_fma_f32 v104, -v170, v103, v102
	v_rcp_f32_e32 v99, v98
	v_fmac_f32_e32 v103, v104, v171
	v_fma_f32 v102, -v170, v103, v102
	v_div_fmas_f32 v100, v102, v171, v103
	v_div_fixup_f32 v79, v100, v79, v162
	v_fma_f32 v100, -v98, v99, 1.0
	v_fmac_f32_e32 v99, v100, v99
	s_waitcnt vmcnt(14)
	v_mfma_f32_32x32x16_bf16 v[48:63], v[106:109], v[94:97], v[48:63]
	v_div_scale_f32 v94, vcc, v169, v78, v169
	v_mul_f32_e32 v95, v94, v99
	v_fma_f32 v96, -v98, v95, v94
	v_fmac_f32_e32 v95, v96, v99
	v_fma_f32 v94, -v98, v95, v94
	v_div_fmas_f32 v94, v94, v99, v95
	v_lshlrev_b32_e32 v96, 16, v163
	v_and_b32_e32 v97, 0xffff0000, v163
	v_div_fixup_f32 v78, v94, v78, v169
	v_mul_f32_e32 v94, 0xbfb8aa3b, v96
	v_mul_f32_e32 v95, 0xbfb8aa3b, v97
	v_exp_f32_e32 v94, v94
	v_exp_f32_e32 v95, v95
	v_pk_mul_f32 v[16:17], v[16:17], v[78:79]
	v_lshlrev_b32_e32 v78, 16, v161
	v_and_b32_e32 v79, 0xffff0000, v161
	v_pk_add_f32 v[64:65], v[94:95], 1.0 op_sel_hi:[1,0]
	v_pk_fma_f32 v[18:19], v[128:129], v[78:79], v[18:19] op_sel_hi:[0,1,1]
	v_div_scale_f32 v80, s[0:1], v65, v65, v97
	v_rcp_f32_e32 v81, v80
	v_pk_fma_f32 v[0:1], v[130:131], v[32:33], v[0:1] op_sel_hi:[0,1,1]
	v_pk_fma_f32 v[0:1], v[132:133], v[48:49], v[0:1] op_sel_hi:[0,1,1]
	v_pk_fma_f32 v[2:3], v[130:131], v[34:35], v[2:3] op_sel_hi:[0,1,1]
	v_fma_f32 v78, -v80, v81, 1.0
	v_fmac_f32_e32 v81, v78, v81
	v_div_scale_f32 v78, vcc, v97, v65, v97
	v_mul_f32_e32 v79, v78, v81
	v_fma_f32 v94, -v80, v79, v78
	v_fmac_f32_e32 v79, v94, v81
	v_fma_f32 v78, -v80, v79, v78
	v_div_scale_f32 v80, s[0:1], v64, v64, v96
	v_rcp_f32_e32 v94, v80
	v_div_fmas_f32 v78, v78, v81, v79
	v_div_fixup_f32 v65, v78, v65, v97
	v_pk_fma_f32 v[2:3], v[132:133], v[50:51], v[2:3] op_sel_hi:[0,1,1]
	v_fma_f32 v78, -v80, v94, 1.0
	v_fmac_f32_e32 v94, v78, v94
	v_div_scale_f32 v78, vcc, v96, v64, v96
	v_mul_f32_e32 v79, v78, v94
	v_fma_f32 v81, -v80, v79, v78
	v_fmac_f32_e32 v79, v81, v94
	v_fma_f32 v78, -v80, v79, v78
	v_div_fmas_f32 v78, v78, v94, v79
	v_div_fixup_f32 v64, v78, v64, v96
	v_pk_mul_f32 v[18:19], v[18:19], v[64:65]
	v_cvt_pk_bf16_f32 v64, v16, v17
	v_and_b32_e32 v17, 0xffff0000, v64
	v_cvt_pk_bf16_f32 v65, v18, v19
	v_lshlrev_b32_e32 v16, 16, v64
	v_mul_f32_e32 v80, v17, v17
	s_waitcnt vmcnt(6)
	v_lshlrev_b32_e32 v81, 16, v158
	v_and_b32_e32 v94, 0xffff0000, v158
	v_lshlrev_b32_e32 v18, 16, v65
	v_fmac_f32_e32 v80, v16, v16
	v_mul_f32_e32 v78, 0xbfb8aa3b, v81
	v_mul_f32_e32 v79, 0xbfb8aa3b, v94
	v_and_b32_e32 v19, 0xffff0000, v65
	v_fmac_f32_e32 v80, v18, v18
	v_exp_f32_e32 v78, v78
	v_exp_f32_e32 v79, v79
	v_fmac_f32_e32 v80, v19, v19
	v_lshl_add_u64 v[18:19], v[118:119], 0, v[122:123]
	v_lshl_add_u64 v[16:17], v[18:19], 0, s[64:65]
	v_add_co_u32_e32 v18, vcc, s75, v18
	s_nop 1
	v_addc_co_u32_e32 v19, vcc, 0, v19, vcc
	global_store_dwordx2 v[18:19], v[64:65], off offset:1024
	v_pk_fma_f32 v[18:19], v[130:131], v[66:67], v[20:21] op_sel_hi:[0,1,1]
	v_pk_add_f32 v[20:21], v[78:79], 1.0 op_sel_hi:[1,0]
	v_pk_fma_f32 v[18:19], v[132:133], v[82:83], v[18:19] op_sel_hi:[0,1,1]
	v_div_scale_f32 v66, s[0:1], v21, v21, v94
	v_rcp_f32_e32 v67, v66
	v_lshlrev_b32_e32 v64, 16, v156
	v_and_b32_e32 v65, 0xffff0000, v156
	v_pk_fma_f32 v[18:19], v[128:129], v[64:65], v[18:19] op_sel_hi:[0,1,1]
	v_fma_f32 v64, -v66, v67, 1.0
	v_fmac_f32_e32 v67, v64, v67
	v_div_scale_f32 v64, vcc, v94, v21, v94
	v_mul_f32_e32 v65, v64, v67
	v_fma_f32 v78, -v66, v65, v64
	v_fmac_f32_e32 v65, v78, v67
	v_fma_f32 v64, -v66, v65, v64
	v_div_scale_f32 v66, s[0:1], v20, v20, v81
	v_rcp_f32_e32 v78, v66
	v_div_fmas_f32 v64, v64, v67, v65
	v_div_fixup_f32 v21, v64, v21, v94
	v_fma_f32 v64, -v66, v78, 1.0
	v_fmac_f32_e32 v78, v64, v78
	v_div_scale_f32 v64, vcc, v81, v20, v81
	v_mul_f32_e32 v65, v64, v78
	v_fma_f32 v67, -v66, v65, v64
	v_fmac_f32_e32 v65, v67, v78
	v_fma_f32 v64, -v66, v65, v64
	v_div_fmas_f32 v64, v64, v78, v65
	v_lshlrev_b32_e32 v66, 16, v159
	v_and_b32_e32 v67, 0xffff0000, v159
	v_div_fixup_f32 v20, v64, v20, v81
	v_mul_f32_e32 v64, 0xbfb8aa3b, v66
	v_mul_f32_e32 v65, 0xbfb8aa3b, v67
	v_exp_f32_e32 v64, v64
	v_exp_f32_e32 v65, v65
	v_pk_mul_f32 v[18:19], v[18:19], v[20:21]
	v_pk_fma_f32 v[20:21], v[130:131], v[68:69], v[22:23] op_sel_hi:[0,1,1]
	v_pk_fma_f32 v[20:21], v[132:133], v[84:85], v[20:21] op_sel_hi:[0,1,1]
	v_pk_add_f32 v[22:23], v[64:65], 1.0 op_sel_hi:[1,0]
	v_lshlrev_b32_e32 v64, 16, v157
	v_div_scale_f32 v68, s[0:1], v23, v23, v67
	v_rcp_f32_e32 v69, v68
	v_and_b32_e32 v65, 0xffff0000, v157
	v_pk_fma_f32 v[20:21], v[128:129], v[64:65], v[20:21] op_sel_hi:[0,1,1]
	v_cvt_pk_bf16_f32 v18, v18, v19
	v_fma_f32 v64, -v68, v69, 1.0
	v_fmac_f32_e32 v69, v64, v69
	v_div_scale_f32 v64, vcc, v67, v23, v67
	v_mul_f32_e32 v65, v64, v69
	v_fma_f32 v78, -v68, v65, v64
	v_fmac_f32_e32 v65, v78, v69
	v_fma_f32 v64, -v68, v65, v64
	v_div_scale_f32 v68, s[0:1], v22, v22, v66
	v_rcp_f32_e32 v78, v68
	v_div_fmas_f32 v64, v64, v69, v65
	v_div_fixup_f32 v23, v64, v23, v67
	v_fma_f32 v64, -v68, v78, 1.0
	v_fmac_f32_e32 v78, v64, v78
	v_div_scale_f32 v64, vcc, v66, v22, v66
	v_mul_f32_e32 v65, v64, v78
	v_fma_f32 v67, -v68, v65, v64
	v_fmac_f32_e32 v65, v67, v78
	v_fma_f32 v64, -v68, v65, v64
	v_div_fmas_f32 v64, v64, v78, v65
	v_div_fixup_f32 v22, v64, v22, v66
	v_pk_mul_f32 v[20:21], v[20:21], v[22:23]
	s_waitcnt vmcnt(6)
	v_lshlrev_b32_e32 v65, 16, v154
	v_cvt_pk_bf16_f32 v19, v20, v21
	v_and_b32_e32 v21, 0xffff0000, v18
	v_lshlrev_b32_e32 v20, 16, v18
	v_mul_f32_e32 v21, v21, v21
	v_lshlrev_b32_e32 v22, 16, v19
	v_fmac_f32_e32 v21, v20, v20
	v_and_b32_e32 v23, 0xffff0000, v19
	v_fmac_f32_e32 v21, v22, v22
	v_fmac_f32_e32 v21, v23, v23
	v_and_b32_e32 v66, 0xffff0000, v154
	v_add_f32_e32 v64, v80, v21
	v_mul_f32_e32 v20, 0xbfb8aa3b, v65
	v_mul_f32_e32 v21, 0xbfb8aa3b, v66
	v_exp_f32_e32 v20, v20
	v_exp_f32_e32 v21, v21
	global_store_dwordx2 v[16:17], v[18:19], off offset:16
	v_pk_fma_f32 v[18:19], v[130:131], v[70:71], v[24:25] op_sel_hi:[0,1,1]
	v_pk_fma_f32 v[18:19], v[132:133], v[86:87], v[18:19] op_sel_hi:[0,1,1]
	v_pk_add_f32 v[20:21], v[20:21], 1.0 op_sel_hi:[1,0]
	v_lshlrev_b32_e32 v22, 16, v152
	v_div_scale_f32 v24, s[0:1], v21, v21, v66
	v_rcp_f32_e32 v25, v24
	v_and_b32_e32 v23, 0xffff0000, v152
	v_pk_fma_f32 v[18:19], v[128:129], v[22:23], v[18:19] op_sel_hi:[0,1,1]
	v_fma_f32 v22, -v24, v25, 1.0
	v_fmac_f32_e32 v25, v22, v25
	v_div_scale_f32 v22, vcc, v66, v21, v66
	v_mul_f32_e32 v23, v22, v25
	v_fma_f32 v67, -v24, v23, v22
	v_fmac_f32_e32 v23, v67, v25
	v_fma_f32 v22, -v24, v23, v22
	v_div_scale_f32 v24, s[0:1], v20, v20, v65
	v_rcp_f32_e32 v67, v24
	v_div_fmas_f32 v22, v22, v25, v23
	v_div_fixup_f32 v21, v22, v21, v66
	v_and_b32_e32 v66, 0xffff0000, v155
	v_fma_f32 v22, -v24, v67, 1.0
	v_fmac_f32_e32 v67, v22, v67
	v_div_scale_f32 v22, vcc, v65, v20, v65
	v_mul_f32_e32 v23, v22, v67
	v_fma_f32 v25, -v24, v23, v22
	v_fmac_f32_e32 v23, v25, v67
	v_fma_f32 v22, -v24, v23, v22
	v_div_fmas_f32 v22, v22, v67, v23
	v_div_fixup_f32 v20, v22, v20, v65
	v_lshlrev_b32_e32 v65, 16, v155
	v_mul_f32_e32 v22, 0xbfb8aa3b, v65
	v_mul_f32_e32 v23, 0xbfb8aa3b, v66
	v_exp_f32_e32 v22, v22
	v_exp_f32_e32 v23, v23
	v_pk_mul_f32 v[18:19], v[18:19], v[20:21]
	v_pk_fma_f32 v[20:21], v[130:131], v[72:73], v[26:27] op_sel_hi:[0,1,1]
	v_pk_fma_f32 v[20:21], v[132:133], v[88:89], v[20:21] op_sel_hi:[0,1,1]
	v_pk_add_f32 v[22:23], v[22:23], 1.0 op_sel_hi:[1,0]
	v_lshlrev_b32_e32 v24, 16, v153
	v_div_scale_f32 v26, s[0:1], v23, v23, v66
	v_rcp_f32_e32 v27, v26
	v_and_b32_e32 v25, 0xffff0000, v153
	v_pk_fma_f32 v[20:21], v[128:129], v[24:25], v[20:21] op_sel_hi:[0,1,1]
	v_cvt_pk_bf16_f32 v18, v18, v19
	v_fma_f32 v24, -v26, v27, 1.0
	v_fmac_f32_e32 v27, v24, v27
	v_div_scale_f32 v24, vcc, v66, v23, v66
	v_mul_f32_e32 v25, v24, v27
	v_fma_f32 v67, -v26, v25, v24
	v_fmac_f32_e32 v25, v67, v27
	v_fma_f32 v24, -v26, v25, v24
	v_div_scale_f32 v26, s[0:1], v22, v22, v65
	v_rcp_f32_e32 v67, v26
	v_div_fmas_f32 v24, v24, v27, v25
	v_div_fixup_f32 v23, v24, v23, v66
	v_fma_f32 v24, -v26, v67, 1.0
	v_fmac_f32_e32 v67, v24, v67
	v_div_scale_f32 v24, vcc, v65, v22, v65
	v_mul_f32_e32 v25, v24, v67
	v_fma_f32 v27, -v26, v25, v24
	v_fmac_f32_e32 v25, v27, v67
	v_fma_f32 v24, -v26, v25, v24
	v_div_fmas_f32 v24, v24, v67, v25
	v_div_fixup_f32 v22, v24, v22, v65
	v_pk_mul_f32 v[20:21], v[20:21], v[22:23]
	s_waitcnt vmcnt(6)
	v_lshlrev_b32_e32 v24, 16, v150
	v_cvt_pk_bf16_f32 v19, v20, v21
	v_and_b32_e32 v21, 0xffff0000, v18
	v_lshlrev_b32_e32 v20, 16, v18
	v_mul_f32_e32 v21, v21, v21
	v_lshlrev_b32_e32 v22, 16, v19
	v_fmac_f32_e32 v21, v20, v20
	v_and_b32_e32 v23, 0xffff0000, v19
	v_fmac_f32_e32 v21, v22, v22
	v_fmac_f32_e32 v21, v23, v23
	v_and_b32_e32 v25, 0xffff0000, v150
	v_add_f32_e32 v26, v64, v21
	v_mul_f32_e32 v20, 0xbfb8aa3b, v24
	v_mul_f32_e32 v21, 0xbfb8aa3b, v25
	v_exp_f32_e32 v20, v20
	v_exp_f32_e32 v21, v21
	global_store_dwordx2 v[16:17], v[18:19], off offset:32
	v_pk_fma_f32 v[18:19], v[130:131], v[74:75], v[28:29] op_sel_hi:[0,1,1]
	v_pk_fma_f32 v[18:19], v[132:133], v[90:91], v[18:19] op_sel_hi:[0,1,1]
	v_pk_add_f32 v[20:21], v[20:21], 1.0 op_sel_hi:[1,0]
	v_lshlrev_b32_e32 v22, 16, v148
	v_div_scale_f32 v27, s[0:1], v21, v21, v25
	v_rcp_f32_e32 v28, v27
	v_and_b32_e32 v23, 0xffff0000, v148
	v_pk_fma_f32 v[18:19], v[128:129], v[22:23], v[18:19] op_sel_hi:[0,1,1]
	v_fma_f32 v22, -v27, v28, 1.0
	v_fmac_f32_e32 v28, v22, v28
	v_div_scale_f32 v22, vcc, v25, v21, v25
	v_mul_f32_e32 v23, v22, v28
	v_fma_f32 v29, -v27, v23, v22
	v_fmac_f32_e32 v23, v29, v28
	v_fma_f32 v22, -v27, v23, v22
	v_div_scale_f32 v27, s[0:1], v20, v20, v24
	v_rcp_f32_e32 v29, v27
	v_div_fmas_f32 v22, v22, v28, v23
	v_div_fixup_f32 v21, v22, v21, v25
	v_and_b32_e32 v28, 0xffff0000, v151
	v_fma_f32 v22, -v27, v29, 1.0
	v_fmac_f32_e32 v29, v22, v29
	v_div_scale_f32 v22, vcc, v24, v20, v24
	v_mul_f32_e32 v23, v22, v29
	v_fma_f32 v25, -v27, v23, v22
	v_fmac_f32_e32 v23, v25, v29
	v_fma_f32 v22, -v27, v23, v22
	v_div_fmas_f32 v22, v22, v29, v23
	v_lshlrev_b32_e32 v27, 16, v151
	v_div_fixup_f32 v20, v22, v20, v24
	v_mul_f32_e32 v22, 0xbfb8aa3b, v27
	v_mul_f32_e32 v23, 0xbfb8aa3b, v28
	v_exp_f32_e32 v22, v22
	v_exp_f32_e32 v23, v23
	v_pk_mul_f32 v[18:19], v[18:19], v[20:21]
	v_pk_fma_f32 v[20:21], v[130:131], v[76:77], v[30:31] op_sel_hi:[0,1,1]
	v_pk_fma_f32 v[20:21], v[132:133], v[92:93], v[20:21] op_sel_hi:[0,1,1]
	v_pk_add_f32 v[22:23], v[22:23], 1.0 op_sel_hi:[1,0]
	v_lshlrev_b32_e32 v24, 16, v149
	v_div_scale_f32 v29, s[0:1], v23, v23, v28
	v_rcp_f32_e32 v30, v29
	v_and_b32_e32 v25, 0xffff0000, v149
	v_pk_fma_f32 v[20:21], v[128:129], v[24:25], v[20:21] op_sel_hi:[0,1,1]
	v_cvt_pk_bf16_f32 v18, v18, v19
	v_fma_f32 v24, -v29, v30, 1.0
	v_fmac_f32_e32 v30, v24, v30
	v_div_scale_f32 v24, vcc, v28, v23, v28
	v_mul_f32_e32 v25, v24, v30
	v_fma_f32 v31, -v29, v25, v24
	v_fmac_f32_e32 v25, v31, v30
	v_fma_f32 v24, -v29, v25, v24
	v_div_scale_f32 v29, s[0:1], v22, v22, v27
	v_rcp_f32_e32 v31, v29
	v_div_fmas_f32 v24, v24, v30, v25
	v_div_fixup_f32 v23, v24, v23, v28
	v_fma_f32 v24, -v29, v31, 1.0
	v_fmac_f32_e32 v31, v24, v31
	v_div_scale_f32 v24, vcc, v27, v22, v27
	v_mul_f32_e32 v25, v24, v31
	v_fma_f32 v28, -v29, v25, v24
	v_fmac_f32_e32 v25, v28, v31
	v_fma_f32 v24, -v29, v25, v24
	v_div_fmas_f32 v24, v24, v31, v25
	v_div_fixup_f32 v22, v24, v22, v27
	v_pk_mul_f32 v[20:21], v[20:21], v[22:23]
	s_waitcnt vmcnt(6)
	v_and_b32_e32 v24, 0xffff0000, v146
	v_cvt_pk_bf16_f32 v19, v20, v21
	v_and_b32_e32 v21, 0xffff0000, v18
	v_lshlrev_b32_e32 v20, 16, v18
	v_mul_f32_e32 v21, v21, v21
	v_lshlrev_b32_e32 v22, 16, v19
	v_fmac_f32_e32 v21, v20, v20
	v_and_b32_e32 v23, 0xffff0000, v19
	v_fmac_f32_e32 v21, v22, v22
	v_fmac_f32_e32 v21, v23, v23
	v_lshlrev_b32_e32 v23, 16, v146
	v_add_f32_e32 v22, v26, v21
	v_mul_f32_e32 v20, 0xbfb8aa3b, v23
	v_mul_f32_e32 v21, 0xbfb8aa3b, v24
	v_exp_f32_e32 v20, v20
	v_exp_f32_e32 v21, v21
	global_store_dwordx2 v[16:17], v[18:19], off offset:48
	v_pk_add_f32 v[18:19], v[20:21], 1.0 op_sel_hi:[1,0]
	s_nop 0
	v_div_scale_f32 v25, s[0:1], v19, v19, v24
	v_rcp_f32_e32 v26, v25
	v_lshlrev_b32_e32 v20, 16, v144
	v_and_b32_e32 v21, 0xffff0000, v144
	v_pk_fma_f32 v[0:1], v[128:129], v[20:21], v[0:1] op_sel_hi:[0,1,1]
	v_fma_f32 v20, -v25, v26, 1.0
	v_fmac_f32_e32 v26, v20, v26
	v_div_scale_f32 v20, vcc, v24, v19, v24
	v_mul_f32_e32 v21, v20, v26
	v_fma_f32 v27, -v25, v21, v20
	v_fmac_f32_e32 v21, v27, v26
	v_fma_f32 v20, -v25, v21, v20
	v_div_scale_f32 v25, s[0:1], v18, v18, v23
	v_rcp_f32_e32 v27, v25
	v_div_fmas_f32 v20, v20, v26, v21
	v_div_fixup_f32 v19, v20, v19, v24
	v_fma_f32 v20, -v25, v27, 1.0
	v_fmac_f32_e32 v27, v20, v27
	v_div_scale_f32 v20, vcc, v23, v18, v23
	v_mul_f32_e32 v21, v20, v27
	v_fma_f32 v24, -v25, v21, v20
	v_fmac_f32_e32 v21, v24, v27
	v_fma_f32 v20, -v25, v21, v20
	v_div_fmas_f32 v20, v20, v27, v21
	v_div_fixup_f32 v18, v20, v18, v23
	v_lshlrev_b32_e32 v23, 16, v147
	v_and_b32_e32 v24, 0xffff0000, v147
	v_mul_f32_e32 v20, 0xbfb8aa3b, v23
	v_mul_f32_e32 v21, 0xbfb8aa3b, v24
	v_exp_f32_e32 v20, v20
	v_exp_f32_e32 v21, v21
	v_pk_mul_f32 v[0:1], v[0:1], v[18:19]
	v_pk_add_f32 v[18:19], v[20:21], 1.0 op_sel_hi:[1,0]
	s_nop 0
	v_div_scale_f32 v25, s[0:1], v19, v19, v24
	v_rcp_f32_e32 v26, v25
	v_lshlrev_b32_e32 v20, 16, v145
	v_and_b32_e32 v21, 0xffff0000, v145
	v_pk_fma_f32 v[2:3], v[128:129], v[20:21], v[2:3] op_sel_hi:[0,1,1]
	v_fma_f32 v20, -v25, v26, 1.0
	v_fmac_f32_e32 v26, v20, v26
	v_div_scale_f32 v20, vcc, v24, v19, v24
	v_mul_f32_e32 v21, v20, v26
	v_fma_f32 v27, -v25, v21, v20
	v_fmac_f32_e32 v21, v27, v26
	v_fma_f32 v20, -v25, v21, v20
	v_div_scale_f32 v25, s[0:1], v18, v18, v23
	v_rcp_f32_e32 v27, v25
	v_div_fmas_f32 v20, v20, v26, v21
	v_div_fixup_f32 v19, v20, v19, v24
	v_cvt_pk_bf16_f32 v0, v0, v1
	v_fma_f32 v20, -v25, v27, 1.0
	v_fmac_f32_e32 v27, v20, v27
	v_div_scale_f32 v20, vcc, v23, v18, v23
	v_mul_f32_e32 v21, v20, v27
	v_fma_f32 v24, -v25, v21, v20
	v_fmac_f32_e32 v21, v24, v27
	v_fma_f32 v20, -v25, v21, v20
	v_div_fmas_f32 v20, v20, v27, v21
	v_div_fixup_f32 v18, v20, v18, v23
	v_pk_mul_f32 v[2:3], v[2:3], v[18:19]
	s_waitcnt vmcnt(6)
	v_and_b32_e32 v20, 0xffff0000, v142
	v_cvt_pk_bf16_f32 v1, v2, v3
	v_and_b32_e32 v3, 0xffff0000, v0
	v_lshlrev_b32_e32 v2, 16, v0
	v_mul_f32_e32 v3, v3, v3
	v_lshlrev_b32_e32 v18, 16, v1
	v_fmac_f32_e32 v3, v2, v2
	v_and_b32_e32 v19, 0xffff0000, v1
	v_fmac_f32_e32 v3, v18, v18
	v_fmac_f32_e32 v3, v19, v19
	v_lshlrev_b32_e32 v19, 16, v142
	v_add_f32_e32 v18, v22, v3
	v_mul_f32_e32 v2, 0xbfb8aa3b, v19
	v_mul_f32_e32 v3, 0xbfb8aa3b, v20
	v_exp_f32_e32 v2, v2
	v_exp_f32_e32 v3, v3
	global_store_dwordx2 v[16:17], v[0:1], off offset:64
	v_pk_fma_f32 v[0:1], v[130:131], v[36:37], v[4:5] op_sel_hi:[0,1,1]
	v_pk_fma_f32 v[0:1], v[132:133], v[52:53], v[0:1] op_sel_hi:[0,1,1]
	v_pk_add_f32 v[2:3], v[2:3], 1.0 op_sel_hi:[1,0]
	v_lshlrev_b32_e32 v4, 16, v140
	v_div_scale_f32 v21, s[0:1], v3, v3, v20
	v_rcp_f32_e32 v22, v21
	v_and_b32_e32 v5, 0xffff0000, v140
	v_pk_fma_f32 v[0:1], v[128:129], v[4:5], v[0:1] op_sel_hi:[0,1,1]
	v_fma_f32 v4, -v21, v22, 1.0
	v_fmac_f32_e32 v22, v4, v22
	v_div_scale_f32 v4, vcc, v20, v3, v20
	v_mul_f32_e32 v5, v4, v22
	v_fma_f32 v23, -v21, v5, v4
	v_fmac_f32_e32 v5, v23, v22
	v_fma_f32 v4, -v21, v5, v4
	v_div_scale_f32 v21, s[0:1], v2, v2, v19
	v_rcp_f32_e32 v23, v21
	v_div_fmas_f32 v4, v4, v22, v5
	v_div_fixup_f32 v3, v4, v3, v20
	v_fma_f32 v4, -v21, v23, 1.0
	v_fmac_f32_e32 v23, v4, v23
	v_div_scale_f32 v4, vcc, v19, v2, v19
	v_mul_f32_e32 v5, v4, v23
	v_fma_f32 v20, -v21, v5, v4
	v_fmac_f32_e32 v5, v20, v23
	v_fma_f32 v4, -v21, v5, v4
	v_div_fmas_f32 v4, v4, v23, v5
	v_div_fixup_f32 v2, v4, v2, v19
	v_lshlrev_b32_e32 v19, 16, v143
	v_and_b32_e32 v20, 0xffff0000, v143
	v_mul_f32_e32 v4, 0xbfb8aa3b, v19
	v_mul_f32_e32 v5, 0xbfb8aa3b, v20
	v_exp_f32_e32 v4, v4
	v_exp_f32_e32 v5, v5
	v_pk_mul_f32 v[0:1], v[0:1], v[2:3]
	v_pk_fma_f32 v[2:3], v[130:131], v[38:39], v[6:7] op_sel_hi:[0,1,1]
	v_pk_fma_f32 v[2:3], v[132:133], v[54:55], v[2:3] op_sel_hi:[0,1,1]
	v_pk_add_f32 v[4:5], v[4:5], 1.0 op_sel_hi:[1,0]
	v_lshlrev_b32_e32 v6, 16, v141
	v_div_scale_f32 v21, s[0:1], v5, v5, v20
	v_rcp_f32_e32 v22, v21
	v_and_b32_e32 v7, 0xffff0000, v141
	v_pk_fma_f32 v[2:3], v[128:129], v[6:7], v[2:3] op_sel_hi:[0,1,1]
	v_cvt_pk_bf16_f32 v0, v0, v1
	v_fma_f32 v6, -v21, v22, 1.0
	v_fmac_f32_e32 v22, v6, v22
	v_div_scale_f32 v6, vcc, v20, v5, v20
	v_mul_f32_e32 v7, v6, v22
	v_fma_f32 v23, -v21, v7, v6
	v_fmac_f32_e32 v7, v23, v22
	v_fma_f32 v6, -v21, v7, v6
	v_div_scale_f32 v21, s[0:1], v4, v4, v19
	v_rcp_f32_e32 v23, v21
	v_div_fmas_f32 v6, v6, v22, v7
	v_div_fixup_f32 v5, v6, v5, v20
	v_fma_f32 v6, -v21, v23, 1.0
	v_fmac_f32_e32 v23, v6, v23
	v_div_scale_f32 v6, vcc, v19, v4, v19
	v_mul_f32_e32 v7, v6, v23
	v_fma_f32 v20, -v21, v7, v6
	v_fmac_f32_e32 v7, v20, v23
	v_fma_f32 v6, -v21, v7, v6
	v_div_fmas_f32 v6, v6, v23, v7
	v_div_fixup_f32 v4, v6, v4, v19
	v_pk_mul_f32 v[2:3], v[2:3], v[4:5]
	s_waitcnt vmcnt(6)
	v_lshlrev_b32_e32 v19, 16, v138
	v_cvt_pk_bf16_f32 v1, v2, v3
	v_and_b32_e32 v3, 0xffff0000, v0
	v_lshlrev_b32_e32 v2, 16, v0
	v_mul_f32_e32 v6, v3, v3
	v_and_b32_e32 v20, 0xffff0000, v138
	v_fmac_f32_e32 v6, v2, v2
	v_mul_f32_e32 v2, 0xbfb8aa3b, v19
	v_mul_f32_e32 v3, 0xbfb8aa3b, v20
	v_exp_f32_e32 v2, v2
	v_exp_f32_e32 v3, v3
	v_lshlrev_b32_e32 v4, 16, v1
	v_and_b32_e32 v5, 0xffff0000, v1
	v_fmac_f32_e32 v6, v4, v4
	v_pk_add_f32 v[2:3], v[2:3], 1.0 op_sel_hi:[1,0]
	v_fmac_f32_e32 v6, v5, v5
	v_pk_fma_f32 v[4:5], v[130:131], v[40:41], v[8:9] op_sel_hi:[0,1,1]
	v_div_scale_f32 v8, s[0:1], v3, v3, v20
	v_rcp_f32_e32 v9, v8
	v_add_f32_e32 v18, v18, v6
	v_pk_fma_f32 v[4:5], v[132:133], v[56:57], v[4:5] op_sel_hi:[0,1,1]
	v_lshlrev_b32_e32 v6, 16, v136
	v_and_b32_e32 v7, 0xffff0000, v136
	v_pk_fma_f32 v[4:5], v[128:129], v[6:7], v[4:5] op_sel_hi:[0,1,1]
	v_fma_f32 v6, -v8, v9, 1.0
	v_fmac_f32_e32 v9, v6, v9
	v_div_scale_f32 v6, vcc, v20, v3, v20
	v_mul_f32_e32 v7, v6, v9
	v_fma_f32 v21, -v8, v7, v6
	v_fmac_f32_e32 v7, v21, v9
	v_fma_f32 v6, -v8, v7, v6
	v_div_scale_f32 v8, s[0:1], v2, v2, v19
	v_rcp_f32_e32 v21, v8
	v_div_fmas_f32 v6, v6, v9, v7
	v_div_fixup_f32 v3, v6, v3, v20
	v_and_b32_e32 v20, 0xffff0000, v139
	v_fma_f32 v6, -v8, v21, 1.0
	v_fmac_f32_e32 v21, v6, v21
	v_div_scale_f32 v6, vcc, v19, v2, v19
	v_mul_f32_e32 v7, v6, v21
	v_fma_f32 v9, -v8, v7, v6
	v_fmac_f32_e32 v7, v9, v21
	v_fma_f32 v6, -v8, v7, v6
	v_div_fmas_f32 v6, v6, v21, v7
	v_div_fixup_f32 v2, v6, v2, v19
	v_lshlrev_b32_e32 v19, 16, v139
	v_mul_f32_e32 v6, 0xbfb8aa3b, v19
	v_mul_f32_e32 v7, 0xbfb8aa3b, v20
	v_exp_f32_e32 v6, v6
	v_exp_f32_e32 v7, v7
	v_pk_mul_f32 v[2:3], v[4:5], v[2:3]
	v_pk_fma_f32 v[4:5], v[130:131], v[42:43], v[10:11] op_sel_hi:[0,1,1]
	v_pk_fma_f32 v[4:5], v[132:133], v[58:59], v[4:5] op_sel_hi:[0,1,1]
	v_pk_add_f32 v[6:7], v[6:7], 1.0 op_sel_hi:[1,0]
	v_lshlrev_b32_e32 v8, 16, v137
	v_div_scale_f32 v10, s[0:1], v7, v7, v20
	v_rcp_f32_e32 v11, v10
	v_and_b32_e32 v9, 0xffff0000, v137
	v_pk_fma_f32 v[4:5], v[128:129], v[8:9], v[4:5] op_sel_hi:[0,1,1]
	v_cvt_pk_bf16_f32 v2, v2, v3
	v_fma_f32 v8, -v10, v11, 1.0
	v_fmac_f32_e32 v11, v8, v11
	v_div_scale_f32 v8, vcc, v20, v7, v20
	v_mul_f32_e32 v9, v8, v11
	v_fma_f32 v21, -v10, v9, v8
	v_fmac_f32_e32 v9, v21, v11
	v_fma_f32 v8, -v10, v9, v8
	v_div_scale_f32 v10, s[0:1], v6, v6, v19
	v_rcp_f32_e32 v21, v10
	v_div_fmas_f32 v8, v8, v11, v9
	v_div_fixup_f32 v7, v8, v7, v20
	v_fma_f32 v8, -v10, v21, 1.0
	v_fmac_f32_e32 v21, v8, v21
	v_div_scale_f32 v8, vcc, v19, v6, v19
	v_mul_f32_e32 v9, v8, v21
	v_fma_f32 v11, -v10, v9, v8
	v_fmac_f32_e32 v9, v11, v21
	v_fma_f32 v8, -v10, v9, v8
	v_div_fmas_f32 v8, v8, v21, v9
	v_div_fixup_f32 v6, v8, v6, v19
	v_pk_mul_f32 v[4:5], v[4:5], v[6:7]
	s_waitcnt vmcnt(5)
	v_lshlrev_b32_e32 v10, 16, v134
	v_cvt_pk_bf16_f32 v3, v4, v5
	v_and_b32_e32 v5, 0xffff0000, v2
	v_lshlrev_b32_e32 v4, 16, v2
	v_mul_f32_e32 v8, v5, v5
	v_and_b32_e32 v11, 0xffff0000, v134
	v_fmac_f32_e32 v8, v4, v4
	v_mul_f32_e32 v4, 0xbfb8aa3b, v10
	v_mul_f32_e32 v5, 0xbfb8aa3b, v11
	v_exp_f32_e32 v4, v4
	v_exp_f32_e32 v5, v5
	v_lshlrev_b32_e32 v6, 16, v3
	v_and_b32_e32 v7, 0xffff0000, v3
	v_fmac_f32_e32 v8, v6, v6
	v_pk_add_f32 v[4:5], v[4:5], 1.0 op_sel_hi:[1,0]
	v_fmac_f32_e32 v8, v7, v7
	v_pk_fma_f32 v[6:7], v[130:131], v[44:45], v[12:13] op_sel_hi:[0,1,1]
	v_div_scale_f32 v12, s[0:1], v5, v5, v11
	v_rcp_f32_e32 v13, v12
	v_add_f32_e32 v18, v18, v8
	v_pk_fma_f32 v[6:7], v[132:133], v[60:61], v[6:7] op_sel_hi:[0,1,1]
	v_lshlrev_b32_e32 v8, 16, v126
	v_and_b32_e32 v9, 0xffff0000, v126
	v_pk_fma_f32 v[6:7], v[128:129], v[8:9], v[6:7] op_sel_hi:[0,1,1]
	v_fma_f32 v8, -v12, v13, 1.0
	v_fmac_f32_e32 v13, v8, v13
	v_div_scale_f32 v8, vcc, v11, v5, v11
	v_mul_f32_e32 v9, v8, v13
	v_fma_f32 v19, -v12, v9, v8
	v_fmac_f32_e32 v9, v19, v13
	v_fma_f32 v8, -v12, v9, v8
	v_div_scale_f32 v12, s[0:1], v4, v4, v10
	v_rcp_f32_e32 v19, v12
	v_div_fmas_f32 v8, v8, v13, v9
	v_div_fixup_f32 v5, v8, v5, v11
	v_and_b32_e32 v13, 0xffff0000, v135
	v_fma_f32 v8, -v12, v19, 1.0
	v_fmac_f32_e32 v19, v8, v19
	v_div_scale_f32 v8, vcc, v10, v4, v10
	v_mul_f32_e32 v9, v8, v19
	v_fma_f32 v11, -v12, v9, v8
	v_fmac_f32_e32 v9, v11, v19
	v_fma_f32 v8, -v12, v9, v8
	v_div_fmas_f32 v8, v8, v19, v9
	v_lshlrev_b32_e32 v12, 16, v135
	v_div_fixup_f32 v4, v8, v4, v10
	v_mul_f32_e32 v8, 0xbfb8aa3b, v12
	v_mul_f32_e32 v9, 0xbfb8aa3b, v13
	v_exp_f32_e32 v8, v8
	v_exp_f32_e32 v9, v9
	v_pk_mul_f32 v[4:5], v[6:7], v[4:5]
	v_pk_fma_f32 v[6:7], v[130:131], v[46:47], v[14:15] op_sel_hi:[0,1,1]
	v_pk_fma_f32 v[6:7], v[132:133], v[62:63], v[6:7] op_sel_hi:[0,1,1]
	v_pk_add_f32 v[8:9], v[8:9], 1.0 op_sel_hi:[1,0]
	v_lshlrev_b32_e32 v10, 16, v127
	v_div_scale_f32 v14, s[0:1], v9, v9, v13
	v_rcp_f32_e32 v15, v14
	v_and_b32_e32 v11, 0xffff0000, v127
	v_pk_fma_f32 v[6:7], v[128:129], v[10:11], v[6:7] op_sel_hi:[0,1,1]
	v_fma_f32 v10, -v14, v15, 1.0
	v_fmac_f32_e32 v15, v10, v15
	v_div_scale_f32 v10, vcc, v13, v9, v13
	v_mul_f32_e32 v11, v10, v15
	v_fma_f32 v19, -v14, v11, v10
	v_fmac_f32_e32 v11, v19, v15
	v_fma_f32 v10, -v14, v11, v10
	v_div_scale_f32 v14, s[0:1], v8, v8, v12
	v_rcp_f32_e32 v19, v14
	v_div_fmas_f32 v10, v10, v15, v11
	v_div_fixup_f32 v9, v10, v9, v13
	v_fma_f32 v10, -v14, v19, 1.0
	v_fmac_f32_e32 v19, v10, v19
	v_div_scale_f32 v10, vcc, v12, v8, v12
	v_mul_f32_e32 v11, v10, v19
	v_fma_f32 v13, -v14, v11, v10
	v_fmac_f32_e32 v11, v13, v19
	v_fma_f32 v10, -v14, v11, v10
	v_div_fmas_f32 v10, v10, v19, v11
	v_div_fixup_f32 v8, v10, v8, v12
	v_pk_mul_f32 v[6:7], v[6:7], v[8:9]
	v_cvt_pk_bf16_f32 v8, v4, v5
	v_and_b32_e32 v5, 0xffff0000, v8
	v_cvt_pk_bf16_f32 v9, v6, v7
	v_lshlrev_b32_e32 v4, 16, v8
	v_mul_f32_e32 v5, v5, v5
	v_lshlrev_b32_e32 v6, 16, v9
	v_fmac_f32_e32 v5, v4, v4
	v_and_b32_e32 v7, 0xffff0000, v9
	v_fmac_f32_e32 v5, v6, v6
	v_fmac_f32_e32 v5, v7, v7
	v_cmp_lt_i32_e32 vcc, v131, v167
	v_add_f32_e32 v4, v18, v5
	global_store_dwordx2 v[16:17], v[0:1], off offset:80
	global_store_dwordx2 v[16:17], v[2:3], off offset:96
	global_store_dwordx2 v[16:17], v[8:9], off offset:112
	v_cndmask_b32_e32 v5, v165, v131, vcc
	v_lshlrev_b32_e32 v5, 2, v5
	ds_bpermute_b32 v5, v5, v4
	v_cmp_eq_u32_e32 vcc, 0, v168
	s_and_saveexec_b64 s[66:67], vcc
	s_cbranch_execz .LBB0_720
	v_lshlrev_b64 v[0:1], 5, v[124:125]
	v_lshl_add_u64 v[0:1], s[58:59], 0, v[0:1]
	s_mov_b32 s5, s61
	v_lshl_add_u64 v[0:1], v[0:1], 0, s[4:5]
	s_waitcnt lgkmcnt(0)
	v_add_f32_e32 v2, v4, v5
	global_store_dword v[0:1], v2, off
	s_branch .LBB0_720

.LBB0_2197:
	s_or_b64 exec, exec, s[30:31]
	v_lshlrev_b32_e32 v59, 3, v111
	v_mov_b32_e32 v2, s1
	v_mov_b32_e32 v3, s0
	v_cndmask_b32_e32 v1, v5, v4, vcc
	v_cndmask_b32_e32 v2, v2, v3, vcc
	v_lshl_add_u32 v64, v59, 1, s23
	v_lshl_add_u32 v1, v1, 2, v2
	v_mad_u32_u24 v8, v56, s39, v64
	ds_write_b32 v1, v0
	s_waitcnt lgkmcnt(0)
	s_barrier
	ds_read_b128 v[0:3], v8 offset:17408
	ds_read_b128 v[4:7], v8 offset:17440
	s_waitcnt lgkmcnt(1)
	v_mfma_f32_32x32x16_bf16 v[24:39], v[0:3], v[48:51], 0
	v_lshlrev_b32_e32 v58, 2, v111
	v_cmp_ge_u32_e32 vcc, v58, v57
	s_waitcnt lgkmcnt(0)
	v_mfma_f32_32x32x16_bf16 v[24:39], v[4:7], v[102:105], v[24:39]
	ds_read_b128 v[0:3], v8 offset:17472
	ds_read_b128 v[4:7], v8 offset:17504
	s_waitcnt lgkmcnt(1)
	v_mfma_f32_32x32x16_bf16 v[24:39], v[0:3], v[98:101], v[24:39]
	v_lshl_add_u32 v0, v57, 2, s23
	ds_read2st64_b32 v[54:55], v0 offset0:140 offset1:142
	s_waitcnt lgkmcnt(1)
	v_mfma_f32_32x32x16_bf16 v[24:39], v[4:7], v[94:97], v[24:39]
	v_lshl_add_u32 v236, v58, 2, s23
	v_sub_u32_e32 v237, v57, v58
	ds_read_b128 v[170:173], v236 offset:35840
	ds_read_b128 v[174:177], v236 offset:36352
	ds_read_b128 v[178:181], v236 offset:36864
	ds_read_b128 v[182:185], v236 offset:37376
	ds_read_b128 v[186:189], v236 offset:35872
	ds_read_b128 v[190:193], v236 offset:36384
	ds_read_b128 v[194:197], v236 offset:36896
	ds_read_b128 v[198:201], v236 offset:37408
	ds_read_b128 v[202:205], v236 offset:35904
	ds_read_b128 v[206:209], v236 offset:36416
	ds_read_b128 v[210:213], v236 offset:36928
	ds_read_b128 v[214:217], v236 offset:37440
	s_waitcnt lgkmcnt(8)
	ds_read_b128 v[218:221], v236 offset:35936
	ds_read_b128 v[222:225], v236 offset:36448
	ds_read_b128 v[226:229], v236 offset:36960
	ds_read_b128 v[230:233], v236 offset:37472
	v_mov_b32_e32 v238, v237
	v_cmp_lt_i32_e32 vcc, 0, v238
	v_cmp_lt_i32_e64 s[4:5], 1, v238
	v_cmp_lt_i32_e64 s[6:7], 2, v238
	v_cmp_lt_i32_e64 s[30:31], 3, v238
	v_sub_f32_e32 v170, v54, v170
	v_sub_f32_e32 v171, v54, v171
	v_sub_f32_e32 v172, v54, v172
	v_sub_f32_e32 v173, v54, v173
	v_sub_f32_e32 v174, v55, v174
	v_sub_f32_e32 v175, v55, v175
	v_sub_f32_e32 v176, v55, v176
	v_sub_f32_e32 v177, v55, v177
	v_cndmask_b32_e64 v170, v174, v170, vcc
	v_cndmask_b32_e64 v171, v175, v171, s[4:5]
	v_cndmask_b32_e64 v172, v176, v172, s[6:7]
	v_cndmask_b32_e64 v173, v177, v173, s[30:31]
	v_add_f32_e32 v174, v178, v182
	v_add_f32_e32 v175, v179, v183
	v_add_f32_e32 v176, v180, v184
	v_add_f32_e32 v177, v181, v185
	v_cndmask_b32_e64 v178, v182, v178, vcc
	v_cndmask_b32_e64 v179, v183, v179, s[4:5]
	v_cndmask_b32_e64 v180, v184, v180, s[6:7]
	v_cndmask_b32_e64 v181, v185, v181, s[30:31]
	v_cmp_eq_u32_e32 vcc, 0, v238
	v_cmp_eq_u32_e64 s[4:5], 1, v238
	v_cmp_eq_u32_e64 s[6:7], 2, v238
	v_cmp_eq_u32_e64 s[30:31], 3, v238
	v_mul_f32_e32 v170, 0x3fb8aa3b, v170
	v_mul_f32_e32 v171, 0x3fb8aa3b, v171
	v_mul_f32_e32 v172, 0x3fb8aa3b, v172
	v_mul_f32_e32 v173, 0x3fb8aa3b, v173
	v_exp_f32_e32 v170, v170
	v_exp_f32_e32 v171, v171
	v_exp_f32_e32 v172, v172
	v_exp_f32_e32 v173, v173
	v_mul_f32_e32 v178, v178, v170
	v_mul_f32_e32 v179, v179, v171
	v_mul_f32_e32 v180, v180, v172
	v_mul_f32_e32 v181, v181, v173
	v_cndmask_b32_e64 v0, v178, v174, vcc
	v_cndmask_b32_e64 v1, v179, v175, s[4:5]
	v_cndmask_b32_e64 v2, v180, v176, s[6:7]
	v_cndmask_b32_e64 v3, v181, v177, s[30:31]
	s_waitcnt lgkmcnt(8)
	v_add_u32_e32 v238, -8, v237
	v_cmp_lt_i32_e32 vcc, 0, v238
	v_cmp_lt_i32_e64 s[4:5], 1, v238
	v_cmp_lt_i32_e64 s[6:7], 2, v238
	v_cmp_lt_i32_e64 s[30:31], 3, v238
	v_sub_f32_e32 v186, v54, v186
	v_sub_f32_e32 v187, v54, v187
	v_sub_f32_e32 v188, v54, v188
	v_sub_f32_e32 v189, v54, v189
	v_sub_f32_e32 v190, v55, v190
	v_sub_f32_e32 v191, v55, v191
	v_sub_f32_e32 v192, v55, v192
	v_sub_f32_e32 v193, v55, v193
	v_cndmask_b32_e64 v186, v190, v186, vcc
	v_cndmask_b32_e64 v187, v191, v187, s[4:5]
	v_cndmask_b32_e64 v188, v192, v188, s[6:7]
	v_cndmask_b32_e64 v189, v193, v189, s[30:31]
	v_add_f32_e32 v190, v194, v198
	v_add_f32_e32 v191, v195, v199
	v_add_f32_e32 v192, v196, v200
	v_add_f32_e32 v193, v197, v201
	v_cndmask_b32_e64 v194, v198, v194, vcc
	v_cndmask_b32_e64 v195, v199, v195, s[4:5]
	v_cndmask_b32_e64 v196, v200, v196, s[6:7]
	v_cndmask_b32_e64 v197, v201, v197, s[30:31]
	v_cmp_eq_u32_e32 vcc, 0, v238
	v_cmp_eq_u32_e64 s[4:5], 1, v238
	v_cmp_eq_u32_e64 s[6:7], 2, v238
	v_cmp_eq_u32_e64 s[30:31], 3, v238
	v_mul_f32_e32 v186, 0x3fb8aa3b, v186
	v_mul_f32_e32 v187, 0x3fb8aa3b, v187
	v_mul_f32_e32 v188, 0x3fb8aa3b, v188
	v_mul_f32_e32 v189, 0x3fb8aa3b, v189
	v_exp_f32_e32 v186, v186
	v_exp_f32_e32 v187, v187
	v_exp_f32_e32 v188, v188
	v_exp_f32_e32 v189, v189
	v_mul_f32_e32 v194, v194, v186
	v_mul_f32_e32 v195, v195, v187
	v_mul_f32_e32 v196, v196, v188
	v_mul_f32_e32 v197, v197, v189
	v_cndmask_b32_e64 v4, v194, v190, vcc
	v_cndmask_b32_e64 v5, v195, v191, s[4:5]
	v_cndmask_b32_e64 v6, v196, v192, s[6:7]
	v_cndmask_b32_e64 v7, v197, v193, s[30:31]
	s_waitcnt lgkmcnt(4)
	v_add_u32_e32 v238, -16, v237
	v_cmp_lt_i32_e32 vcc, 0, v238
	v_cmp_lt_i32_e64 s[4:5], 1, v238
	v_cmp_lt_i32_e64 s[6:7], 2, v238
	v_cmp_lt_i32_e64 s[30:31], 3, v238
	v_sub_f32_e32 v202, v54, v202
	v_sub_f32_e32 v203, v54, v203
	v_sub_f32_e32 v204, v54, v204
	v_sub_f32_e32 v205, v54, v205
	v_sub_f32_e32 v206, v55, v206
	v_sub_f32_e32 v207, v55, v207
	v_sub_f32_e32 v208, v55, v208
	v_sub_f32_e32 v209, v55, v209
	v_cndmask_b32_e64 v202, v206, v202, vcc
	v_cndmask_b32_e64 v203, v207, v203, s[4:5]
	v_cndmask_b32_e64 v204, v208, v204, s[6:7]
	v_cndmask_b32_e64 v205, v209, v205, s[30:31]
	v_add_f32_e32 v206, v210, v214
	v_add_f32_e32 v207, v211, v215
	v_add_f32_e32 v208, v212, v216
	v_add_f32_e32 v209, v213, v217
	v_cndmask_b32_e64 v210, v214, v210, vcc
	v_cndmask_b32_e64 v211, v215, v211, s[4:5]
	v_cndmask_b32_e64 v212, v216, v212, s[6:7]
	v_cndmask_b32_e64 v213, v217, v213, s[30:31]
	v_cmp_eq_u32_e32 vcc, 0, v238
	v_cmp_eq_u32_e64 s[4:5], 1, v238
	v_cmp_eq_u32_e64 s[6:7], 2, v238
	v_cmp_eq_u32_e64 s[30:31], 3, v238
	v_mul_f32_e32 v202, 0x3fb8aa3b, v202
	v_mul_f32_e32 v203, 0x3fb8aa3b, v203
	v_mul_f32_e32 v204, 0x3fb8aa3b, v204
	v_mul_f32_e32 v205, 0x3fb8aa3b, v205
	v_exp_f32_e32 v202, v202
	v_exp_f32_e32 v203, v203
	v_exp_f32_e32 v204, v204
	v_exp_f32_e32 v205, v205
	v_mul_f32_e32 v210, v210, v202
	v_mul_f32_e32 v211, v211, v203
	v_mul_f32_e32 v212, v212, v204
	v_mul_f32_e32 v213, v213, v205
	v_cndmask_b32_e64 v40, v210, v206, vcc
	v_cndmask_b32_e64 v41, v211, v207, s[4:5]
	v_cndmask_b32_e64 v8, v212, v208, s[6:7]
	v_cndmask_b32_e64 v9, v213, v209, s[30:31]
	s_waitcnt lgkmcnt(0)
	v_add_u32_e32 v238, 0xffffffe8, v237
	v_cmp_lt_i32_e32 vcc, 0, v238
	v_cmp_lt_i32_e64 s[4:5], 1, v238
	v_cmp_lt_i32_e64 s[6:7], 2, v238
	v_cmp_lt_i32_e64 s[30:31], 3, v238
	v_sub_f32_e32 v218, v54, v218
	v_sub_f32_e32 v219, v54, v219
	v_sub_f32_e32 v220, v54, v220
	v_sub_f32_e32 v221, v54, v221
	v_sub_f32_e32 v222, v55, v222
	v_sub_f32_e32 v223, v55, v223
	v_sub_f32_e32 v224, v55, v224
	v_sub_f32_e32 v225, v55, v225
	v_cndmask_b32_e64 v218, v222, v218, vcc
	v_cndmask_b32_e64 v219, v223, v219, s[4:5]
	v_cndmask_b32_e64 v220, v224, v220, s[6:7]
	v_cndmask_b32_e64 v221, v225, v221, s[30:31]
	v_add_f32_e32 v222, v226, v230
	v_add_f32_e32 v223, v227, v231
	v_add_f32_e32 v224, v228, v232
	v_add_f32_e32 v225, v229, v233
	v_cndmask_b32_e64 v226, v230, v226, vcc
	v_cndmask_b32_e64 v227, v231, v227, s[4:5]
	v_cndmask_b32_e64 v228, v232, v228, s[6:7]
	v_cndmask_b32_e64 v229, v233, v229, s[30:31]
	v_cmp_eq_u32_e32 vcc, 0, v238
	v_cmp_eq_u32_e64 s[4:5], 1, v238
	v_cmp_eq_u32_e64 s[6:7], 2, v238
	v_cmp_eq_u32_e64 s[30:31], 3, v238
	v_mul_f32_e32 v218, 0x3fb8aa3b, v218
	v_mul_f32_e32 v219, 0x3fb8aa3b, v219
	v_mul_f32_e32 v220, 0x3fb8aa3b, v220
	v_mul_f32_e32 v221, 0x3fb8aa3b, v221
	v_exp_f32_e32 v218, v218
	v_exp_f32_e32 v219, v219
	v_exp_f32_e32 v220, v220
	v_exp_f32_e32 v221, v221
	v_mul_f32_e32 v226, v226, v218
	v_mul_f32_e32 v227, v227, v219
	v_mul_f32_e32 v228, v228, v220
	v_mul_f32_e32 v229, v229, v221
	v_cndmask_b32_e64 v10, v226, v222, vcc
	v_cndmask_b32_e64 v11, v227, v223, s[4:5]
	v_cndmask_b32_e64 v12, v228, v224, s[6:7]
	v_cndmask_b32_e64 v42, v229, v225, s[30:31]
	v_mul_f32_e32 v16, v28, v4
	v_mul_u32_u24_e32 v4, 0x88, v56
	v_lshl_add_u32 v63, v58, 1, s23
	v_lshl_add_u32 v61, v4, 1, v63
	v_mul_f32_e32 v13, v31, v7
	v_mul_f32_e32 v14, v30, v6
	v_mul_f32_e32 v15, v29, v5
	ds_read2_b64 v[4:7], v61 offset1:2
	v_mul_f32_e32 v3, v27, v3
	v_mul_f32_e32 v2, v26, v2
	v_mul_f32_e32 v1, v25, v1
	v_mul_f32_e32 v0, v24, v0
	v_cvt_pk_bf16_f32 v0, v0, v1
	v_cvt_pk_bf16_f32 v1, v2, v3
	v_cvt_pk_bf16_f32 v2, v16, v15
	v_cvt_pk_bf16_f32 v3, v14, v13
	v_add_u32_e32 v62, 0x2000, v61
	v_mul_f32_e32 v44, v37, v11
	v_mul_f32_e32 v45, v36, v10
	v_mul_f32_e32 v46, v35, v9
	v_mul_f32_e32 v47, v34, v8
	ds_read2_b64 v[34:37], v61 offset0:4 offset1:6
	s_waitcnt lgkmcnt(1)
	v_mfma_f32_32x32x16_bf16 v[16:31], v[4:7], v[0:3], 0
	ds_read2_b64 v[4:7], v62 offset0:64 offset1:66
	v_mul_f32_e32 v43, v38, v12
	v_mul_f32_e32 v33, v33, v41
	v_mul_f32_e32 v32, v32, v40
	v_mul_f32_e32 v41, v39, v42
	v_cvt_pk_bf16_f32 v38, v32, v33
	v_cvt_pk_bf16_f32 v39, v47, v46
	v_cvt_pk_bf16_f32 v40, v45, v44
	v_cvt_pk_bf16_f32 v41, v43, v41
	s_waitcnt lgkmcnt(0)
	v_mfma_f32_32x32x16_bf16 v[0:15], v[4:7], v[0:3], 0
	v_mfma_f32_32x32x16_bf16 v[16:31], v[34:37], v[38:41], v[16:31]
	ds_read2_b64 v[32:35], v62 offset0:68 offset1:70
	v_or_b32_e32 v36, 32, v56
	v_mad_u32_u24 v65, v36, s39, v64
	s_waitcnt lgkmcnt(0)
	v_mfma_f32_32x32x16_bf16 v[0:15], v[32:35], v[38:41], v[0:15]
	ds_read_b128 v[32:35], v65 offset:17408
	ds_read_b128 v[66:69], v65 offset:17440
	s_waitcnt lgkmcnt(1)
	v_mfma_f32_32x32x16_bf16 v[32:47], v[32:35], v[48:51], 0
	s_waitcnt lgkmcnt(0)
	v_mfma_f32_32x32x16_bf16 v[32:47], v[66:69], v[102:105], v[32:47]
	ds_read_b128 v[66:69], v65 offset:17472
	ds_read_b128 v[70:73], v65 offset:17504
	s_waitcnt lgkmcnt(1)
	v_mfma_f32_32x32x16_bf16 v[32:47], v[66:69], v[98:101], v[32:47]
	v_or_b32_e32 v66, 32, v58
	v_cmp_ge_u32_e32 vcc, v66, v57
	s_waitcnt lgkmcnt(0)
	v_mfma_f32_32x32x16_bf16 v[32:47], v[70:73], v[94:97], v[32:47]
	v_lshl_add_u32 v236, v58, 2, s23
	v_sub_u32_e32 v237, v57, v58
	ds_read_b128 v[170:173], v236 offset:35968
	ds_read_b128 v[174:177], v236 offset:36480
	ds_read_b128 v[178:181], v236 offset:36992
	ds_read_b128 v[182:185], v236 offset:37504
	ds_read_b128 v[186:189], v236 offset:36000
	ds_read_b128 v[190:193], v236 offset:36512
	ds_read_b128 v[194:197], v236 offset:37024
	ds_read_b128 v[198:201], v236 offset:37536
	ds_read_b128 v[202:205], v236 offset:36032
	ds_read_b128 v[206:209], v236 offset:36544
	ds_read_b128 v[210:213], v236 offset:37056
	ds_read_b128 v[214:217], v236 offset:37568
	s_waitcnt lgkmcnt(8)
	ds_read_b128 v[218:221], v236 offset:36064
	ds_read_b128 v[222:225], v236 offset:36576
	ds_read_b128 v[226:229], v236 offset:37088
	ds_read_b128 v[230:233], v236 offset:37600
	v_add_u32_e32 v238, 0xffffffe0, v237
	v_cmp_lt_i32_e32 vcc, 0, v238
	v_cmp_lt_i32_e64 s[4:5], 1, v238
	v_cmp_lt_i32_e64 s[6:7], 2, v238
	v_cmp_lt_i32_e64 s[30:31], 3, v238
	v_sub_f32_e32 v170, v54, v170
	v_sub_f32_e32 v171, v54, v171
	v_sub_f32_e32 v172, v54, v172
	v_sub_f32_e32 v173, v54, v173
	v_sub_f32_e32 v174, v55, v174
	v_sub_f32_e32 v175, v55, v175
	v_sub_f32_e32 v176, v55, v176
	v_sub_f32_e32 v177, v55, v177
	v_cndmask_b32_e64 v170, v174, v170, vcc
	v_cndmask_b32_e64 v171, v175, v171, s[4:5]
	v_cndmask_b32_e64 v172, v176, v172, s[6:7]
	v_cndmask_b32_e64 v173, v177, v173, s[30:31]
	v_add_f32_e32 v174, v178, v182
	v_add_f32_e32 v175, v179, v183
	v_add_f32_e32 v176, v180, v184
	v_add_f32_e32 v177, v181, v185
	v_cndmask_b32_e64 v178, v182, v178, vcc
	v_cndmask_b32_e64 v179, v183, v179, s[4:5]
	v_cndmask_b32_e64 v180, v184, v180, s[6:7]
	v_cndmask_b32_e64 v181, v185, v181, s[30:31]
	v_cmp_eq_u32_e32 vcc, 0, v238
	v_cmp_eq_u32_e64 s[4:5], 1, v238
	v_cmp_eq_u32_e64 s[6:7], 2, v238
	v_cmp_eq_u32_e64 s[30:31], 3, v238
	v_mul_f32_e32 v170, 0x3fb8aa3b, v170
	v_mul_f32_e32 v171, 0x3fb8aa3b, v171
	v_mul_f32_e32 v172, 0x3fb8aa3b, v172
	v_mul_f32_e32 v173, 0x3fb8aa3b, v173
	v_exp_f32_e32 v170, v170
	v_exp_f32_e32 v171, v171
	v_exp_f32_e32 v172, v172
	v_exp_f32_e32 v173, v173
	v_mul_f32_e32 v178, v178, v170
	v_mul_f32_e32 v179, v179, v171
	v_mul_f32_e32 v180, v180, v172
	v_mul_f32_e32 v181, v181, v173
	v_cndmask_b32_e64 v65, v178, v174, vcc
	v_cndmask_b32_e64 v66, v179, v175, s[4:5]
	v_cndmask_b32_e64 v67, v180, v176, s[6:7]
	v_cndmask_b32_e64 v68, v181, v177, s[30:31]
	s_waitcnt lgkmcnt(8)
	v_add_u32_e32 v238, 0xffffffd8, v237
	v_cmp_lt_i32_e32 vcc, 0, v238
	v_cmp_lt_i32_e64 s[4:5], 1, v238
	v_cmp_lt_i32_e64 s[6:7], 2, v238
	v_cmp_lt_i32_e64 s[30:31], 3, v238
	v_sub_f32_e32 v186, v54, v186
	v_sub_f32_e32 v187, v54, v187
	v_sub_f32_e32 v188, v54, v188
	v_sub_f32_e32 v189, v54, v189
	v_sub_f32_e32 v190, v55, v190
	v_sub_f32_e32 v191, v55, v191
	v_sub_f32_e32 v192, v55, v192
	v_sub_f32_e32 v193, v55, v193
	v_cndmask_b32_e64 v186, v190, v186, vcc
	v_cndmask_b32_e64 v187, v191, v187, s[4:5]
	v_cndmask_b32_e64 v188, v192, v188, s[6:7]
	v_cndmask_b32_e64 v189, v193, v189, s[30:31]
	v_add_f32_e32 v190, v194, v198
	v_add_f32_e32 v191, v195, v199
	v_add_f32_e32 v192, v196, v200
	v_add_f32_e32 v193, v197, v201
	v_cndmask_b32_e64 v194, v198, v194, vcc
	v_cndmask_b32_e64 v195, v199, v195, s[4:5]
	v_cndmask_b32_e64 v196, v200, v196, s[6:7]
	v_cndmask_b32_e64 v197, v201, v197, s[30:31]
	v_cmp_eq_u32_e32 vcc, 0, v238
	v_cmp_eq_u32_e64 s[4:5], 1, v238
	v_cmp_eq_u32_e64 s[6:7], 2, v238
	v_cmp_eq_u32_e64 s[30:31], 3, v238
	v_mul_f32_e32 v186, 0x3fb8aa3b, v186
	v_mul_f32_e32 v187, 0x3fb8aa3b, v187
	v_mul_f32_e32 v188, 0x3fb8aa3b, v188
	v_mul_f32_e32 v189, 0x3fb8aa3b, v189
	v_exp_f32_e32 v186, v186
	v_exp_f32_e32 v187, v187
	v_exp_f32_e32 v188, v188
	v_exp_f32_e32 v189, v189
	v_mul_f32_e32 v194, v194, v186
	v_mul_f32_e32 v195, v195, v187
	v_mul_f32_e32 v196, v196, v188
	v_mul_f32_e32 v197, v197, v189
	v_cndmask_b32_e64 v69, v194, v190, vcc
	v_cndmask_b32_e64 v70, v195, v191, s[4:5]
	v_cndmask_b32_e64 v71, v196, v192, s[6:7]
	v_cndmask_b32_e64 v72, v197, v193, s[30:31]
	s_waitcnt lgkmcnt(4)
	v_add_u32_e32 v238, 0xffffffd0, v237
	v_cmp_lt_i32_e32 vcc, 0, v238
	v_cmp_lt_i32_e64 s[4:5], 1, v238
	v_cmp_lt_i32_e64 s[6:7], 2, v238
	v_cmp_lt_i32_e64 s[30:31], 3, v238
	v_sub_f32_e32 v202, v54, v202
	v_sub_f32_e32 v203, v54, v203
	v_sub_f32_e32 v204, v54, v204
	v_sub_f32_e32 v205, v54, v205
	v_sub_f32_e32 v206, v55, v206
	v_sub_f32_e32 v207, v55, v207
	v_sub_f32_e32 v208, v55, v208
	v_sub_f32_e32 v209, v55, v209
	v_cndmask_b32_e64 v202, v206, v202, vcc
	v_cndmask_b32_e64 v203, v207, v203, s[4:5]
	v_cndmask_b32_e64 v204, v208, v204, s[6:7]
	v_cndmask_b32_e64 v205, v209, v205, s[30:31]
	v_add_f32_e32 v206, v210, v214
	v_add_f32_e32 v207, v211, v215
	v_add_f32_e32 v208, v212, v216
	v_add_f32_e32 v209, v213, v217
	v_cndmask_b32_e64 v210, v214, v210, vcc
	v_cndmask_b32_e64 v211, v215, v211, s[4:5]
	v_cndmask_b32_e64 v212, v216, v212, s[6:7]
	v_cndmask_b32_e64 v213, v217, v213, s[30:31]
	v_cmp_eq_u32_e32 vcc, 0, v238
	v_cmp_eq_u32_e64 s[4:5], 1, v238
	v_cmp_eq_u32_e64 s[6:7], 2, v238
	v_cmp_eq_u32_e64 s[30:31], 3, v238
	v_mul_f32_e32 v202, 0x3fb8aa3b, v202
	v_mul_f32_e32 v203, 0x3fb8aa3b, v203
	v_mul_f32_e32 v204, 0x3fb8aa3b, v204
	v_mul_f32_e32 v205, 0x3fb8aa3b, v205
	v_exp_f32_e32 v202, v202
	v_exp_f32_e32 v203, v203
	v_exp_f32_e32 v204, v204
	v_exp_f32_e32 v205, v205
	v_mul_f32_e32 v210, v210, v202
	v_mul_f32_e32 v211, v211, v203
	v_mul_f32_e32 v212, v212, v204
	v_mul_f32_e32 v213, v213, v205
	v_cndmask_b32_e64 v73, v210, v206, vcc
	v_cndmask_b32_e64 v74, v211, v207, s[4:5]
	v_cndmask_b32_e64 v75, v212, v208, s[6:7]
	v_cndmask_b32_e64 v76, v213, v209, s[30:31]
	s_waitcnt lgkmcnt(0)
	v_add_u32_e32 v238, 0xffffffc8, v237
	v_cmp_lt_i32_e32 vcc, 0, v238
	v_cmp_lt_i32_e64 s[4:5], 1, v238
	v_cmp_lt_i32_e64 s[6:7], 2, v238
	v_cmp_lt_i32_e64 s[30:31], 3, v238
	v_sub_f32_e32 v218, v54, v218
	v_sub_f32_e32 v219, v54, v219
	v_sub_f32_e32 v220, v54, v220
	v_sub_f32_e32 v221, v54, v221
	v_sub_f32_e32 v222, v55, v222
	v_sub_f32_e32 v223, v55, v223
	v_sub_f32_e32 v224, v55, v224
	v_sub_f32_e32 v225, v55, v225
	v_cndmask_b32_e64 v218, v222, v218, vcc
	v_cndmask_b32_e64 v219, v223, v219, s[4:5]
	v_cndmask_b32_e64 v220, v224, v220, s[6:7]
	v_cndmask_b32_e64 v221, v225, v221, s[30:31]
	v_add_f32_e32 v222, v226, v230
	v_add_f32_e32 v223, v227, v231
	v_add_f32_e32 v224, v228, v232
	v_add_f32_e32 v225, v229, v233
	v_cndmask_b32_e64 v226, v230, v226, vcc
	v_cndmask_b32_e64 v227, v231, v227, s[4:5]
	v_cndmask_b32_e64 v228, v232, v228, s[6:7]
	v_cndmask_b32_e64 v229, v233, v229, s[30:31]
	v_cmp_eq_u32_e32 vcc, 0, v238
	v_cmp_eq_u32_e64 s[4:5], 1, v238
	v_cmp_eq_u32_e64 s[6:7], 2, v238
	v_cmp_eq_u32_e64 s[30:31], 3, v238
	v_mul_f32_e32 v218, 0x3fb8aa3b, v218
	v_mul_f32_e32 v219, 0x3fb8aa3b, v219
	v_mul_f32_e32 v220, 0x3fb8aa3b, v220
	v_mul_f32_e32 v221, 0x3fb8aa3b, v221
	v_exp_f32_e32 v218, v218
	v_exp_f32_e32 v219, v219
	v_exp_f32_e32 v220, v220
	v_exp_f32_e32 v221, v221
	v_mul_f32_e32 v226, v226, v218
	v_mul_f32_e32 v227, v227, v219
	v_mul_f32_e32 v228, v228, v220
	v_mul_f32_e32 v229, v229, v221
	v_cndmask_b32_e64 v77, v226, v222, vcc
	v_cndmask_b32_e64 v78, v227, v223, s[4:5]
	v_cndmask_b32_e64 v79, v228, v224, s[6:7]
	v_cndmask_b32_e64 v80, v229, v225, s[30:31]
	v_mul_f32_e32 v72, v39, v72
	v_mul_f32_e32 v71, v38, v71
	v_mul_f32_e32 v70, v37, v70
	v_mul_f32_e32 v69, v36, v69
	ds_read2_b64 v[36:39], v61 offset0:8 offset1:10
	v_mul_f32_e32 v35, v35, v68
	v_mul_f32_e32 v34, v34, v67
	v_mul_f32_e32 v33, v33, v66
	v_mul_f32_e32 v32, v32, v65
	v_cvt_pk_bf16_f32 v32, v32, v33
	v_cvt_pk_bf16_f32 v33, v34, v35
	v_cvt_pk_bf16_f32 v34, v69, v70
	v_cvt_pk_bf16_f32 v35, v71, v72
	v_mul_f32_e32 v65, v45, v78
	v_mul_f32_e32 v66, v44, v77
	s_waitcnt lgkmcnt(0)
	v_mfma_f32_32x32x16_bf16 v[16:31], v[36:39], v[32:35], v[16:31]
	ds_read2_b64 v[36:39], v62 offset0:72 offset1:74
	v_mul_f32_e32 v67, v43, v76
	v_mul_f32_e32 v68, v42, v75
	ds_read2_b64 v[42:45], v61 offset0:12 offset1:14
	v_mul_f32_e32 v46, v46, v79
	s_waitcnt lgkmcnt(1)
	v_mfma_f32_32x32x16_bf16 v[0:15], v[36:39], v[32:35], v[0:15]
	ds_read2_b64 v[36:39], v62 offset0:76 offset1:78
	v_mul_f32_e32 v32, v41, v74
	v_mul_f32_e32 v33, v40, v73
	v_mul_f32_e32 v35, v47, v80
	v_mul_u32_u24_e32 v40, 0x90, v56
	v_cvt_pk_bf16_f32 v32, v33, v32
	v_cvt_pk_bf16_f32 v33, v68, v67
	v_cvt_pk_bf16_f32 v34, v66, v65
	v_cvt_pk_bf16_f32 v35, v46, v35
	v_add_u32_e32 v64, v64, v40
	s_waitcnt lgkmcnt(1)
	v_mfma_f32_32x32x16_bf16 v[16:31], v[42:45], v[32:35], v[16:31]
	s_waitcnt lgkmcnt(0)
	v_mfma_f32_32x32x16_bf16 v[0:15], v[36:39], v[32:35], v[0:15]
	ds_read_b128 v[32:35], v64 offset:26624
	ds_read_b128 v[66:69], v64 offset:26656
	s_waitcnt lgkmcnt(1)
	v_mfma_f32_32x32x16_bf16 v[32:47], v[32:35], v[48:51], 0
	s_waitcnt lgkmcnt(0)
	v_mfma_f32_32x32x16_bf16 v[32:47], v[66:69], v[102:105], v[32:47]
	ds_read_b128 v[66:69], v64 offset:26688
	ds_read_b128 v[70:73], v64 offset:26720
	s_waitcnt lgkmcnt(1)
	v_mfma_f32_32x32x16_bf16 v[32:47], v[66:69], v[98:101], v[32:47]
	v_or_b32_e32 v66, 64, v58
	v_cmp_ge_u32_e32 vcc, v66, v57
	s_waitcnt lgkmcnt(0)
	v_mfma_f32_32x32x16_bf16 v[32:47], v[70:73], v[94:97], v[32:47]
	v_lshl_add_u32 v236, v58, 2, s23
	v_sub_u32_e32 v237, v57, v58
	ds_read_b128 v[170:173], v236 offset:36096
	ds_read_b128 v[174:177], v236 offset:36608
	ds_read_b128 v[178:181], v236 offset:37120
	ds_read_b128 v[182:185], v236 offset:37632
	ds_read_b128 v[186:189], v236 offset:36128
	ds_read_b128 v[190:193], v236 offset:36640
	ds_read_b128 v[194:197], v236 offset:37152
	ds_read_b128 v[198:201], v236 offset:37664
	ds_read_b128 v[202:205], v236 offset:36160
	ds_read_b128 v[206:209], v236 offset:36672
	ds_read_b128 v[210:213], v236 offset:37184
	ds_read_b128 v[214:217], v236 offset:37696
	s_waitcnt lgkmcnt(8)
	ds_read_b128 v[218:221], v236 offset:36192
	ds_read_b128 v[222:225], v236 offset:36704
	ds_read_b128 v[226:229], v236 offset:37216
	ds_read_b128 v[230:233], v236 offset:37728
	v_add_u32_e32 v238, 0xffffffc0, v237
	v_cmp_lt_i32_e32 vcc, 0, v238
	v_cmp_lt_i32_e64 s[4:5], 1, v238
	v_cmp_lt_i32_e64 s[6:7], 2, v238
	v_cmp_lt_i32_e64 s[30:31], 3, v238
	v_sub_f32_e32 v170, v54, v170
	v_sub_f32_e32 v171, v54, v171
	v_sub_f32_e32 v172, v54, v172
	v_sub_f32_e32 v173, v54, v173
	v_sub_f32_e32 v174, v55, v174
	v_sub_f32_e32 v175, v55, v175
	v_sub_f32_e32 v176, v55, v176
	v_sub_f32_e32 v177, v55, v177
	v_cndmask_b32_e64 v170, v174, v170, vcc
	v_cndmask_b32_e64 v171, v175, v171, s[4:5]
	v_cndmask_b32_e64 v172, v176, v172, s[6:7]
	v_cndmask_b32_e64 v173, v177, v173, s[30:31]
	v_add_f32_e32 v174, v178, v182
	v_add_f32_e32 v175, v179, v183
	v_add_f32_e32 v176, v180, v184
	v_add_f32_e32 v177, v181, v185
	v_cndmask_b32_e64 v178, v182, v178, vcc
	v_cndmask_b32_e64 v179, v183, v179, s[4:5]
	v_cndmask_b32_e64 v180, v184, v180, s[6:7]
	v_cndmask_b32_e64 v181, v185, v181, s[30:31]
	v_cmp_eq_u32_e32 vcc, 0, v238
	v_cmp_eq_u32_e64 s[4:5], 1, v238
	v_cmp_eq_u32_e64 s[6:7], 2, v238
	v_cmp_eq_u32_e64 s[30:31], 3, v238
	v_mul_f32_e32 v170, 0x3fb8aa3b, v170
	v_mul_f32_e32 v171, 0x3fb8aa3b, v171
	v_mul_f32_e32 v172, 0x3fb8aa3b, v172
	v_mul_f32_e32 v173, 0x3fb8aa3b, v173
	v_exp_f32_e32 v170, v170
	v_exp_f32_e32 v171, v171
	v_exp_f32_e32 v172, v172
	v_exp_f32_e32 v173, v173
	v_mul_f32_e32 v178, v178, v170
	v_mul_f32_e32 v179, v179, v171
	v_mul_f32_e32 v180, v180, v172
	v_mul_f32_e32 v181, v181, v173
	v_cndmask_b32_e64 v65, v178, v174, vcc
	v_cndmask_b32_e64 v66, v179, v175, s[4:5]
	v_cndmask_b32_e64 v67, v180, v176, s[6:7]
	v_cndmask_b32_e64 v68, v181, v177, s[30:31]
	s_waitcnt lgkmcnt(8)
	v_add_u32_e32 v238, 0xffffffb8, v237
	v_cmp_lt_i32_e32 vcc, 0, v238
	v_cmp_lt_i32_e64 s[4:5], 1, v238
	v_cmp_lt_i32_e64 s[6:7], 2, v238
	v_cmp_lt_i32_e64 s[30:31], 3, v238
	v_sub_f32_e32 v186, v54, v186
	v_sub_f32_e32 v187, v54, v187
	v_sub_f32_e32 v188, v54, v188
	v_sub_f32_e32 v189, v54, v189
	v_sub_f32_e32 v190, v55, v190
	v_sub_f32_e32 v191, v55, v191
	v_sub_f32_e32 v192, v55, v192
	v_sub_f32_e32 v193, v55, v193
	v_cndmask_b32_e64 v186, v190, v186, vcc
	v_cndmask_b32_e64 v187, v191, v187, s[4:5]
	v_cndmask_b32_e64 v188, v192, v188, s[6:7]
	v_cndmask_b32_e64 v189, v193, v189, s[30:31]
	v_add_f32_e32 v190, v194, v198
	v_add_f32_e32 v191, v195, v199
	v_add_f32_e32 v192, v196, v200
	v_add_f32_e32 v193, v197, v201
	v_cndmask_b32_e64 v194, v198, v194, vcc
	v_cndmask_b32_e64 v195, v199, v195, s[4:5]
	v_cndmask_b32_e64 v196, v200, v196, s[6:7]
	v_cndmask_b32_e64 v197, v201, v197, s[30:31]
	v_cmp_eq_u32_e32 vcc, 0, v238
	v_cmp_eq_u32_e64 s[4:5], 1, v238
	v_cmp_eq_u32_e64 s[6:7], 2, v238
	v_cmp_eq_u32_e64 s[30:31], 3, v238
	v_mul_f32_e32 v186, 0x3fb8aa3b, v186
	v_mul_f32_e32 v187, 0x3fb8aa3b, v187
	v_mul_f32_e32 v188, 0x3fb8aa3b, v188
	v_mul_f32_e32 v189, 0x3fb8aa3b, v189
	v_exp_f32_e32 v186, v186
	v_exp_f32_e32 v187, v187
	v_exp_f32_e32 v188, v188
	v_exp_f32_e32 v189, v189
	v_mul_f32_e32 v194, v194, v186
	v_mul_f32_e32 v195, v195, v187
	v_mul_f32_e32 v196, v196, v188
	v_mul_f32_e32 v197, v197, v189
	v_cndmask_b32_e64 v69, v194, v190, vcc
	v_cndmask_b32_e64 v70, v195, v191, s[4:5]
	v_cndmask_b32_e64 v71, v196, v192, s[6:7]
	v_cndmask_b32_e64 v72, v197, v193, s[30:31]
	s_waitcnt lgkmcnt(4)
	v_add_u32_e32 v238, 0xffffffb0, v237
	v_cmp_lt_i32_e32 vcc, 0, v238
	v_cmp_lt_i32_e64 s[4:5], 1, v238
	v_cmp_lt_i32_e64 s[6:7], 2, v238
	v_cmp_lt_i32_e64 s[30:31], 3, v238
	v_sub_f32_e32 v202, v54, v202
	v_sub_f32_e32 v203, v54, v203
	v_sub_f32_e32 v204, v54, v204
	v_sub_f32_e32 v205, v54, v205
	v_sub_f32_e32 v206, v55, v206
	v_sub_f32_e32 v207, v55, v207
	v_sub_f32_e32 v208, v55, v208
	v_sub_f32_e32 v209, v55, v209
	v_cndmask_b32_e64 v202, v206, v202, vcc
	v_cndmask_b32_e64 v203, v207, v203, s[4:5]
	v_cndmask_b32_e64 v204, v208, v204, s[6:7]
	v_cndmask_b32_e64 v205, v209, v205, s[30:31]
	v_add_f32_e32 v206, v210, v214
	v_add_f32_e32 v207, v211, v215
	v_add_f32_e32 v208, v212, v216
	v_add_f32_e32 v209, v213, v217
	v_cndmask_b32_e64 v210, v214, v210, vcc
	v_cndmask_b32_e64 v211, v215, v211, s[4:5]
	v_cndmask_b32_e64 v212, v216, v212, s[6:7]
	v_cndmask_b32_e64 v213, v217, v213, s[30:31]
	v_cmp_eq_u32_e32 vcc, 0, v238
	v_cmp_eq_u32_e64 s[4:5], 1, v238
	v_cmp_eq_u32_e64 s[6:7], 2, v238
	v_cmp_eq_u32_e64 s[30:31], 3, v238
	v_mul_f32_e32 v202, 0x3fb8aa3b, v202
	v_mul_f32_e32 v203, 0x3fb8aa3b, v203
	v_mul_f32_e32 v204, 0x3fb8aa3b, v204
	v_mul_f32_e32 v205, 0x3fb8aa3b, v205
	v_exp_f32_e32 v202, v202
	v_exp_f32_e32 v203, v203
	v_exp_f32_e32 v204, v204
	v_exp_f32_e32 v205, v205
	v_mul_f32_e32 v210, v210, v202
	v_mul_f32_e32 v211, v211, v203
	v_mul_f32_e32 v212, v212, v204
	v_mul_f32_e32 v213, v213, v205
	v_cndmask_b32_e64 v73, v210, v206, vcc
	v_cndmask_b32_e64 v74, v211, v207, s[4:5]
	v_cndmask_b32_e64 v75, v212, v208, s[6:7]
	v_cndmask_b32_e64 v76, v213, v209, s[30:31]
	s_waitcnt lgkmcnt(0)
	v_add_u32_e32 v238, 0xffffffa8, v237
	v_cmp_lt_i32_e32 vcc, 0, v238
	v_cmp_lt_i32_e64 s[4:5], 1, v238
	v_cmp_lt_i32_e64 s[6:7], 2, v238
	v_cmp_lt_i32_e64 s[30:31], 3, v238
	v_sub_f32_e32 v218, v54, v218
	v_sub_f32_e32 v219, v54, v219
	v_sub_f32_e32 v220, v54, v220
	v_sub_f32_e32 v221, v54, v221
	v_sub_f32_e32 v222, v55, v222
	v_sub_f32_e32 v223, v55, v223
	v_sub_f32_e32 v224, v55, v224
	v_sub_f32_e32 v225, v55, v225
	v_cndmask_b32_e64 v218, v222, v218, vcc
	v_cndmask_b32_e64 v219, v223, v219, s[4:5]
	v_cndmask_b32_e64 v220, v224, v220, s[6:7]
	v_cndmask_b32_e64 v221, v225, v221, s[30:31]
	v_add_f32_e32 v222, v226, v230
	v_add_f32_e32 v223, v227, v231
	v_add_f32_e32 v224, v228, v232
	v_add_f32_e32 v225, v229, v233
	v_cndmask_b32_e64 v226, v230, v226, vcc
	v_cndmask_b32_e64 v227, v231, v227, s[4:5]
	v_cndmask_b32_e64 v228, v232, v228, s[6:7]
	v_cndmask_b32_e64 v229, v233, v229, s[30:31]
	v_cmp_eq_u32_e32 vcc, 0, v238
	v_cmp_eq_u32_e64 s[4:5], 1, v238
	v_cmp_eq_u32_e64 s[6:7], 2, v238
	v_cmp_eq_u32_e64 s[30:31], 3, v238
	v_mul_f32_e32 v218, 0x3fb8aa3b, v218
	v_mul_f32_e32 v219, 0x3fb8aa3b, v219
	v_mul_f32_e32 v220, 0x3fb8aa3b, v220
	v_mul_f32_e32 v221, 0x3fb8aa3b, v221
	v_exp_f32_e32 v218, v218
	v_exp_f32_e32 v219, v219
	v_exp_f32_e32 v220, v220
	v_exp_f32_e32 v221, v221
	v_mul_f32_e32 v226, v226, v218
	v_mul_f32_e32 v227, v227, v219
	v_mul_f32_e32 v228, v228, v220
	v_mul_f32_e32 v229, v229, v221
	v_cndmask_b32_e64 v77, v226, v222, vcc
	v_cndmask_b32_e64 v78, v227, v223, s[4:5]
	v_cndmask_b32_e64 v79, v228, v224, s[6:7]
	v_cndmask_b32_e64 v80, v229, v225, s[30:31]
	v_mul_f32_e32 v72, v39, v72
	v_mul_f32_e32 v71, v38, v71
	v_mul_f32_e32 v70, v37, v70
	v_mul_f32_e32 v69, v36, v69
	ds_read2_b64 v[36:39], v61 offset0:16 offset1:18
	v_mul_f32_e32 v35, v35, v68
	v_mul_f32_e32 v34, v34, v67
	v_mul_f32_e32 v33, v33, v66
	v_mul_f32_e32 v32, v32, v65
	v_cvt_pk_bf16_f32 v32, v32, v33
	v_cvt_pk_bf16_f32 v33, v34, v35
	v_cvt_pk_bf16_f32 v34, v69, v70
	v_cvt_pk_bf16_f32 v35, v71, v72
	v_mul_f32_e32 v65, v45, v78
	v_mul_f32_e32 v66, v44, v77
	s_waitcnt lgkmcnt(0)
	v_mfma_f32_32x32x16_bf16 v[16:31], v[36:39], v[32:35], v[16:31]
	ds_read2_b64 v[36:39], v62 offset0:80 offset1:82
	v_mul_f32_e32 v67, v43, v76
	v_mul_f32_e32 v68, v42, v75
	ds_read2_b64 v[42:45], v61 offset0:20 offset1:22
	v_mul_f32_e32 v46, v46, v79
	s_waitcnt lgkmcnt(1)
	v_mfma_f32_32x32x16_bf16 v[0:15], v[36:39], v[32:35], v[0:15]
	ds_read2_b64 v[36:39], v62 offset0:84 offset1:86
	v_mul_f32_e32 v32, v41, v74
	v_mul_f32_e32 v33, v40, v73
	v_mul_f32_e32 v35, v47, v80
	v_cvt_pk_bf16_f32 v32, v33, v32
	v_cvt_pk_bf16_f32 v33, v68, v67
	v_cvt_pk_bf16_f32 v34, v66, v65
	v_cvt_pk_bf16_f32 v35, v46, v35
	v_or_b32_e32 v65, 0x60, v58
	v_cmp_ge_u32_e32 vcc, v65, v57
	s_waitcnt lgkmcnt(1)
	v_mfma_f32_32x32x16_bf16 v[16:31], v[42:45], v[32:35], v[16:31]
	s_waitcnt lgkmcnt(0)
	v_mfma_f32_32x32x16_bf16 v[0:15], v[36:39], v[32:35], v[0:15]
	ds_read_b128 v[32:35], v64 offset:31232
	ds_read_b128 v[66:69], v64 offset:31264
	s_waitcnt lgkmcnt(1)
	v_mfma_f32_32x32x16_bf16 v[32:47], v[32:35], v[48:51], 0
	s_waitcnt lgkmcnt(0)
	v_mfma_f32_32x32x16_bf16 v[32:47], v[66:69], v[102:105], v[32:47]
	ds_read_b128 v[66:69], v64 offset:31296
	ds_read_b128 v[70:73], v64 offset:31328
	s_waitcnt lgkmcnt(1)
	v_mfma_f32_32x32x16_bf16 v[32:47], v[66:69], v[98:101], v[32:47]
	s_waitcnt lgkmcnt(0)
	v_mfma_f32_32x32x16_bf16 v[32:47], v[70:73], v[94:97], v[32:47]
	v_lshl_add_u32 v236, v58, 2, s23
	v_sub_u32_e32 v237, v57, v58
	ds_read_b128 v[170:173], v236 offset:36224
	ds_read_b128 v[174:177], v236 offset:36736
	ds_read_b128 v[178:181], v236 offset:37248
	ds_read_b128 v[182:185], v236 offset:37760
	ds_read_b128 v[186:189], v236 offset:36256
	ds_read_b128 v[190:193], v236 offset:36768
	ds_read_b128 v[194:197], v236 offset:37280
	ds_read_b128 v[198:201], v236 offset:37792
	ds_read_b128 v[202:205], v236 offset:36288
	ds_read_b128 v[206:209], v236 offset:36800
	ds_read_b128 v[210:213], v236 offset:37312
	ds_read_b128 v[214:217], v236 offset:37824
	s_waitcnt lgkmcnt(8)
	ds_read_b128 v[218:221], v236 offset:36320
	ds_read_b128 v[222:225], v236 offset:36832
	ds_read_b128 v[226:229], v236 offset:37344
	ds_read_b128 v[230:233], v236 offset:37856
	v_add_u32_e32 v238, 0xffffffa0, v237
	v_cmp_lt_i32_e32 vcc, 0, v238
	v_cmp_lt_i32_e64 s[4:5], 1, v238
	v_cmp_lt_i32_e64 s[6:7], 2, v238
	v_cmp_lt_i32_e64 s[30:31], 3, v238
	v_sub_f32_e32 v170, v54, v170
	v_sub_f32_e32 v171, v54, v171
	v_sub_f32_e32 v172, v54, v172
	v_sub_f32_e32 v173, v54, v173
	v_sub_f32_e32 v174, v55, v174
	v_sub_f32_e32 v175, v55, v175
	v_sub_f32_e32 v176, v55, v176
	v_sub_f32_e32 v177, v55, v177
	v_cndmask_b32_e64 v170, v174, v170, vcc
	v_cndmask_b32_e64 v171, v175, v171, s[4:5]
	v_cndmask_b32_e64 v172, v176, v172, s[6:7]
	v_cndmask_b32_e64 v173, v177, v173, s[30:31]
	v_add_f32_e32 v174, v178, v182
	v_add_f32_e32 v175, v179, v183
	v_add_f32_e32 v176, v180, v184
	v_add_f32_e32 v177, v181, v185
	v_cndmask_b32_e64 v178, v182, v178, vcc
	v_cndmask_b32_e64 v179, v183, v179, s[4:5]
	v_cndmask_b32_e64 v180, v184, v180, s[6:7]
	v_cndmask_b32_e64 v181, v185, v181, s[30:31]
	v_cmp_eq_u32_e32 vcc, 0, v238
	v_cmp_eq_u32_e64 s[4:5], 1, v238
	v_cmp_eq_u32_e64 s[6:7], 2, v238
	v_cmp_eq_u32_e64 s[30:31], 3, v238
	v_mul_f32_e32 v170, 0x3fb8aa3b, v170
	v_mul_f32_e32 v171, 0x3fb8aa3b, v171
	v_mul_f32_e32 v172, 0x3fb8aa3b, v172
	v_mul_f32_e32 v173, 0x3fb8aa3b, v173
	v_exp_f32_e32 v170, v170
	v_exp_f32_e32 v171, v171
	v_exp_f32_e32 v172, v172
	v_exp_f32_e32 v173, v173
	v_mul_f32_e32 v178, v178, v170
	v_mul_f32_e32 v179, v179, v171
	v_mul_f32_e32 v180, v180, v172
	v_mul_f32_e32 v181, v181, v173
	v_cndmask_b32_e64 v64, v178, v174, vcc
	v_cndmask_b32_e64 v65, v179, v175, s[4:5]
	v_cndmask_b32_e64 v66, v180, v176, s[6:7]
	v_cndmask_b32_e64 v67, v181, v177, s[30:31]
	s_waitcnt lgkmcnt(8)
	v_add_u32_e32 v238, 0xffffff98, v237
	v_cmp_lt_i32_e32 vcc, 0, v238
	v_cmp_lt_i32_e64 s[4:5], 1, v238
	v_cmp_lt_i32_e64 s[6:7], 2, v238
	v_cmp_lt_i32_e64 s[30:31], 3, v238
	v_sub_f32_e32 v186, v54, v186
	v_sub_f32_e32 v187, v54, v187
	v_sub_f32_e32 v188, v54, v188
	v_sub_f32_e32 v189, v54, v189
	v_sub_f32_e32 v190, v55, v190
	v_sub_f32_e32 v191, v55, v191
	v_sub_f32_e32 v192, v55, v192
	v_sub_f32_e32 v193, v55, v193
	v_cndmask_b32_e64 v186, v190, v186, vcc
	v_cndmask_b32_e64 v187, v191, v187, s[4:5]
	v_cndmask_b32_e64 v188, v192, v188, s[6:7]
	v_cndmask_b32_e64 v189, v193, v189, s[30:31]
	v_add_f32_e32 v190, v194, v198
	v_add_f32_e32 v191, v195, v199
	v_add_f32_e32 v192, v196, v200
	v_add_f32_e32 v193, v197, v201
	v_cndmask_b32_e64 v194, v198, v194, vcc
	v_cndmask_b32_e64 v195, v199, v195, s[4:5]
	v_cndmask_b32_e64 v196, v200, v196, s[6:7]
	v_cndmask_b32_e64 v197, v201, v197, s[30:31]
	v_cmp_eq_u32_e32 vcc, 0, v238
	v_cmp_eq_u32_e64 s[4:5], 1, v238
	v_cmp_eq_u32_e64 s[6:7], 2, v238
	v_cmp_eq_u32_e64 s[30:31], 3, v238
	v_mul_f32_e32 v186, 0x3fb8aa3b, v186
	v_mul_f32_e32 v187, 0x3fb8aa3b, v187
	v_mul_f32_e32 v188, 0x3fb8aa3b, v188
	v_mul_f32_e32 v189, 0x3fb8aa3b, v189
	v_exp_f32_e32 v186, v186
	v_exp_f32_e32 v187, v187
	v_exp_f32_e32 v188, v188
	v_exp_f32_e32 v189, v189
	v_mul_f32_e32 v194, v194, v186
	v_mul_f32_e32 v195, v195, v187
	v_mul_f32_e32 v196, v196, v188
	v_mul_f32_e32 v197, v197, v189
	v_cndmask_b32_e64 v63, v194, v190, vcc
	v_cndmask_b32_e64 v68, v195, v191, s[4:5]
	v_cndmask_b32_e64 v69, v196, v192, s[6:7]
	v_cndmask_b32_e64 v70, v197, v193, s[30:31]
	s_waitcnt lgkmcnt(4)
	v_add_u32_e32 v238, 0xffffff90, v237
	v_cmp_lt_i32_e32 vcc, 0, v238
	v_cmp_lt_i32_e64 s[4:5], 1, v238
	v_cmp_lt_i32_e64 s[6:7], 2, v238
	v_cmp_lt_i32_e64 s[30:31], 3, v238
	v_sub_f32_e32 v202, v54, v202
	v_sub_f32_e32 v203, v54, v203
	v_sub_f32_e32 v204, v54, v204
	v_sub_f32_e32 v205, v54, v205
	v_sub_f32_e32 v206, v55, v206
	v_sub_f32_e32 v207, v55, v207
	v_sub_f32_e32 v208, v55, v208
	v_sub_f32_e32 v209, v55, v209
	v_cndmask_b32_e64 v202, v206, v202, vcc
	v_cndmask_b32_e64 v203, v207, v203, s[4:5]
	v_cndmask_b32_e64 v204, v208, v204, s[6:7]
	v_cndmask_b32_e64 v205, v209, v205, s[30:31]
	v_add_f32_e32 v206, v210, v214
	v_add_f32_e32 v207, v211, v215
	v_add_f32_e32 v208, v212, v216
	v_add_f32_e32 v209, v213, v217
	v_cndmask_b32_e64 v210, v214, v210, vcc
	v_cndmask_b32_e64 v211, v215, v211, s[4:5]
	v_cndmask_b32_e64 v212, v216, v212, s[6:7]
	v_cndmask_b32_e64 v213, v217, v213, s[30:31]
	v_cmp_eq_u32_e32 vcc, 0, v238
	v_cmp_eq_u32_e64 s[4:5], 1, v238
	v_cmp_eq_u32_e64 s[6:7], 2, v238
	v_cmp_eq_u32_e64 s[30:31], 3, v238
	v_mul_f32_e32 v202, 0x3fb8aa3b, v202
	v_mul_f32_e32 v203, 0x3fb8aa3b, v203
	v_mul_f32_e32 v204, 0x3fb8aa3b, v204
	v_mul_f32_e32 v205, 0x3fb8aa3b, v205
	v_exp_f32_e32 v202, v202
	v_exp_f32_e32 v203, v203
	v_exp_f32_e32 v204, v204
	v_exp_f32_e32 v205, v205
	v_mul_f32_e32 v210, v210, v202
	v_mul_f32_e32 v211, v211, v203
	v_mul_f32_e32 v212, v212, v204
	v_mul_f32_e32 v213, v213, v205
	v_cndmask_b32_e64 v71, v210, v206, vcc
	v_cndmask_b32_e64 v72, v211, v207, s[4:5]
	v_cndmask_b32_e64 v73, v212, v208, s[6:7]
	v_cndmask_b32_e64 v74, v213, v209, s[30:31]
	s_waitcnt lgkmcnt(0)
	v_add_u32_e32 v238, 0xffffff88, v237
	v_cmp_lt_i32_e32 vcc, 0, v238
	v_cmp_lt_i32_e64 s[4:5], 1, v238
	v_cmp_lt_i32_e64 s[6:7], 2, v238
	v_cmp_lt_i32_e64 s[30:31], 3, v238
	v_sub_f32_e32 v218, v54, v218
	v_sub_f32_e32 v219, v54, v219
	v_sub_f32_e32 v220, v54, v220
	v_sub_f32_e32 v221, v54, v221
	v_sub_f32_e32 v222, v55, v222
	v_sub_f32_e32 v223, v55, v223
	v_sub_f32_e32 v224, v55, v224
	v_sub_f32_e32 v225, v55, v225
	v_cndmask_b32_e64 v218, v222, v218, vcc
	v_cndmask_b32_e64 v219, v223, v219, s[4:5]
	v_cndmask_b32_e64 v220, v224, v220, s[6:7]
	v_cndmask_b32_e64 v221, v225, v221, s[30:31]
	v_add_f32_e32 v222, v226, v230
	v_add_f32_e32 v223, v227, v231
	v_add_f32_e32 v224, v228, v232
	v_add_f32_e32 v225, v229, v233
	v_cndmask_b32_e64 v226, v230, v226, vcc
	v_cndmask_b32_e64 v227, v231, v227, s[4:5]
	v_cndmask_b32_e64 v228, v232, v228, s[6:7]
	v_cndmask_b32_e64 v229, v233, v229, s[30:31]
	v_cmp_eq_u32_e32 vcc, 0, v238
	v_cmp_eq_u32_e64 s[4:5], 1, v238
	v_cmp_eq_u32_e64 s[6:7], 2, v238
	v_cmp_eq_u32_e64 s[30:31], 3, v238
	v_mul_f32_e32 v218, 0x3fb8aa3b, v218
	v_mul_f32_e32 v219, 0x3fb8aa3b, v219
	v_mul_f32_e32 v220, 0x3fb8aa3b, v220
	v_mul_f32_e32 v221, 0x3fb8aa3b, v221
	v_exp_f32_e32 v218, v218
	v_exp_f32_e32 v219, v219
	v_exp_f32_e32 v220, v220
	v_exp_f32_e32 v221, v221
	v_mul_f32_e32 v226, v226, v218
	v_mul_f32_e32 v227, v227, v219
	v_mul_f32_e32 v228, v228, v220
	v_mul_f32_e32 v229, v229, v221
	v_cndmask_b32_e64 v75, v226, v222, vcc
	v_cndmask_b32_e64 v76, v227, v223, s[4:5]
	v_cndmask_b32_e64 v77, v228, v224, s[6:7]
	v_cndmask_b32_e64 v78, v229, v225, s[30:31]
	s_lshl_b32 s2, s48, 6
	s_mul_i32 s4, s50, 34
	s_add_i32 s4, s4, s49
	s_ashr_i32 s5, s4, 31
	s_lshl_b64 s[4:5], s[4:5], 16
	s_lshl_b32 s6, s48, 13
	s_add_u32 s6, s34, s6
	s_addc_u32 s7, s35, 0
	v_lshlrev_b32_e32 v106, 1, v59
	v_lshl_add_u64 v[80:81], s[6:7], 0, v[106:107]
	v_lshl_add_u64 v[88:89], v[80:81], 0, s[4:5]
	v_lshlrev_b32_e32 v106, 7, v56
	v_lshl_add_u64 v[56:57], v[88:89], 0, v[106:107]
	global_load_dwordx4 v[80:83], v[56:57], off
	v_mov_b32_e32 v147, v107
	v_or_b32_e32 v146, 0x1000, v106
	v_lshl_add_u64 v[148:149], v[88:89], 0, s[24:25]
	v_lshl_add_u64 v[142:143], v[88:89], 0, v[146:147]
	v_lshl_add_u64 v[92:93], v[148:149], 0, v[106:107]
	global_load_dwordx4 v[84:87], v[142:143], off
	global_load_dwordx4 v[88:91], v[92:93], off
	global_load_dwordx4 v[114:117], v[56:57], off offset:32
	global_load_dwordx4 v[118:121], v[142:143], off offset:32
	v_mul_f32_e32 v59, v37, v68
	v_mul_f32_e32 v60, v36, v63
	v_mul_f32_e32 v63, v35, v67
	v_mul_f32_e32 v68, v34, v66
	ds_read2_b64 v[34:37], v61 offset0:24 offset1:26
	v_mul_f32_e32 v39, v39, v70
	v_mul_f32_e32 v38, v38, v69
	v_mul_f32_e32 v33, v33, v65
	v_mul_f32_e32 v32, v32, v64
	ds_read2_b64 v[64:67], v62 offset0:88 offset1:90
	global_load_dwordx4 v[122:125], v[92:93], off offset:32
	global_load_dwordx4 v[134:137], v[92:93], off offset:64
	v_cvt_pk_bf16_f32 v126, v32, v33
	v_cvt_pk_bf16_f32 v127, v68, v63
	v_cvt_pk_bf16_f32 v128, v60, v59
	global_load_dwordx4 v[130:133], v[56:57], off offset:64
	v_cvt_pk_bf16_f32 v129, v38, v39
	v_mul_f32_e32 v46, v46, v77
	v_mul_f32_e32 v45, v45, v76
	s_waitcnt lgkmcnt(1)
	v_mfma_f32_32x32x16_bf16 v[16:31], v[34:37], v[126:129], v[16:31]
	ds_read2_b64 v[32:35], v61 offset0:28 offset1:30
	v_mul_f32_e32 v44, v44, v75
	v_mul_f32_e32 v43, v43, v74
	v_mul_f32_e32 v42, v42, v73
	v_mul_f32_e32 v41, v41, v72
	v_mul_f32_e32 v40, v40, v71
	v_mul_f32_e32 v47, v47, v78
	s_waitcnt lgkmcnt(1)
	v_mfma_f32_32x32x16_bf16 v[0:15], v[64:67], v[126:129], v[0:15]
	global_load_dwordx4 v[126:129], v[142:143], off offset:64
	global_load_dwordx4 v[138:141], v[56:57], off offset:96
	v_cvt_pk_bf16_f32 v40, v40, v41
	v_cvt_pk_bf16_f32 v41, v42, v43
	v_cvt_pk_bf16_f32 v42, v44, v45
	v_cvt_pk_bf16_f32 v43, v46, v47
	s_lshl_b32 s20, s2, 1
	v_lshlrev_b32_e32 v106, 1, v58
	s_waitcnt lgkmcnt(0)
	v_mfma_f32_32x32x16_bf16 v[16:31], v[32:35], v[40:43], v[16:31]
	v_mov_b64_e32 v[32:33], s[8:9]
	v_mad_i64_i32 v[60:61], s[4:5], v108, s44, v[32:33]
	v_lshl_add_u64 v[32:33], v[60:61], 0, s[20:21]
	v_lshl_add_u64 v[162:163], v[32:33], 0, v[106:107]
	v_add_co_u32_e32 v78, vcc, s45, v162
	v_lshl_add_u64 v[52:53], v[52:53], 0, s[20:21]
	s_nop 0
	v_addc_co_u32_e32 v79, vcc, 0, v163, vcc
	v_lshl_add_u64 v[52:53], v[52:53], 0, v[106:107]
	global_load_dwordx2 v[168:169], v[78:79], off offset:2368
	global_load_dwordx2 v[170:171], v[52:53], off
	global_load_dwordx4 v[56:59], v[92:93], off offset:96
	v_lshl_add_u64 v[158:159], v[148:149], 0, v[146:147]
	global_load_dwordx4 v[142:145], v[142:143], off offset:96
	s_lshl_b32 s6, s48, 2
	global_load_dwordx4 v[146:149], v[158:159], off
	v_mov_b32_e32 v109, s6
	global_load_dword v110, v109, s[12:13] offset:32
	global_load_dwordx4 v[150:153], v[158:159], off offset:32
	global_load_dwordx4 v[154:157], v[158:159], off offset:64
	ds_read2_b64 v[36:39], v62 offset0:92 offset1:94
	global_load_dwordx4 v[158:161], v[158:159], off offset:96
	s_waitcnt lgkmcnt(0)
	v_mfma_f32_32x32x16_bf16 v[0:15], v[36:39], v[40:43], v[0:15]
	v_mul_f32_e32 v54, 0x3fb8aa3b, v54
	v_mul_f32_e32 v55, 0x3fb8aa3b, v55
	v_exp_f32_e32 v112, v54
	v_ashrrev_i32_e32 v109, 31, v108
	s_waitcnt vmcnt(8)
	v_and_b32_e32 v167, 0xffff0000, v168
	v_mfma_f32_32x32x16_bf16 v[62:77], v[80:83], v[48:51], 0
	v_mfma_f32_32x32x16_bf16 v[32:47], v[84:87], v[48:51], 0
	v_mfma_f32_32x32x16_bf16 v[78:93], v[88:91], v[48:51], 0
	v_mfma_f32_32x32x16_bf16 v[62:77], v[114:117], v[102:105], v[62:77]
	v_exp_f32_e32 v114, v55
	v_mad_i64_i32 v[54:55], s[4:5], v108, s46, v[60:61]
	v_lshl_add_u64 v[172:173], v[54:55], 0, s[20:21]
	v_lshl_add_u64 v[54:55], v[162:163], 0, s[26:27]
	v_lshlrev_b32_e32 v115, 16, v168
	v_mfma_f32_32x32x16_bf16 v[32:47], v[118:121], v[102:105], v[32:47]
	v_mfma_f32_32x32x16_bf16 v[78:93], v[122:125], v[102:105], v[78:93]
	v_mfma_f32_32x32x16_bf16 v[62:77], v[130:133], v[98:101], v[62:77]
	v_mfma_f32_32x32x16_bf16 v[32:47], v[126:129], v[98:101], v[32:47]
	v_mfma_f32_32x32x16_bf16 v[78:93], v[134:137], v[98:101], v[78:93]
	global_load_dwordx2 v[162:163], v[52:53], off offset:16
	global_load_dwordx2 v[136:137], v[52:53], off offset:32
	global_load_dwordx2 v[132:133], v[52:53], off offset:48
	global_load_dwordx2 v[128:129], v[52:53], off offset:64
	global_load_dwordx2 v[124:125], v[52:53], off offset:80
	global_load_dwordx2 v[120:121], v[52:53], off offset:96
	global_load_dwordx2 v[116:117], v[52:53], off offset:112
	v_mul_f32_e32 v52, 0xbfb8aa3b, v115
	v_mul_f32_e32 v53, 0xbfb8aa3b, v167
	v_exp_f32_e32 v52, v52
	v_exp_f32_e32 v53, v53
	v_mfma_f32_32x32x16_bf16 v[62:77], v[138:141], v[94:97], v[62:77]
	global_load_dwordx2 v[140:141], v[54:55], off offset:16
	global_load_dwordx2 v[138:139], v[54:55], off offset:32
	global_load_dwordx2 v[134:135], v[54:55], off offset:48
	global_load_dwordx2 v[130:131], v[54:55], off offset:64
	global_load_dwordx2 v[126:127], v[54:55], off offset:80
	global_load_dwordx2 v[122:123], v[54:55], off offset:96
	global_load_dwordx2 v[118:119], v[54:55], off offset:112
	s_waitcnt vmcnt(21)
	v_lshlrev_b32_e32 v54, 16, v170
	v_and_b32_e32 v55, 0xffff0000, v170
	s_nop 1
	v_pk_fma_f32 v[16:17], v[112:113], v[62:63], v[16:17] op_sel_hi:[0,1,1]
	s_waitcnt vmcnt(20)
	v_mfma_f32_32x32x16_bf16 v[78:93], v[56:59], v[94:97], v[78:93]
	v_fma_f32 v18, v112, v64, v18
	v_fma_f32 v19, v112, v65, v19
	s_waitcnt vmcnt(19)
	v_mfma_f32_32x32x16_bf16 v[32:47], v[142:145], v[94:97], v[32:47]
	s_nop 7
	v_fma_f32 v16, v114, v78, v16
	v_fma_f32 v17, v114, v79, v17
	v_add_f32_e64 v78, v52, 1.0
	v_add_f32_e64 v79, v53, 1.0
	s_waitcnt vmcnt(17)
	v_pk_fma_f32 v[16:17], v[110:111], v[54:55], v[16:17] op_sel_hi:[0,1,1]
	v_div_scale_f32 v142, s[4:5], v79, v79, v167
	v_rcp_f32_e32 v143, v142
	v_pk_fma_f32 v[18:19], v[114:115], v[80:81], v[18:19] op_sel_hi:[0,1,1]
	v_mfma_f32_32x32x16_bf16 v[48:63], v[146:149], v[48:51], 0
	v_fma_f32 v0, v112, v32, v0
	v_fma_f32 v1, v112, v33, v1
	v_fma_f32 v144, -v142, v143, 1.0
	v_fmac_f32_e32 v143, v144, v143
	v_div_scale_f32 v144, vcc, v167, v79, v167
	v_mul_f32_e32 v145, v144, v143
	v_fma_f32 v146, -v142, v145, v144
	s_waitcnt vmcnt(16)
	v_mfma_f32_32x32x16_bf16 v[48:63], v[150:153], v[102:105], v[48:63]
	v_div_scale_f32 v103, s[4:5], v78, v78, v115
	v_rcp_f32_e32 v104, v103
	v_fmac_f32_e32 v145, v146, v143
	v_fma_f32 v102, -v142, v145, v144
	v_div_fmas_f32 v102, v102, v143, v145
	v_div_fixup_f32 v79, v102, v79, v167
	s_waitcnt vmcnt(15)
	v_mfma_f32_32x32x16_bf16 v[48:63], v[154:157], v[98:101], v[48:63]
	v_fma_f32 v98, -v103, v104, 1.0
	v_fmac_f32_e32 v104, v98, v104
	v_div_scale_f32 v98, vcc, v115, v78, v115
	v_mul_f32_e32 v99, v98, v104
	v_fma_f32 v100, -v103, v99, v98
	v_fmac_f32_e32 v99, v100, v104
	s_waitcnt vmcnt(14)
	v_mfma_f32_32x32x16_bf16 v[48:63], v[158:161], v[94:97], v[48:63]
	v_fma_f32 v94, -v103, v99, v98
	v_div_fmas_f32 v94, v94, v104, v99
	v_lshlrev_b32_e32 v96, 16, v169
	v_and_b32_e32 v97, 0xffff0000, v169
	v_div_fixup_f32 v78, v94, v78, v115
	v_mul_f32_e32 v94, 0xbfb8aa3b, v96
	v_mul_f32_e32 v95, 0xbfb8aa3b, v97
	v_exp_f32_e32 v94, v94
	v_exp_f32_e32 v95, v95
	v_pk_mul_f32 v[16:17], v[16:17], v[78:79]
	v_lshlrev_b32_e32 v78, 16, v171
	v_and_b32_e32 v79, 0xffff0000, v171
	v_pk_add_f32 v[64:65], v[94:95], 1.0 op_sel_hi:[1,0]
	v_pk_fma_f32 v[18:19], v[110:111], v[78:79], v[18:19] op_sel_hi:[0,1,1]
	v_div_scale_f32 v80, s[4:5], v65, v65, v97
	v_rcp_f32_e32 v81, v80
	v_pk_fma_f32 v[0:1], v[114:115], v[48:49], v[0:1] op_sel_hi:[0,1,1]
	v_pk_fma_f32 v[2:3], v[112:113], v[34:35], v[2:3] op_sel_hi:[0,1,1]
	v_pk_fma_f32 v[2:3], v[114:115], v[50:51], v[2:3] op_sel_hi:[0,1,1]
	v_fma_f32 v78, -v80, v81, 1.0
	v_fmac_f32_e32 v81, v78, v81
	v_div_scale_f32 v78, vcc, v97, v65, v97
	v_mul_f32_e32 v79, v78, v81
	v_fma_f32 v94, -v80, v79, v78
	v_fmac_f32_e32 v79, v94, v81
	v_fma_f32 v78, -v80, v79, v78
	v_div_scale_f32 v80, s[4:5], v64, v64, v96
	v_rcp_f32_e32 v94, v80
	v_div_fmas_f32 v78, v78, v81, v79
	v_div_fixup_f32 v65, v78, v65, v97
	v_fma_f32 v78, -v80, v94, 1.0
	v_fmac_f32_e32 v94, v78, v94
	v_div_scale_f32 v78, vcc, v96, v64, v96
	v_mul_f32_e32 v79, v78, v94
	v_fma_f32 v81, -v80, v79, v78
	v_fmac_f32_e32 v79, v81, v94
	v_fma_f32 v78, -v80, v79, v78
	v_div_fmas_f32 v78, v78, v94, v79
	v_div_fixup_f32 v64, v78, v64, v96
	v_pk_mul_f32 v[18:19], v[18:19], v[64:65]
	v_cvt_pk_bf16_f32 v64, v16, v17
	v_and_b32_e32 v17, 0xffff0000, v64
	v_cvt_pk_bf16_f32 v65, v18, v19
	v_lshlrev_b32_e32 v16, 16, v64
	v_mul_f32_e32 v80, v17, v17
	s_waitcnt vmcnt(6)
	v_lshlrev_b32_e32 v81, 16, v140
	v_and_b32_e32 v94, 0xffff0000, v140
	v_lshlrev_b32_e32 v18, 16, v65
	v_fmac_f32_e32 v80, v16, v16
	v_mul_f32_e32 v78, 0xbfb8aa3b, v81
	v_mul_f32_e32 v79, 0xbfb8aa3b, v94
	v_and_b32_e32 v19, 0xffff0000, v65
	v_fmac_f32_e32 v80, v18, v18
	v_exp_f32_e32 v78, v78
	v_exp_f32_e32 v79, v79
	v_fmac_f32_e32 v80, v19, v19
	v_lshl_add_u64 v[18:19], v[172:173], 0, v[106:107]
	v_lshl_add_u64 v[16:17], v[18:19], 0, s[28:29]
	v_add_co_u32_e32 v18, vcc, s47, v18
	s_nop 1
	v_addc_co_u32_e32 v19, vcc, 0, v19, vcc
	global_store_dwordx2 v[18:19], v[64:65], off offset:1024
	v_pk_fma_f32 v[18:19], v[112:113], v[66:67], v[20:21] op_sel_hi:[0,1,1]
	v_pk_add_f32 v[20:21], v[78:79], 1.0 op_sel_hi:[1,0]
	v_pk_fma_f32 v[18:19], v[114:115], v[82:83], v[18:19] op_sel_hi:[0,1,1]
	v_div_scale_f32 v66, s[4:5], v21, v21, v94
	v_rcp_f32_e32 v67, v66
	v_lshlrev_b32_e32 v64, 16, v162
	v_and_b32_e32 v65, 0xffff0000, v162
	v_pk_fma_f32 v[18:19], v[110:111], v[64:65], v[18:19] op_sel_hi:[0,1,1]
	v_fma_f32 v64, -v66, v67, 1.0
	v_fmac_f32_e32 v67, v64, v67
	v_div_scale_f32 v64, vcc, v94, v21, v94
	v_mul_f32_e32 v65, v64, v67
	v_fma_f32 v78, -v66, v65, v64
	v_fmac_f32_e32 v65, v78, v67
	v_fma_f32 v64, -v66, v65, v64
	v_div_scale_f32 v66, s[4:5], v20, v20, v81
	v_rcp_f32_e32 v78, v66
	v_div_fmas_f32 v64, v64, v67, v65
	v_div_fixup_f32 v21, v64, v21, v94
	v_fma_f32 v64, -v66, v78, 1.0
	v_fmac_f32_e32 v78, v64, v78
	v_div_scale_f32 v64, vcc, v81, v20, v81
	v_mul_f32_e32 v65, v64, v78
	v_fma_f32 v67, -v66, v65, v64
	v_fmac_f32_e32 v65, v67, v78
	v_fma_f32 v64, -v66, v65, v64
	v_div_fmas_f32 v64, v64, v78, v65
	v_lshlrev_b32_e32 v66, 16, v141
	v_and_b32_e32 v67, 0xffff0000, v141
	v_div_fixup_f32 v20, v64, v20, v81
	v_mul_f32_e32 v64, 0xbfb8aa3b, v66
	v_mul_f32_e32 v65, 0xbfb8aa3b, v67
	v_exp_f32_e32 v64, v64
	v_exp_f32_e32 v65, v65
	v_pk_mul_f32 v[18:19], v[18:19], v[20:21]
	v_pk_fma_f32 v[20:21], v[112:113], v[68:69], v[22:23] op_sel_hi:[0,1,1]
	v_pk_fma_f32 v[20:21], v[114:115], v[84:85], v[20:21] op_sel_hi:[0,1,1]
	v_pk_add_f32 v[22:23], v[64:65], 1.0 op_sel_hi:[1,0]
	v_lshlrev_b32_e32 v64, 16, v163
	v_div_scale_f32 v68, s[4:5], v23, v23, v67
	v_rcp_f32_e32 v69, v68
	v_and_b32_e32 v65, 0xffff0000, v163
	v_pk_fma_f32 v[20:21], v[110:111], v[64:65], v[20:21] op_sel_hi:[0,1,1]
	v_cvt_pk_bf16_f32 v18, v18, v19
	v_fma_f32 v64, -v68, v69, 1.0
	v_fmac_f32_e32 v69, v64, v69
	v_div_scale_f32 v64, vcc, v67, v23, v67
	v_mul_f32_e32 v65, v64, v69
	v_fma_f32 v78, -v68, v65, v64
	v_fmac_f32_e32 v65, v78, v69
	v_fma_f32 v64, -v68, v65, v64
	v_div_scale_f32 v68, s[4:5], v22, v22, v66
	v_rcp_f32_e32 v78, v68
	v_div_fmas_f32 v64, v64, v69, v65
	v_div_fixup_f32 v23, v64, v23, v67
	v_fma_f32 v64, -v68, v78, 1.0
	v_fmac_f32_e32 v78, v64, v78
	v_div_scale_f32 v64, vcc, v66, v22, v66
	v_mul_f32_e32 v65, v64, v78
	v_fma_f32 v67, -v68, v65, v64
	v_fmac_f32_e32 v65, v67, v78
	v_fma_f32 v64, -v68, v65, v64
	v_div_fmas_f32 v64, v64, v78, v65
	v_div_fixup_f32 v22, v64, v22, v66
	v_pk_mul_f32 v[20:21], v[20:21], v[22:23]
	s_waitcnt vmcnt(6)
	v_lshlrev_b32_e32 v65, 16, v138
	v_cvt_pk_bf16_f32 v19, v20, v21
	v_and_b32_e32 v21, 0xffff0000, v18
	v_lshlrev_b32_e32 v20, 16, v18
	v_mul_f32_e32 v21, v21, v21
	v_lshlrev_b32_e32 v22, 16, v19
	v_fmac_f32_e32 v21, v20, v20
	v_and_b32_e32 v23, 0xffff0000, v19
	v_fmac_f32_e32 v21, v22, v22
	v_fmac_f32_e32 v21, v23, v23
	v_and_b32_e32 v66, 0xffff0000, v138
	v_add_f32_e32 v64, v80, v21
	v_mul_f32_e32 v20, 0xbfb8aa3b, v65
	v_mul_f32_e32 v21, 0xbfb8aa3b, v66
	v_exp_f32_e32 v20, v20
	v_exp_f32_e32 v21, v21
	global_store_dwordx2 v[16:17], v[18:19], off offset:16
	v_pk_fma_f32 v[18:19], v[112:113], v[70:71], v[24:25] op_sel_hi:[0,1,1]
	v_pk_fma_f32 v[18:19], v[114:115], v[86:87], v[18:19] op_sel_hi:[0,1,1]
	v_pk_add_f32 v[20:21], v[20:21], 1.0 op_sel_hi:[1,0]
	v_lshlrev_b32_e32 v22, 16, v136
	v_div_scale_f32 v24, s[4:5], v21, v21, v66
	v_rcp_f32_e32 v25, v24
	v_and_b32_e32 v23, 0xffff0000, v136
	v_pk_fma_f32 v[18:19], v[110:111], v[22:23], v[18:19] op_sel_hi:[0,1,1]
	v_fma_f32 v22, -v24, v25, 1.0
	v_fmac_f32_e32 v25, v22, v25
	v_div_scale_f32 v22, vcc, v66, v21, v66
	v_mul_f32_e32 v23, v22, v25
	v_fma_f32 v67, -v24, v23, v22
	v_fmac_f32_e32 v23, v67, v25
	v_fma_f32 v22, -v24, v23, v22
	v_div_scale_f32 v24, s[4:5], v20, v20, v65
	v_rcp_f32_e32 v67, v24
	v_div_fmas_f32 v22, v22, v25, v23
	v_div_fixup_f32 v21, v22, v21, v66
	v_and_b32_e32 v66, 0xffff0000, v139
	v_fma_f32 v22, -v24, v67, 1.0
	v_fmac_f32_e32 v67, v22, v67
	v_div_scale_f32 v22, vcc, v65, v20, v65
	v_mul_f32_e32 v23, v22, v67
	v_fma_f32 v25, -v24, v23, v22
	v_fmac_f32_e32 v23, v25, v67
	v_fma_f32 v22, -v24, v23, v22
	v_div_fmas_f32 v22, v22, v67, v23
	v_div_fixup_f32 v20, v22, v20, v65
	v_lshlrev_b32_e32 v65, 16, v139
	v_mul_f32_e32 v22, 0xbfb8aa3b, v65
	v_mul_f32_e32 v23, 0xbfb8aa3b, v66
	v_exp_f32_e32 v22, v22
	v_exp_f32_e32 v23, v23
	v_pk_mul_f32 v[18:19], v[18:19], v[20:21]
	v_pk_fma_f32 v[20:21], v[112:113], v[72:73], v[26:27] op_sel_hi:[0,1,1]
	v_pk_fma_f32 v[20:21], v[114:115], v[88:89], v[20:21] op_sel_hi:[0,1,1]
	v_pk_add_f32 v[22:23], v[22:23], 1.0 op_sel_hi:[1,0]
	v_lshlrev_b32_e32 v24, 16, v137
	v_div_scale_f32 v26, s[4:5], v23, v23, v66
	v_rcp_f32_e32 v27, v26
	v_and_b32_e32 v25, 0xffff0000, v137
	v_pk_fma_f32 v[20:21], v[110:111], v[24:25], v[20:21] op_sel_hi:[0,1,1]
	v_cvt_pk_bf16_f32 v18, v18, v19
	v_fma_f32 v24, -v26, v27, 1.0
	v_fmac_f32_e32 v27, v24, v27
	v_div_scale_f32 v24, vcc, v66, v23, v66
	v_mul_f32_e32 v25, v24, v27
	v_fma_f32 v67, -v26, v25, v24
	v_fmac_f32_e32 v25, v67, v27
	v_fma_f32 v24, -v26, v25, v24
	v_div_scale_f32 v26, s[4:5], v22, v22, v65
	v_rcp_f32_e32 v67, v26
	v_div_fmas_f32 v24, v24, v27, v25
	v_div_fixup_f32 v23, v24, v23, v66
	v_fma_f32 v24, -v26, v67, 1.0
	v_fmac_f32_e32 v67, v24, v67
	v_div_scale_f32 v24, vcc, v65, v22, v65
	v_mul_f32_e32 v25, v24, v67
	v_fma_f32 v27, -v26, v25, v24
	v_fmac_f32_e32 v25, v27, v67
	v_fma_f32 v24, -v26, v25, v24
	v_div_fmas_f32 v24, v24, v67, v25
	v_div_fixup_f32 v22, v24, v22, v65
	v_pk_mul_f32 v[20:21], v[20:21], v[22:23]
	s_waitcnt vmcnt(6)
	v_lshlrev_b32_e32 v24, 16, v134
	v_cvt_pk_bf16_f32 v19, v20, v21
	v_and_b32_e32 v21, 0xffff0000, v18
	v_lshlrev_b32_e32 v20, 16, v18
	v_mul_f32_e32 v21, v21, v21
	v_lshlrev_b32_e32 v22, 16, v19
	v_fmac_f32_e32 v21, v20, v20
	v_and_b32_e32 v23, 0xffff0000, v19
	v_fmac_f32_e32 v21, v22, v22
	v_fmac_f32_e32 v21, v23, v23
	v_and_b32_e32 v25, 0xffff0000, v134
	v_add_f32_e32 v26, v64, v21
	v_mul_f32_e32 v20, 0xbfb8aa3b, v24
	v_mul_f32_e32 v21, 0xbfb8aa3b, v25
	v_exp_f32_e32 v20, v20
	v_exp_f32_e32 v21, v21
	global_store_dwordx2 v[16:17], v[18:19], off offset:32
	v_pk_fma_f32 v[18:19], v[112:113], v[74:75], v[28:29] op_sel_hi:[0,1,1]
	v_pk_fma_f32 v[18:19], v[114:115], v[90:91], v[18:19] op_sel_hi:[0,1,1]
	v_pk_add_f32 v[20:21], v[20:21], 1.0 op_sel_hi:[1,0]
	v_lshlrev_b32_e32 v22, 16, v132
	v_div_scale_f32 v27, s[4:5], v21, v21, v25
	v_rcp_f32_e32 v28, v27
	v_and_b32_e32 v23, 0xffff0000, v132
	v_pk_fma_f32 v[18:19], v[110:111], v[22:23], v[18:19] op_sel_hi:[0,1,1]
	v_fma_f32 v22, -v27, v28, 1.0
	v_fmac_f32_e32 v28, v22, v28
	v_div_scale_f32 v22, vcc, v25, v21, v25
	v_mul_f32_e32 v23, v22, v28
	v_fma_f32 v29, -v27, v23, v22
	v_fmac_f32_e32 v23, v29, v28
	v_fma_f32 v22, -v27, v23, v22
	v_div_scale_f32 v27, s[4:5], v20, v20, v24
	v_rcp_f32_e32 v29, v27
	v_div_fmas_f32 v22, v22, v28, v23
	v_div_fixup_f32 v21, v22, v21, v25
	v_and_b32_e32 v28, 0xffff0000, v135
	v_fma_f32 v22, -v27, v29, 1.0
	v_fmac_f32_e32 v29, v22, v29
	v_div_scale_f32 v22, vcc, v24, v20, v24
	v_mul_f32_e32 v23, v22, v29
	v_fma_f32 v25, -v27, v23, v22
	v_fmac_f32_e32 v23, v25, v29
	v_fma_f32 v22, -v27, v23, v22
	v_div_fmas_f32 v22, v22, v29, v23
	v_lshlrev_b32_e32 v27, 16, v135
	v_div_fixup_f32 v20, v22, v20, v24
	v_mul_f32_e32 v22, 0xbfb8aa3b, v27
	v_mul_f32_e32 v23, 0xbfb8aa3b, v28
	v_exp_f32_e32 v22, v22
	v_exp_f32_e32 v23, v23
	v_pk_mul_f32 v[18:19], v[18:19], v[20:21]
	v_pk_fma_f32 v[20:21], v[112:113], v[76:77], v[30:31] op_sel_hi:[0,1,1]
	v_pk_fma_f32 v[20:21], v[114:115], v[92:93], v[20:21] op_sel_hi:[0,1,1]
	v_pk_add_f32 v[22:23], v[22:23], 1.0 op_sel_hi:[1,0]
	v_lshlrev_b32_e32 v24, 16, v133
	v_div_scale_f32 v29, s[4:5], v23, v23, v28
	v_rcp_f32_e32 v30, v29
	v_and_b32_e32 v25, 0xffff0000, v133
	v_pk_fma_f32 v[20:21], v[110:111], v[24:25], v[20:21] op_sel_hi:[0,1,1]
	v_cvt_pk_bf16_f32 v18, v18, v19
	v_fma_f32 v24, -v29, v30, 1.0
	v_fmac_f32_e32 v30, v24, v30
	v_div_scale_f32 v24, vcc, v28, v23, v28
	v_mul_f32_e32 v25, v24, v30
	v_fma_f32 v31, -v29, v25, v24
	v_fmac_f32_e32 v25, v31, v30
	v_fma_f32 v24, -v29, v25, v24
	v_div_scale_f32 v29, s[4:5], v22, v22, v27
	v_rcp_f32_e32 v31, v29
	v_div_fmas_f32 v24, v24, v30, v25
	v_div_fixup_f32 v23, v24, v23, v28
	v_fma_f32 v24, -v29, v31, 1.0
	v_fmac_f32_e32 v31, v24, v31
	v_div_scale_f32 v24, vcc, v27, v22, v27
	v_mul_f32_e32 v25, v24, v31
	v_fma_f32 v28, -v29, v25, v24
	v_fmac_f32_e32 v25, v28, v31
	v_fma_f32 v24, -v29, v25, v24
	v_div_fmas_f32 v24, v24, v31, v25
	v_div_fixup_f32 v22, v24, v22, v27
	v_pk_mul_f32 v[20:21], v[20:21], v[22:23]
	s_waitcnt vmcnt(6)
	v_and_b32_e32 v24, 0xffff0000, v130
	v_cvt_pk_bf16_f32 v19, v20, v21
	v_and_b32_e32 v21, 0xffff0000, v18
	v_lshlrev_b32_e32 v20, 16, v18
	v_mul_f32_e32 v21, v21, v21
	v_lshlrev_b32_e32 v22, 16, v19
	v_fmac_f32_e32 v21, v20, v20
	v_and_b32_e32 v23, 0xffff0000, v19
	v_fmac_f32_e32 v21, v22, v22
	v_fmac_f32_e32 v21, v23, v23
	v_lshlrev_b32_e32 v23, 16, v130
	v_add_f32_e32 v22, v26, v21
	v_mul_f32_e32 v20, 0xbfb8aa3b, v23
	v_mul_f32_e32 v21, 0xbfb8aa3b, v24
	v_exp_f32_e32 v20, v20
	v_exp_f32_e32 v21, v21
	global_store_dwordx2 v[16:17], v[18:19], off offset:48
	v_pk_add_f32 v[18:19], v[20:21], 1.0 op_sel_hi:[1,0]
	s_nop 0
	v_div_scale_f32 v25, s[4:5], v19, v19, v24
	v_rcp_f32_e32 v26, v25
	v_lshlrev_b32_e32 v20, 16, v128
	v_and_b32_e32 v21, 0xffff0000, v128
	v_pk_fma_f32 v[0:1], v[110:111], v[20:21], v[0:1] op_sel_hi:[0,1,1]
	v_fma_f32 v20, -v25, v26, 1.0
	v_fmac_f32_e32 v26, v20, v26
	v_div_scale_f32 v20, vcc, v24, v19, v24
	v_mul_f32_e32 v21, v20, v26
	v_fma_f32 v27, -v25, v21, v20
	v_fmac_f32_e32 v21, v27, v26
	v_fma_f32 v20, -v25, v21, v20
	v_div_scale_f32 v25, s[4:5], v18, v18, v23
	v_rcp_f32_e32 v27, v25
	v_div_fmas_f32 v20, v20, v26, v21
	v_div_fixup_f32 v19, v20, v19, v24
	v_fma_f32 v20, -v25, v27, 1.0
	v_fmac_f32_e32 v27, v20, v27
	v_div_scale_f32 v20, vcc, v23, v18, v23
	v_mul_f32_e32 v21, v20, v27
	v_fma_f32 v24, -v25, v21, v20
	v_fmac_f32_e32 v21, v24, v27
	v_fma_f32 v20, -v25, v21, v20
	v_div_fmas_f32 v20, v20, v27, v21
	v_div_fixup_f32 v18, v20, v18, v23
	v_lshlrev_b32_e32 v23, 16, v131
	v_and_b32_e32 v24, 0xffff0000, v131
	v_mul_f32_e32 v20, 0xbfb8aa3b, v23
	v_mul_f32_e32 v21, 0xbfb8aa3b, v24
	v_exp_f32_e32 v20, v20
	v_exp_f32_e32 v21, v21
	v_pk_mul_f32 v[0:1], v[0:1], v[18:19]
	v_pk_add_f32 v[18:19], v[20:21], 1.0 op_sel_hi:[1,0]
	s_nop 0
	v_div_scale_f32 v25, s[4:5], v19, v19, v24
	v_rcp_f32_e32 v26, v25
	v_lshlrev_b32_e32 v20, 16, v129
	v_and_b32_e32 v21, 0xffff0000, v129
	v_pk_fma_f32 v[2:3], v[110:111], v[20:21], v[2:3] op_sel_hi:[0,1,1]
	v_fma_f32 v20, -v25, v26, 1.0
	v_fmac_f32_e32 v26, v20, v26
	v_div_scale_f32 v20, vcc, v24, v19, v24
	v_mul_f32_e32 v21, v20, v26
	v_fma_f32 v27, -v25, v21, v20
	v_fmac_f32_e32 v21, v27, v26
	v_fma_f32 v20, -v25, v21, v20
	v_div_scale_f32 v25, s[4:5], v18, v18, v23
	v_rcp_f32_e32 v27, v25
	v_div_fmas_f32 v20, v20, v26, v21
	v_div_fixup_f32 v19, v20, v19, v24
	v_cvt_pk_bf16_f32 v0, v0, v1
	v_fma_f32 v20, -v25, v27, 1.0
	v_fmac_f32_e32 v27, v20, v27
	v_div_scale_f32 v20, vcc, v23, v18, v23
	v_mul_f32_e32 v21, v20, v27
	v_fma_f32 v24, -v25, v21, v20
	v_fmac_f32_e32 v21, v24, v27
	v_fma_f32 v20, -v25, v21, v20
	v_div_fmas_f32 v20, v20, v27, v21
	v_div_fixup_f32 v18, v20, v18, v23
	v_pk_mul_f32 v[2:3], v[2:3], v[18:19]
	s_waitcnt vmcnt(6)
	v_and_b32_e32 v20, 0xffff0000, v126
	v_cvt_pk_bf16_f32 v1, v2, v3
	v_and_b32_e32 v3, 0xffff0000, v0
	v_lshlrev_b32_e32 v2, 16, v0
	v_mul_f32_e32 v3, v3, v3
	v_lshlrev_b32_e32 v18, 16, v1
	v_fmac_f32_e32 v3, v2, v2
	v_and_b32_e32 v19, 0xffff0000, v1
	v_fmac_f32_e32 v3, v18, v18
	v_fmac_f32_e32 v3, v19, v19
	v_lshlrev_b32_e32 v19, 16, v126
	v_add_f32_e32 v18, v22, v3
	v_mul_f32_e32 v2, 0xbfb8aa3b, v19
	v_mul_f32_e32 v3, 0xbfb8aa3b, v20
	v_exp_f32_e32 v2, v2
	v_exp_f32_e32 v3, v3
	global_store_dwordx2 v[16:17], v[0:1], off offset:64
	v_pk_fma_f32 v[0:1], v[112:113], v[36:37], v[4:5] op_sel_hi:[0,1,1]
	v_pk_fma_f32 v[0:1], v[114:115], v[52:53], v[0:1] op_sel_hi:[0,1,1]
	v_pk_add_f32 v[2:3], v[2:3], 1.0 op_sel_hi:[1,0]
	v_lshlrev_b32_e32 v4, 16, v124
	v_div_scale_f32 v21, s[4:5], v3, v3, v20
	v_rcp_f32_e32 v22, v21
	v_and_b32_e32 v5, 0xffff0000, v124
	v_pk_fma_f32 v[0:1], v[110:111], v[4:5], v[0:1] op_sel_hi:[0,1,1]
	v_fma_f32 v4, -v21, v22, 1.0
	v_fmac_f32_e32 v22, v4, v22
	v_div_scale_f32 v4, vcc, v20, v3, v20
	v_mul_f32_e32 v5, v4, v22
	v_fma_f32 v23, -v21, v5, v4
	v_fmac_f32_e32 v5, v23, v22
	v_fma_f32 v4, -v21, v5, v4
	v_div_scale_f32 v21, s[4:5], v2, v2, v19
	v_rcp_f32_e32 v23, v21
	v_div_fmas_f32 v4, v4, v22, v5
	v_div_fixup_f32 v3, v4, v3, v20
	v_fma_f32 v4, -v21, v23, 1.0
	v_fmac_f32_e32 v23, v4, v23
	v_div_scale_f32 v4, vcc, v19, v2, v19
	v_mul_f32_e32 v5, v4, v23
	v_fma_f32 v20, -v21, v5, v4
	v_fmac_f32_e32 v5, v20, v23
	v_fma_f32 v4, -v21, v5, v4
	v_div_fmas_f32 v4, v4, v23, v5
	v_div_fixup_f32 v2, v4, v2, v19
	v_lshlrev_b32_e32 v19, 16, v127
	v_and_b32_e32 v20, 0xffff0000, v127
	v_mul_f32_e32 v4, 0xbfb8aa3b, v19
	v_mul_f32_e32 v5, 0xbfb8aa3b, v20
	v_exp_f32_e32 v4, v4
	v_exp_f32_e32 v5, v5
	v_pk_mul_f32 v[0:1], v[0:1], v[2:3]
	v_pk_fma_f32 v[2:3], v[112:113], v[38:39], v[6:7] op_sel_hi:[0,1,1]
	v_pk_fma_f32 v[2:3], v[114:115], v[54:55], v[2:3] op_sel_hi:[0,1,1]
	v_pk_add_f32 v[4:5], v[4:5], 1.0 op_sel_hi:[1,0]
	v_lshlrev_b32_e32 v6, 16, v125
	v_div_scale_f32 v21, s[4:5], v5, v5, v20
	v_rcp_f32_e32 v22, v21
	v_and_b32_e32 v7, 0xffff0000, v125
	v_pk_fma_f32 v[2:3], v[110:111], v[6:7], v[2:3] op_sel_hi:[0,1,1]
	v_cvt_pk_bf16_f32 v0, v0, v1
	v_fma_f32 v6, -v21, v22, 1.0
	v_fmac_f32_e32 v22, v6, v22
	v_div_scale_f32 v6, vcc, v20, v5, v20
	v_mul_f32_e32 v7, v6, v22
	v_fma_f32 v23, -v21, v7, v6
	v_fmac_f32_e32 v7, v23, v22
	v_fma_f32 v6, -v21, v7, v6
	v_div_scale_f32 v21, s[4:5], v4, v4, v19
	v_rcp_f32_e32 v23, v21
	v_div_fmas_f32 v6, v6, v22, v7
	v_div_fixup_f32 v5, v6, v5, v20
	v_fma_f32 v6, -v21, v23, 1.0
	v_fmac_f32_e32 v23, v6, v23
	v_div_scale_f32 v6, vcc, v19, v4, v19
	v_mul_f32_e32 v7, v6, v23
	v_fma_f32 v20, -v21, v7, v6
	v_fmac_f32_e32 v7, v20, v23
	v_fma_f32 v6, -v21, v7, v6
	v_div_fmas_f32 v6, v6, v23, v7
	v_div_fixup_f32 v4, v6, v4, v19
	v_pk_mul_f32 v[2:3], v[2:3], v[4:5]
	s_waitcnt vmcnt(6)
	v_lshlrev_b32_e32 v19, 16, v122
	v_cvt_pk_bf16_f32 v1, v2, v3
	v_and_b32_e32 v3, 0xffff0000, v0
	v_lshlrev_b32_e32 v2, 16, v0
	v_mul_f32_e32 v6, v3, v3
	v_and_b32_e32 v20, 0xffff0000, v122
	v_fmac_f32_e32 v6, v2, v2
	v_mul_f32_e32 v2, 0xbfb8aa3b, v19
	v_mul_f32_e32 v3, 0xbfb8aa3b, v20
	v_exp_f32_e32 v2, v2
	v_exp_f32_e32 v3, v3
	v_lshlrev_b32_e32 v4, 16, v1
	v_and_b32_e32 v5, 0xffff0000, v1
	v_fmac_f32_e32 v6, v4, v4
	v_pk_add_f32 v[2:3], v[2:3], 1.0 op_sel_hi:[1,0]
	v_fmac_f32_e32 v6, v5, v5
	v_pk_fma_f32 v[4:5], v[112:113], v[40:41], v[8:9] op_sel_hi:[0,1,1]
	v_div_scale_f32 v8, s[4:5], v3, v3, v20
	v_rcp_f32_e32 v9, v8
	v_add_f32_e32 v18, v18, v6
	v_pk_fma_f32 v[4:5], v[114:115], v[56:57], v[4:5] op_sel_hi:[0,1,1]
	v_lshlrev_b32_e32 v6, 16, v120
	v_and_b32_e32 v7, 0xffff0000, v120
	v_pk_fma_f32 v[4:5], v[110:111], v[6:7], v[4:5] op_sel_hi:[0,1,1]
	v_fma_f32 v6, -v8, v9, 1.0
	v_fmac_f32_e32 v9, v6, v9
	v_div_scale_f32 v6, vcc, v20, v3, v20
	v_mul_f32_e32 v7, v6, v9
	v_fma_f32 v21, -v8, v7, v6
	v_fmac_f32_e32 v7, v21, v9
	v_fma_f32 v6, -v8, v7, v6
	v_div_scale_f32 v8, s[4:5], v2, v2, v19
	v_rcp_f32_e32 v21, v8
	v_div_fmas_f32 v6, v6, v9, v7
	v_div_fixup_f32 v3, v6, v3, v20
	v_and_b32_e32 v20, 0xffff0000, v123
	v_fma_f32 v6, -v8, v21, 1.0
	v_fmac_f32_e32 v21, v6, v21
	v_div_scale_f32 v6, vcc, v19, v2, v19
	v_mul_f32_e32 v7, v6, v21
	v_fma_f32 v9, -v8, v7, v6
	v_fmac_f32_e32 v7, v9, v21
	v_fma_f32 v6, -v8, v7, v6
	v_div_fmas_f32 v6, v6, v21, v7
	v_div_fixup_f32 v2, v6, v2, v19
	v_lshlrev_b32_e32 v19, 16, v123
	v_mul_f32_e32 v6, 0xbfb8aa3b, v19
	v_mul_f32_e32 v7, 0xbfb8aa3b, v20
	v_exp_f32_e32 v6, v6
	v_exp_f32_e32 v7, v7
	v_pk_mul_f32 v[2:3], v[4:5], v[2:3]
	v_pk_fma_f32 v[4:5], v[112:113], v[42:43], v[10:11] op_sel_hi:[0,1,1]
	v_pk_fma_f32 v[4:5], v[114:115], v[58:59], v[4:5] op_sel_hi:[0,1,1]
	v_pk_add_f32 v[6:7], v[6:7], 1.0 op_sel_hi:[1,0]
	v_lshlrev_b32_e32 v8, 16, v121
	v_div_scale_f32 v10, s[4:5], v7, v7, v20
	v_rcp_f32_e32 v11, v10
	v_and_b32_e32 v9, 0xffff0000, v121
	v_pk_fma_f32 v[4:5], v[110:111], v[8:9], v[4:5] op_sel_hi:[0,1,1]
	v_fma_f32 v8, -v10, v11, 1.0
	v_fmac_f32_e32 v11, v8, v11
	v_div_scale_f32 v8, vcc, v20, v7, v20
	v_mul_f32_e32 v9, v8, v11
	v_fma_f32 v21, -v10, v9, v8
	v_fmac_f32_e32 v9, v21, v11
	v_fma_f32 v8, -v10, v9, v8
	v_div_scale_f32 v10, s[4:5], v6, v6, v19
	v_rcp_f32_e32 v21, v10
	v_div_fmas_f32 v8, v8, v11, v9
	v_div_fixup_f32 v7, v8, v7, v20
	v_fma_f32 v8, -v10, v21, 1.0
	v_fmac_f32_e32 v21, v8, v21
	v_div_scale_f32 v8, vcc, v19, v6, v19
	v_mul_f32_e32 v9, v8, v21
	v_fma_f32 v11, -v10, v9, v8
	v_fmac_f32_e32 v9, v11, v21
	v_fma_f32 v8, -v10, v9, v8
	v_div_fmas_f32 v8, v8, v21, v9
	v_div_fixup_f32 v6, v8, v6, v19
	v_pk_mul_f32 v[4:5], v[4:5], v[6:7]
	v_cvt_pk_bf16_f32 v6, v2, v3
	v_and_b32_e32 v3, 0xffff0000, v6
	v_lshlrev_b32_e32 v2, 16, v6
	v_mul_f32_e32 v8, v3, v3
	s_waitcnt vmcnt(5)
	v_lshlrev_b32_e32 v10, 16, v118
	v_and_b32_e32 v11, 0xffff0000, v118
	v_fmac_f32_e32 v8, v2, v2
	v_mul_f32_e32 v2, 0xbfb8aa3b, v10
	v_mul_f32_e32 v3, 0xbfb8aa3b, v11
	v_exp_f32_e32 v2, v2
	v_exp_f32_e32 v3, v3
	v_cvt_pk_bf16_f32 v7, v4, v5
	v_lshlrev_b32_e32 v4, 16, v7
	v_and_b32_e32 v5, 0xffff0000, v7
	v_fmac_f32_e32 v8, v4, v4
	v_pk_add_f32 v[2:3], v[2:3], 1.0 op_sel_hi:[1,0]
	v_fmac_f32_e32 v8, v5, v5
	v_pk_fma_f32 v[4:5], v[112:113], v[44:45], v[12:13] op_sel_hi:[0,1,1]
	v_div_scale_f32 v12, s[4:5], v3, v3, v11
	v_rcp_f32_e32 v13, v12
	v_add_f32_e32 v18, v18, v8
	v_pk_fma_f32 v[4:5], v[114:115], v[60:61], v[4:5] op_sel_hi:[0,1,1]
	v_lshlrev_b32_e32 v8, 16, v116
	v_and_b32_e32 v9, 0xffff0000, v116
	v_pk_fma_f32 v[4:5], v[110:111], v[8:9], v[4:5] op_sel_hi:[0,1,1]
	v_fma_f32 v8, -v12, v13, 1.0
	v_fmac_f32_e32 v13, v8, v13
	v_div_scale_f32 v8, vcc, v11, v3, v11
	v_mul_f32_e32 v9, v8, v13
	v_fma_f32 v19, -v12, v9, v8
	v_fmac_f32_e32 v9, v19, v13
	v_fma_f32 v8, -v12, v9, v8
	v_div_scale_f32 v12, s[4:5], v2, v2, v10
	v_rcp_f32_e32 v19, v12
	v_div_fmas_f32 v8, v8, v13, v9
	v_div_fixup_f32 v3, v8, v3, v11
	v_and_b32_e32 v13, 0xffff0000, v119
	v_fma_f32 v8, -v12, v19, 1.0
	v_fmac_f32_e32 v19, v8, v19
	v_div_scale_f32 v8, vcc, v10, v2, v10
	v_mul_f32_e32 v9, v8, v19
	v_fma_f32 v11, -v12, v9, v8
	v_fmac_f32_e32 v9, v11, v19
	v_fma_f32 v8, -v12, v9, v8
	v_div_fmas_f32 v8, v8, v19, v9
	v_lshlrev_b32_e32 v12, 16, v119
	v_div_fixup_f32 v2, v8, v2, v10
	v_mul_f32_e32 v8, 0xbfb8aa3b, v12
	v_mul_f32_e32 v9, 0xbfb8aa3b, v13
	v_exp_f32_e32 v8, v8
	v_exp_f32_e32 v9, v9
	v_pk_mul_f32 v[2:3], v[4:5], v[2:3]
	v_pk_fma_f32 v[4:5], v[112:113], v[46:47], v[14:15] op_sel_hi:[0,1,1]
	v_pk_fma_f32 v[4:5], v[114:115], v[62:63], v[4:5] op_sel_hi:[0,1,1]
	v_pk_add_f32 v[8:9], v[8:9], 1.0 op_sel_hi:[1,0]
	v_lshlrev_b32_e32 v10, 16, v117
	v_div_scale_f32 v14, s[4:5], v9, v9, v13
	v_rcp_f32_e32 v15, v14
	v_and_b32_e32 v11, 0xffff0000, v117
	v_pk_fma_f32 v[4:5], v[110:111], v[10:11], v[4:5] op_sel_hi:[0,1,1]
	v_fma_f32 v10, -v14, v15, 1.0
	v_fmac_f32_e32 v15, v10, v15
	v_div_scale_f32 v10, vcc, v13, v9, v13
	v_mul_f32_e32 v11, v10, v15
	v_fma_f32 v19, -v14, v11, v10
	v_fmac_f32_e32 v11, v19, v15
	v_fma_f32 v10, -v14, v11, v10
	v_div_scale_f32 v14, s[4:5], v8, v8, v12
	v_rcp_f32_e32 v19, v14
	v_div_fmas_f32 v10, v10, v15, v11
	v_div_fixup_f32 v9, v10, v9, v13
	v_fma_f32 v10, -v14, v19, 1.0
	v_fmac_f32_e32 v19, v10, v19
	v_div_scale_f32 v10, vcc, v12, v8, v12
	v_mul_f32_e32 v11, v10, v19
	v_fma_f32 v13, -v14, v11, v10
	v_fmac_f32_e32 v11, v13, v19
	v_fma_f32 v10, -v14, v11, v10
	v_div_fmas_f32 v10, v10, v19, v11
	v_div_fixup_f32 v8, v10, v8, v12
	v_pk_mul_f32 v[4:5], v[4:5], v[8:9]
	v_cvt_pk_bf16_f32 v8, v2, v3
	v_and_b32_e32 v3, 0xffff0000, v8
	v_cvt_pk_bf16_f32 v9, v4, v5
	v_lshlrev_b32_e32 v2, 16, v8
	v_mul_f32_e32 v3, v3, v3
	v_lshlrev_b32_e32 v4, 16, v9
	v_fmac_f32_e32 v3, v2, v2
	v_and_b32_e32 v5, 0xffff0000, v9
	v_fmac_f32_e32 v3, v4, v4
	v_fmac_f32_e32 v3, v5, v5
	v_add_f32_e32 v2, v18, v3
	v_xor_b32_e32 v3, 32, v165
	v_add_u32_e32 v4, 64, v113
	v_cmp_lt_i32_e32 vcc, v3, v4
	global_store_dwordx2 v[16:17], v[0:1], off offset:80
	global_store_dwordx2 v[16:17], v[6:7], off offset:96
	global_store_dwordx2 v[16:17], v[8:9], off offset:112
	v_cndmask_b32_e32 v3, v165, v3, vcc
	v_lshlrev_b32_e32 v3, 2, v3
	ds_bpermute_b32 v3, v3, v2
	v_cmp_eq_u32_e32 vcc, 0, v111
	s_and_saveexec_b64 s[30:31], vcc
	s_cbranch_execz .LBB0_2184
	v_lshlrev_b64 v[0:1], 5, v[108:109]
	v_lshl_add_u64 v[0:1], s[18:19], 0, v[0:1]
	s_mov_b32 s7, s21
	v_lshl_add_u64 v[0:1], v[0:1], 0, s[6:7]
	s_waitcnt lgkmcnt(0)
	v_add_f32_e32 v2, v2, v3
	global_store_dword v[0:1], v2, off
	s_branch .LBB0_2184
